# MFMA accumulate-chain order, variant m,n,k (activation fragment pair shared by two consecutive chains) instead of n,m,k
# baseline (speedup 1.0000x reference)
; #define PG8_STAGE(bufoff, gbase, voff) do { _Pragma("unroll") for (int _i = 0; _i < 2; ++_i) \
;         __builtin_amdgcn_global_load_lds((const unsigned*)((const char*)(gbase) + (voff)[_i]), (PG8_LAS unsigned*)(lds + (bufoff) + ldsw + _i * 8192), 16, 0, 0); } while (0)
; #define PG8_LDA(dst, b, h) do { _Pragma("unroll") for (int m = 0; m < 4; ++m) _Pragma("unroll") for (int k = 0; k < 2; ++k) dst[m][k] = *(const PG8_LAS bf16x8*)(lds + PG8_SA(b, h) + aoff + m * 2048 + k * 1024); } while (0)
; #define PG8_LDB(dst, b, h) do { _Pragma("unroll") for (int n = 0; n < 2; ++n) _Pragma("unroll") for (int k = 0; k < 2; ++k) dst[n][k] = *(const PG8_LAS bf16x8*)(lds + PG8_SB(b, h) + boff + n * 2048 + k * 1024); } while (0)
; #define PG8_MMA(ai, bj, At, Bt) do { __builtin_amdgcn_s_setprio(1); _Pragma("unroll") for (int m = 0; m < 4; ++m) _Pragma("unroll") for (int n = 0; n < 2; ++n) _Pragma("unroll") for (int k = 0; k < 2; ++k) \
;         acc[ai][bj][m][n] = __builtin_amdgcn_mfma_f32_16x16x32_bf16(Bt[n][k], At[m][k], acc[ai][bj][m][n], 0, 0, 0); __builtin_amdgcn_s_setprio(0); } while (0)
; #define PG8_WAIT_V(n) asm volatile("s_waitcnt vmcnt(" #n ")" ::: "memory")
; #define PG8_WAIT_L(n) asm volatile("s_waitcnt lgkmcnt(" #n ")" ::: "memory")
; template <class Epi, class Sched, bool ALIGN_EPI = false, bool SP2 = false>
; __device__ __forceinline__ void gemm_phase(PG8_LAS unsigned char* lds, const Gemm g, const Sched& S, const Epi& E) {
;     ...
;             const bool last = (t == nt - 2);
;             const char* a1 = cA + (size_t)(t + 1) * kstep;
;             const char* a2 = last ? nA : cA + (size_t)(t + 2) * kstep; const char* b2 = last ? nB : cB + (size_t)(t + 2) * kstep;
;             const char* a3 = a2 + kstep; const char* b3 = b2 + kstep;
;             if (last && has_next) S.a_ready(nxt);
;             if constexpr (SP2) {
;             PG8_LDB(B0, 0, 0); PG8_LDB(B1, 0, 1); PG8_SCHED; PG8_LDA(At, 0, 0); PG8_STAGE(PG8_SA(1, 1), a1 + hstep, voffA);
;             PG8_WAIT_V(8); PG8_WAIT_L(0); PG8_BAR; PG8_MMA(0, 0, At, B0); PG8_MMA(0, 1, At, B1); PG8_BAR; PG8_SCHED;
;             PG8_LDA(At, 0, 1); PG8_STAGE(PG8_SB(0, 0), b2, voffB); PG8_STAGE(PG8_SB(0, 1), b2 + hstep, voffB); PG8_STAGE(PG8_SA(0, 0), a2, voffA);
;             PG8_WAIT_V(8); PG8_WAIT_L(0); PG8_BAR; PG8_MMA(1, 0, At, B0); PG8_MMA(1, 1, At, B1); PG8_BAR; PG8_SCHED;
.Labo_peel:
	ds_read_b128 v[68:71], v254
	ds_read_b128 v[72:75], v254 offset:1024
	ds_read_b128 v[76:79], v254 offset:2048
	ds_read_b128 v[80:83], v254 offset:3072
	ds_read_b128 v[174:177], v254 offset:16384
	ds_read_b128 v[182:185], v254 offset:17408
	ds_read_b128 v[186:189], v254 offset:18432
	ds_read_b128 v[210:213], v254 offset:19456
	s_add_u32 s2, s0, 0xfffc0080
	s_addc_u32 s3, s1, -1
	s_cmp_eq_u32 s56, 12
	s_cselect_b32 s5, s27, s3
	s_cselect_b32 s4, s52, s2
	s_cselect_b32 s3, s25, s55
	s_cselect_b32 s2, s53, s54
	s_add_i32 m0, s29, 0xc000
	ds_read_b128 v[214:217], v179
	ds_read_b128 v[218:221], v179 offset:1024
	ds_read_b128 v[222:225], v179 offset:2048
	ds_read_b128 v[226:229], v179 offset:3072
	ds_read_b128 v[230:233], v179 offset:4096
	ds_read_b128 v[234:237], v179 offset:5120
	ds_read_b128 v[238:241], v179 offset:6144
	ds_read_b128 v[242:245], v179 offset:7168
	global_load_lds_dwordx4 v170, s[0:1]
	s_add_i32 m0, s29, 0xe000
	s_nop 0
	global_load_lds_dwordx4 v172, s[0:1]
	s_waitcnt vmcnt(8)
	s_waitcnt lgkmcnt(0)
	s_barrier
	s_setprio 1
	v_mfma_f32_16x16x32_bf16 v[140:143], v[68:71], v[214:217], 0
	v_mfma_f32_16x16x32_bf16 v[140:143], v[72:75], v[218:221], v[140:143]
	v_mfma_f32_16x16x32_bf16 v[136:139], v[76:79], v[214:217], 0
	v_mfma_f32_16x16x32_bf16 v[136:139], v[80:83], v[218:221], v[136:139]
	v_mfma_f32_16x16x32_bf16 v[124:127], v[68:71], v[222:225], 0
	v_mfma_f32_16x16x32_bf16 v[124:127], v[72:75], v[226:229], v[124:127]
	v_mfma_f32_16x16x32_bf16 v[120:123], v[76:79], v[222:225], 0
	v_mfma_f32_16x16x32_bf16 v[120:123], v[80:83], v[226:229], v[120:123]
	v_mfma_f32_16x16x32_bf16 v[108:111], v[68:71], v[230:233], 0
	v_mfma_f32_16x16x32_bf16 v[108:111], v[72:75], v[234:237], v[108:111]
	v_mfma_f32_16x16x32_bf16 v[104:107], v[76:79], v[230:233], 0
	v_mfma_f32_16x16x32_bf16 v[104:107], v[80:83], v[234:237], v[104:107]
	v_mfma_f32_16x16x32_bf16 v[92:95], v[68:71], v[238:241], 0
	v_mfma_f32_16x16x32_bf16 v[92:95], v[72:75], v[242:245], v[92:95]
	v_mfma_f32_16x16x32_bf16 v[88:91], v[76:79], v[238:241], 0
	v_mfma_f32_16x16x32_bf16 v[88:91], v[80:83], v[242:245], v[88:91]
	v_mfma_f32_16x16x32_bf16 v[132:135], v[174:177], v[214:217], 0
	v_mfma_f32_16x16x32_bf16 v[132:135], v[182:185], v[218:221], v[132:135]
	v_mfma_f32_16x16x32_bf16 v[128:131], v[186:189], v[214:217], 0
	v_mfma_f32_16x16x32_bf16 v[128:131], v[210:213], v[218:221], v[128:131]
	v_mfma_f32_16x16x32_bf16 v[116:119], v[174:177], v[222:225], 0
	v_mfma_f32_16x16x32_bf16 v[116:119], v[182:185], v[226:229], v[116:119]
	v_mfma_f32_16x16x32_bf16 v[112:115], v[186:189], v[222:225], 0
	v_mfma_f32_16x16x32_bf16 v[112:115], v[210:213], v[226:229], v[112:115]
	v_mfma_f32_16x16x32_bf16 v[100:103], v[174:177], v[230:233], 0
	v_mfma_f32_16x16x32_bf16 v[100:103], v[182:185], v[234:237], v[100:103]
	v_mfma_f32_16x16x32_bf16 v[96:99], v[186:189], v[230:233], 0
	v_mfma_f32_16x16x32_bf16 v[96:99], v[210:213], v[234:237], v[96:99]
	v_mfma_f32_16x16x32_bf16 v[84:87], v[174:177], v[238:241], 0
	v_mfma_f32_16x16x32_bf16 v[84:87], v[182:185], v[242:245], v[84:87]
	v_mfma_f32_16x16x32_bf16 v[64:67], v[186:189], v[238:241], 0
	v_mfma_f32_16x16x32_bf16 v[64:67], v[210:213], v[242:245], v[64:67]
	s_setprio 0
	s_barrier
	s_mov_b32 m0, s30
	s_add_u32 s58, s2, 0x40000
	s_addc_u32 s59, s3, 0
	ds_read_b128 v[214:217], v179 offset:16384
	ds_read_b128 v[218:221], v179 offset:17408
	ds_read_b128 v[222:225], v179 offset:18432
	ds_read_b128 v[226:229], v179 offset:19456
	ds_read_b128 v[230:233], v179 offset:20480
	ds_read_b128 v[234:237], v179 offset:21504
	ds_read_b128 v[238:241], v179 offset:22528
	ds_read_b128 v[242:245], v179 offset:23552
	global_load_lds_dwordx4 v166, s[2:3]
	s_mov_b32 m0, s31
	s_nop 0
	global_load_lds_dwordx4 v162, s[2:3]
	s_mov_b32 m0, s33
	s_nop 0
	global_load_lds_dwordx4 v166, s[58:59]
	s_mov_b32 m0, s34
	s_nop 0
	global_load_lds_dwordx4 v162, s[58:59]
	s_mov_b32 m0, s29
	s_nop 0
	global_load_lds_dwordx4 v168, s[4:5]
	s_mov_b32 m0, s35
	s_nop 0
	global_load_lds_dwordx4 v164, s[4:5]
	s_waitcnt vmcnt(8)
	s_waitcnt lgkmcnt(0)
	s_barrier
	s_setprio 1
	v_mfma_f32_16x16x32_bf16 v[60:63], v[68:71], v[214:217], 0
	v_mfma_f32_16x16x32_bf16 v[60:63], v[72:75], v[218:221], v[60:63]
	v_mfma_f32_16x16x32_bf16 v[56:59], v[76:79], v[214:217], 0
	v_mfma_f32_16x16x32_bf16 v[56:59], v[80:83], v[218:221], v[56:59]
	v_mfma_f32_16x16x32_bf16 v[44:47], v[68:71], v[222:225], 0
	v_mfma_f32_16x16x32_bf16 v[44:47], v[72:75], v[226:229], v[44:47]
	v_mfma_f32_16x16x32_bf16 v[40:43], v[76:79], v[222:225], 0
	v_mfma_f32_16x16x32_bf16 v[40:43], v[80:83], v[226:229], v[40:43]
	v_mfma_f32_16x16x32_bf16 v[28:31], v[68:71], v[230:233], 0
	v_mfma_f32_16x16x32_bf16 v[28:31], v[72:75], v[234:237], v[28:31]
	v_mfma_f32_16x16x32_bf16 v[24:27], v[76:79], v[230:233], 0
	v_mfma_f32_16x16x32_bf16 v[24:27], v[80:83], v[234:237], v[24:27]
	v_mfma_f32_16x16x32_bf16 v[12:15], v[68:71], v[238:241], 0
	v_mfma_f32_16x16x32_bf16 v[12:15], v[72:75], v[242:245], v[12:15]
	v_mfma_f32_16x16x32_bf16 v[8:11], v[76:79], v[238:241], 0
	v_mfma_f32_16x16x32_bf16 v[8:11], v[80:83], v[242:245], v[8:11]
	v_mfma_f32_16x16x32_bf16 v[52:55], v[174:177], v[214:217], 0
	v_mfma_f32_16x16x32_bf16 v[52:55], v[182:185], v[218:221], v[52:55]
	v_mfma_f32_16x16x32_bf16 v[48:51], v[186:189], v[214:217], 0
	v_mfma_f32_16x16x32_bf16 v[48:51], v[210:213], v[218:221], v[48:51]
	v_mfma_f32_16x16x32_bf16 v[36:39], v[174:177], v[222:225], 0
	v_mfma_f32_16x16x32_bf16 v[36:39], v[182:185], v[226:229], v[36:39]
	v_mfma_f32_16x16x32_bf16 v[32:35], v[186:189], v[222:225], 0
	v_mfma_f32_16x16x32_bf16 v[32:35], v[210:213], v[226:229], v[32:35]
	v_mfma_f32_16x16x32_bf16 v[20:23], v[174:177], v[230:233], 0
	v_mfma_f32_16x16x32_bf16 v[20:23], v[182:185], v[234:237], v[20:23]
	v_mfma_f32_16x16x32_bf16 v[16:19], v[186:189], v[230:233], 0
	v_mfma_f32_16x16x32_bf16 v[16:19], v[210:213], v[234:237], v[16:19]
	v_mfma_f32_16x16x32_bf16 v[4:7], v[174:177], v[238:241], 0
	v_mfma_f32_16x16x32_bf16 v[4:7], v[182:185], v[242:245], v[4:7]
	v_mfma_f32_16x16x32_bf16 v[0:3], v[186:189], v[238:241], 0
	v_mfma_f32_16x16x32_bf16 v[0:3], v[210:213], v[242:245], v[0:3]
	s_setprio 0
	s_barrier
; #define PG8_STAGE(bufoff, gbase, voff) do { _Pragma("unroll") for (int _i = 0; _i < 2; ++_i) \
;         __builtin_amdgcn_global_load_lds((const unsigned*)((const char*)(gbase) + (voff)[_i]), (PG8_LAS unsigned*)(lds + (bufoff) + ldsw + _i * 8192), 16, 0, 0); } while (0)
; #define PG8_LDA(dst, b, h) do { _Pragma("unroll") for (int m = 0; m < 4; ++m) _Pragma("unroll") for (int k = 0; k < 2; ++k) dst[m][k] = *(const PG8_LAS bf16x8*)(lds + PG8_SA(b, h) + aoff + m * 2048 + k * 1024); } while (0)
; #define PG8_LDB(dst, b, h) do { _Pragma("unroll") for (int n = 0; n < 2; ++n) _Pragma("unroll") for (int k = 0; k < 2; ++k) dst[n][k] = *(const PG8_LAS bf16x8*)(lds + PG8_SB(b, h) + boff + n * 2048 + k * 1024); } while (0)
; #define PG8_MMA(ai, bj, At, Bt) do { __builtin_amdgcn_s_setprio(1); _Pragma("unroll") for (int m = 0; m < 4; ++m) _Pragma("unroll") for (int n = 0; n < 2; ++n) _Pragma("unroll") for (int k = 0; k < 2; ++k) \
;         acc[ai][bj][m][n] = __builtin_amdgcn_mfma_f32_16x16x32_bf16(Bt[n][k], At[m][k], acc[ai][bj][m][n], 0, 0, 0); __builtin_amdgcn_s_setprio(0); } while (0)
; #define PG8_WAIT_V(n) asm volatile("s_waitcnt vmcnt(" #n ")" ::: "memory")
; #define PG8_WAIT_L(n) asm volatile("s_waitcnt lgkmcnt(" #n ")" ::: "memory")
; #define PG8_BAR __builtin_amdgcn_s_barrier()
; #define PG8_SCHED __builtin_amdgcn_sched_barrier(0)
; template <class Epi, class Sched, bool ALIGN_EPI = false, bool SP2 = false>
; __device__ __forceinline__ void gemm_phase(PG8_LAS unsigned char* lds, const Gemm g, const Sched& S, const Epi& E) {
;     ...
;             PG8_LDB(B0, 1, 0); PG8_LDB(B1, 1, 1); PG8_SCHED; PG8_LDA(At, 1, 0); PG8_STAGE(PG8_SA(0, 1), a2 + hstep, voffA);
;             PG8_WAIT_V(8); PG8_WAIT_L(0); PG8_BAR; PG8_MMA(0, 0, At, B0); PG8_MMA(0, 1, At, B1); PG8_BAR; PG8_SCHED;
;             PG8_LDA(At, 1, 1); PG8_STAGE(PG8_SB(1, 0), b3, voffB); PG8_STAGE(PG8_SB(1, 1), b3 + hstep, voffB); PG8_STAGE(PG8_SA(1, 0), a3, voffA);
;             PG8_WAIT_V(8); PG8_WAIT_L(0); PG8_BAR; PG8_MMA(1, 0, At, B0); PG8_MMA(1, 1, At, B1); PG8_BAR; PG8_SCHED;
	ds_read_b128 v[68:71], v254 offset:32768
	ds_read_b128 v[72:75], v254 offset:33792
	ds_read_b128 v[76:79], v254 offset:34816
	ds_read_b128 v[80:83], v254 offset:35840
	ds_read_b128 v[174:177], v254 offset:49152
	ds_read_b128 v[182:185], v254 offset:50176
	ds_read_b128 v[186:189], v254 offset:51200
	ds_read_b128 v[210:213], v254 offset:52224
	s_add_u32 s4, s4, 0x40000
	s_addc_u32 s5, s5, 0
	s_mov_b32 m0, s40
	ds_read_b128 v[214:217], v179 offset:32768
	ds_read_b128 v[218:221], v179 offset:33792
	ds_read_b128 v[222:225], v179 offset:34816
	ds_read_b128 v[226:229], v179 offset:35840
	ds_read_b128 v[230:233], v179 offset:36864
	ds_read_b128 v[234:237], v179 offset:37888
	ds_read_b128 v[238:241], v179 offset:38912
	ds_read_b128 v[242:245], v179 offset:39936
	global_load_lds_dwordx4 v168, s[4:5]
	s_mov_b32 m0, s41
	s_nop 0
	global_load_lds_dwordx4 v164, s[4:5]
	s_waitcnt vmcnt(8)
	s_waitcnt lgkmcnt(0)
	s_barrier
	s_setprio 1
	v_mfma_f32_16x16x32_bf16 v[140:143], v[68:71], v[214:217], v[140:143]
	v_mfma_f32_16x16x32_bf16 v[140:143], v[72:75], v[218:221], v[140:143]
	v_mfma_f32_16x16x32_bf16 v[136:139], v[76:79], v[214:217], v[136:139]
	v_mfma_f32_16x16x32_bf16 v[136:139], v[80:83], v[218:221], v[136:139]
	v_mfma_f32_16x16x32_bf16 v[124:127], v[68:71], v[222:225], v[124:127]
	v_mfma_f32_16x16x32_bf16 v[124:127], v[72:75], v[226:229], v[124:127]
	v_mfma_f32_16x16x32_bf16 v[120:123], v[76:79], v[222:225], v[120:123]
	v_mfma_f32_16x16x32_bf16 v[120:123], v[80:83], v[226:229], v[120:123]
	v_mfma_f32_16x16x32_bf16 v[108:111], v[68:71], v[230:233], v[108:111]
	v_mfma_f32_16x16x32_bf16 v[108:111], v[72:75], v[234:237], v[108:111]
	v_mfma_f32_16x16x32_bf16 v[104:107], v[76:79], v[230:233], v[104:107]
	v_mfma_f32_16x16x32_bf16 v[104:107], v[80:83], v[234:237], v[104:107]
	v_mfma_f32_16x16x32_bf16 v[92:95], v[68:71], v[238:241], v[92:95]
	v_mfma_f32_16x16x32_bf16 v[92:95], v[72:75], v[242:245], v[92:95]
	v_mfma_f32_16x16x32_bf16 v[88:91], v[76:79], v[238:241], v[88:91]
	v_mfma_f32_16x16x32_bf16 v[88:91], v[80:83], v[242:245], v[88:91]
	v_mfma_f32_16x16x32_bf16 v[132:135], v[174:177], v[214:217], v[132:135]
	v_mfma_f32_16x16x32_bf16 v[132:135], v[182:185], v[218:221], v[132:135]
	v_mfma_f32_16x16x32_bf16 v[128:131], v[186:189], v[214:217], v[128:131]
	v_mfma_f32_16x16x32_bf16 v[128:131], v[210:213], v[218:221], v[128:131]
	v_mfma_f32_16x16x32_bf16 v[116:119], v[174:177], v[222:225], v[116:119]
	v_mfma_f32_16x16x32_bf16 v[116:119], v[182:185], v[226:229], v[116:119]
	v_mfma_f32_16x16x32_bf16 v[112:115], v[186:189], v[222:225], v[112:115]
	v_mfma_f32_16x16x32_bf16 v[112:115], v[210:213], v[226:229], v[112:115]
	v_mfma_f32_16x16x32_bf16 v[100:103], v[174:177], v[230:233], v[100:103]
	v_mfma_f32_16x16x32_bf16 v[100:103], v[182:185], v[234:237], v[100:103]
	v_mfma_f32_16x16x32_bf16 v[96:99], v[186:189], v[230:233], v[96:99]
	v_mfma_f32_16x16x32_bf16 v[96:99], v[210:213], v[234:237], v[96:99]
	v_mfma_f32_16x16x32_bf16 v[84:87], v[174:177], v[238:241], v[84:87]
	v_mfma_f32_16x16x32_bf16 v[84:87], v[182:185], v[242:245], v[84:87]
	v_mfma_f32_16x16x32_bf16 v[64:67], v[186:189], v[238:241], v[64:67]
	v_mfma_f32_16x16x32_bf16 v[64:67], v[210:213], v[242:245], v[64:67]
	s_setprio 0
	s_barrier
	s_mov_b32 m0, s45
	s_add_u32 s2, s2, 0x40080
	s_addc_u32 s3, s3, 0
	ds_read_b128 v[214:217], v179 offset:49152
	ds_read_b128 v[218:221], v179 offset:50176
	ds_read_b128 v[222:225], v179 offset:51200
	ds_read_b128 v[226:229], v179 offset:52224
	ds_read_b128 v[230:233], v179 offset:53248
	ds_read_b128 v[234:237], v179 offset:54272
	ds_read_b128 v[238:241], v179 offset:55296
	ds_read_b128 v[242:245], v179 offset:56320
	s_add_u32 s98, s2, 0xfffc0000
	s_addc_u32 s99, s3, -1
	global_load_lds_dwordx4 v166, s[98:99]
	s_mov_b32 m0, s46
	s_nop 0
	global_load_lds_dwordx4 v162, s[98:99]
	s_mov_b32 m0, s49
	s_nop 0
	global_load_lds_dwordx4 v166, s[2:3]
	s_mov_b32 m0, s50
	s_nop 0
	global_load_lds_dwordx4 v162, s[2:3]
	s_mov_b32 m0, s47
	s_nop 0
	s_add_u32 s100, s4, 0xfffc0080
	s_addc_u32 s101, s5, -1
	global_load_lds_dwordx4 v168, s[100:101]
	s_mov_b32 m0, s48
	s_nop 0
	global_load_lds_dwordx4 v164, s[100:101]
	s_waitcnt vmcnt(8)
	s_waitcnt lgkmcnt(0)
	s_barrier
	s_setprio 1
	v_mfma_f32_16x16x32_bf16 v[60:63], v[68:71], v[214:217], v[60:63]
	v_mfma_f32_16x16x32_bf16 v[60:63], v[72:75], v[218:221], v[60:63]
	v_mfma_f32_16x16x32_bf16 v[56:59], v[76:79], v[214:217], v[56:59]
	v_mfma_f32_16x16x32_bf16 v[56:59], v[80:83], v[218:221], v[56:59]
	v_mfma_f32_16x16x32_bf16 v[44:47], v[68:71], v[222:225], v[44:47]
	v_mfma_f32_16x16x32_bf16 v[44:47], v[72:75], v[226:229], v[44:47]
	v_mfma_f32_16x16x32_bf16 v[40:43], v[76:79], v[222:225], v[40:43]
	v_mfma_f32_16x16x32_bf16 v[40:43], v[80:83], v[226:229], v[40:43]
	v_mfma_f32_16x16x32_bf16 v[28:31], v[68:71], v[230:233], v[28:31]
	v_mfma_f32_16x16x32_bf16 v[28:31], v[72:75], v[234:237], v[28:31]
	v_mfma_f32_16x16x32_bf16 v[24:27], v[76:79], v[230:233], v[24:27]
	v_mfma_f32_16x16x32_bf16 v[24:27], v[80:83], v[234:237], v[24:27]
	v_mfma_f32_16x16x32_bf16 v[12:15], v[68:71], v[238:241], v[12:15]
	v_mfma_f32_16x16x32_bf16 v[12:15], v[72:75], v[242:245], v[12:15]
	v_mfma_f32_16x16x32_bf16 v[8:11], v[76:79], v[238:241], v[8:11]
	v_mfma_f32_16x16x32_bf16 v[8:11], v[80:83], v[242:245], v[8:11]
	v_mfma_f32_16x16x32_bf16 v[52:55], v[174:177], v[214:217], v[52:55]
	v_mfma_f32_16x16x32_bf16 v[52:55], v[182:185], v[218:221], v[52:55]
	v_mfma_f32_16x16x32_bf16 v[48:51], v[186:189], v[214:217], v[48:51]
	v_mfma_f32_16x16x32_bf16 v[48:51], v[210:213], v[218:221], v[48:51]
	v_mfma_f32_16x16x32_bf16 v[36:39], v[174:177], v[222:225], v[36:39]
	v_mfma_f32_16x16x32_bf16 v[36:39], v[182:185], v[226:229], v[36:39]
	v_mfma_f32_16x16x32_bf16 v[32:35], v[186:189], v[222:225], v[32:35]
	v_mfma_f32_16x16x32_bf16 v[32:35], v[210:213], v[226:229], v[32:35]
	v_mfma_f32_16x16x32_bf16 v[20:23], v[174:177], v[230:233], v[20:23]
	v_mfma_f32_16x16x32_bf16 v[20:23], v[182:185], v[234:237], v[20:23]
	v_mfma_f32_16x16x32_bf16 v[16:19], v[186:189], v[230:233], v[16:19]
	v_mfma_f32_16x16x32_bf16 v[16:19], v[210:213], v[234:237], v[16:19]
	v_mfma_f32_16x16x32_bf16 v[4:7], v[174:177], v[238:241], v[4:7]
	v_mfma_f32_16x16x32_bf16 v[4:7], v[182:185], v[242:245], v[4:7]
	v_mfma_f32_16x16x32_bf16 v[0:3], v[186:189], v[238:241], v[0:3]
	v_mfma_f32_16x16x32_bf16 v[0:3], v[210:213], v[242:245], v[0:3]
	s_setprio 0
	s_barrier
	s_add_i32 s56, s56, 2
	s_add_u32 s0, s0, 0x100
	s_addc_u32 s1, s1, 0
	s_add_u32 s54, s54, 0x100
	s_addc_u32 s55, s55, 0
	s_cmp_gt_u32 s56, 13
; #define PG8_STAGE(bufoff, gbase, voff) do { _Pragma("unroll") for (int _i = 0; _i < 2; ++_i) \
;         __builtin_amdgcn_global_load_lds((const unsigned*)((const char*)(gbase) + (voff)[_i]), (PG8_LAS unsigned*)(lds + (bufoff) + ldsw + _i * 8192), 16, 0, 0); } while (0)
; #define PG8_LDA(dst, b, h) do { _Pragma("unroll") for (int m = 0; m < 4; ++m) _Pragma("unroll") for (int k = 0; k < 2; ++k) dst[m][k] = *(const PG8_LAS bf16x8*)(lds + PG8_SA(b, h) + aoff + m * 2048 + k * 1024); } while (0)
; #define PG8_LDB(dst, b, h) do { _Pragma("unroll") for (int n = 0; n < 2; ++n) _Pragma("unroll") for (int k = 0; k < 2; ++k) dst[n][k] = *(const PG8_LAS bf16x8*)(lds + PG8_SB(b, h) + boff + n * 2048 + k * 1024); } while (0)
; #define PG8_MMA(ai, bj, At, Bt) do { __builtin_amdgcn_s_setprio(1); _Pragma("unroll") for (int m = 0; m < 4; ++m) _Pragma("unroll") for (int n = 0; n < 2; ++n) _Pragma("unroll") for (int k = 0; k < 2; ++k) \
;         acc[ai][bj][m][n] = __builtin_amdgcn_mfma_f32_16x16x32_bf16(Bt[n][k], At[m][k], acc[ai][bj][m][n], 0, 0, 0); __builtin_amdgcn_s_setprio(0); } while (0)
; #define PG8_WAIT_V(n) asm volatile("s_waitcnt vmcnt(" #n ")" ::: "memory")
; #define PG8_WAIT_L(n) asm volatile("s_waitcnt lgkmcnt(" #n ")" ::: "memory")
; template <class Epi, class Sched, bool ALIGN_EPI = false, bool SP2 = false>
; __device__ __forceinline__ void gemm_phase(PG8_LAS unsigned char* lds, const Gemm g, const Sched& S, const Epi& E) {
;     ...
;             const bool last = (t == nt - 2);
;             const char* a1 = cA + (size_t)(t + 1) * kstep;
;             const char* a2 = last ? nA : cA + (size_t)(t + 2) * kstep; const char* b2 = last ? nB : cB + (size_t)(t + 2) * kstep;
;             const char* a3 = a2 + kstep; const char* b3 = b2 + kstep;
;             if (last && has_next) S.a_ready(nxt);
;             if constexpr (SP2) {
;             PG8_LDB(B0, 0, 0); PG8_LDB(B1, 0, 1); PG8_SCHED; PG8_LDA(At, 0, 0); PG8_STAGE(PG8_SA(1, 1), a1 + hstep, voffA);
;             PG8_WAIT_V(8); PG8_WAIT_L(0); PG8_BAR; PG8_MMA(0, 0, At, B0); PG8_MMA(0, 1, At, B1); PG8_BAR; PG8_SCHED;
;             PG8_LDA(At, 0, 1); PG8_STAGE(PG8_SB(0, 0), b2, voffB); PG8_STAGE(PG8_SB(0, 1), b2 + hstep, voffB); PG8_STAGE(PG8_SA(0, 0), a2, voffA);
;             PG8_WAIT_V(8); PG8_WAIT_L(0); PG8_BAR; PG8_MMA(1, 0, At, B0); PG8_MMA(1, 1, At, B1); PG8_BAR; PG8_SCHED;
.LBB0_327:
	ds_read_b128 v[68:71], v254
	ds_read_b128 v[72:75], v254 offset:1024
	ds_read_b128 v[76:79], v254 offset:2048
	ds_read_b128 v[80:83], v254 offset:3072
	ds_read_b128 v[174:177], v254 offset:16384
	ds_read_b128 v[182:185], v254 offset:17408
	ds_read_b128 v[186:189], v254 offset:18432
	ds_read_b128 v[210:213], v254 offset:19456
	s_add_u32 s2, s0, 0xfffc0080
	s_addc_u32 s3, s1, -1
	s_cmp_eq_u32 s56, 12
	s_cselect_b32 s5, s27, s3
	s_cselect_b32 s4, s52, s2
	s_cselect_b32 s3, s25, s55
	s_cselect_b32 s2, s53, s54
	s_add_i32 m0, s29, 0xc000
	ds_read_b128 v[214:217], v179
	ds_read_b128 v[218:221], v179 offset:1024
	ds_read_b128 v[222:225], v179 offset:2048
	ds_read_b128 v[226:229], v179 offset:3072
	ds_read_b128 v[230:233], v179 offset:4096
	ds_read_b128 v[234:237], v179 offset:5120
	ds_read_b128 v[238:241], v179 offset:6144
	ds_read_b128 v[242:245], v179 offset:7168
	global_load_lds_dwordx4 v170, s[0:1]
	s_add_i32 m0, s29, 0xe000
	s_nop 0
	global_load_lds_dwordx4 v172, s[0:1]
	s_waitcnt vmcnt(8)
	s_waitcnt lgkmcnt(0)
	s_barrier
	s_setprio 1
	v_mfma_f32_16x16x32_bf16 v[140:143], v[68:71], v[214:217], v[140:143]
	v_mfma_f32_16x16x32_bf16 v[140:143], v[72:75], v[218:221], v[140:143]
	v_mfma_f32_16x16x32_bf16 v[136:139], v[76:79], v[214:217], v[136:139]
	v_mfma_f32_16x16x32_bf16 v[136:139], v[80:83], v[218:221], v[136:139]
	v_mfma_f32_16x16x32_bf16 v[124:127], v[68:71], v[222:225], v[124:127]
	v_mfma_f32_16x16x32_bf16 v[124:127], v[72:75], v[226:229], v[124:127]
	v_mfma_f32_16x16x32_bf16 v[120:123], v[76:79], v[222:225], v[120:123]
	v_mfma_f32_16x16x32_bf16 v[120:123], v[80:83], v[226:229], v[120:123]
	v_mfma_f32_16x16x32_bf16 v[108:111], v[68:71], v[230:233], v[108:111]
	v_mfma_f32_16x16x32_bf16 v[108:111], v[72:75], v[234:237], v[108:111]
	v_mfma_f32_16x16x32_bf16 v[104:107], v[76:79], v[230:233], v[104:107]
	v_mfma_f32_16x16x32_bf16 v[104:107], v[80:83], v[234:237], v[104:107]
	v_mfma_f32_16x16x32_bf16 v[92:95], v[68:71], v[238:241], v[92:95]
	v_mfma_f32_16x16x32_bf16 v[92:95], v[72:75], v[242:245], v[92:95]
	v_mfma_f32_16x16x32_bf16 v[88:91], v[76:79], v[238:241], v[88:91]
	v_mfma_f32_16x16x32_bf16 v[88:91], v[80:83], v[242:245], v[88:91]
	v_mfma_f32_16x16x32_bf16 v[132:135], v[174:177], v[214:217], v[132:135]
	v_mfma_f32_16x16x32_bf16 v[132:135], v[182:185], v[218:221], v[132:135]
	v_mfma_f32_16x16x32_bf16 v[128:131], v[186:189], v[214:217], v[128:131]
	v_mfma_f32_16x16x32_bf16 v[128:131], v[210:213], v[218:221], v[128:131]
	v_mfma_f32_16x16x32_bf16 v[116:119], v[174:177], v[222:225], v[116:119]
	v_mfma_f32_16x16x32_bf16 v[116:119], v[182:185], v[226:229], v[116:119]
	v_mfma_f32_16x16x32_bf16 v[112:115], v[186:189], v[222:225], v[112:115]
	v_mfma_f32_16x16x32_bf16 v[112:115], v[210:213], v[226:229], v[112:115]
	v_mfma_f32_16x16x32_bf16 v[100:103], v[174:177], v[230:233], v[100:103]
	v_mfma_f32_16x16x32_bf16 v[100:103], v[182:185], v[234:237], v[100:103]
	v_mfma_f32_16x16x32_bf16 v[96:99], v[186:189], v[230:233], v[96:99]
	v_mfma_f32_16x16x32_bf16 v[96:99], v[210:213], v[234:237], v[96:99]
	v_mfma_f32_16x16x32_bf16 v[84:87], v[174:177], v[238:241], v[84:87]
	v_mfma_f32_16x16x32_bf16 v[84:87], v[182:185], v[242:245], v[84:87]
	v_mfma_f32_16x16x32_bf16 v[64:67], v[186:189], v[238:241], v[64:67]
	v_mfma_f32_16x16x32_bf16 v[64:67], v[210:213], v[242:245], v[64:67]
	s_setprio 0
	s_barrier
	s_mov_b32 m0, s30
	s_add_u32 s58, s2, 0x40000
	s_addc_u32 s59, s3, 0
	ds_read_b128 v[214:217], v179 offset:16384
	ds_read_b128 v[218:221], v179 offset:17408
	ds_read_b128 v[222:225], v179 offset:18432
	ds_read_b128 v[226:229], v179 offset:19456
	ds_read_b128 v[230:233], v179 offset:20480
	ds_read_b128 v[234:237], v179 offset:21504
	ds_read_b128 v[238:241], v179 offset:22528
	ds_read_b128 v[242:245], v179 offset:23552
	global_load_lds_dwordx4 v166, s[2:3]
	s_mov_b32 m0, s31
	s_nop 0
	global_load_lds_dwordx4 v162, s[2:3]
	s_mov_b32 m0, s33
	s_nop 0
	global_load_lds_dwordx4 v166, s[58:59]
	s_mov_b32 m0, s34
	s_nop 0
	global_load_lds_dwordx4 v162, s[58:59]
	s_mov_b32 m0, s29
	s_nop 0
	global_load_lds_dwordx4 v168, s[4:5]
	s_mov_b32 m0, s35
	s_nop 0
	global_load_lds_dwordx4 v164, s[4:5]
	s_waitcnt vmcnt(8)
	s_waitcnt lgkmcnt(0)
	s_barrier
	s_setprio 1
	v_mfma_f32_16x16x32_bf16 v[60:63], v[68:71], v[214:217], v[60:63]
	v_mfma_f32_16x16x32_bf16 v[60:63], v[72:75], v[218:221], v[60:63]
	v_mfma_f32_16x16x32_bf16 v[56:59], v[76:79], v[214:217], v[56:59]
	v_mfma_f32_16x16x32_bf16 v[56:59], v[80:83], v[218:221], v[56:59]
	v_mfma_f32_16x16x32_bf16 v[44:47], v[68:71], v[222:225], v[44:47]
	v_mfma_f32_16x16x32_bf16 v[44:47], v[72:75], v[226:229], v[44:47]
	v_mfma_f32_16x16x32_bf16 v[40:43], v[76:79], v[222:225], v[40:43]
	v_mfma_f32_16x16x32_bf16 v[40:43], v[80:83], v[226:229], v[40:43]
	v_mfma_f32_16x16x32_bf16 v[28:31], v[68:71], v[230:233], v[28:31]
	v_mfma_f32_16x16x32_bf16 v[28:31], v[72:75], v[234:237], v[28:31]
	v_mfma_f32_16x16x32_bf16 v[24:27], v[76:79], v[230:233], v[24:27]
	v_mfma_f32_16x16x32_bf16 v[24:27], v[80:83], v[234:237], v[24:27]
	v_mfma_f32_16x16x32_bf16 v[12:15], v[68:71], v[238:241], v[12:15]
	v_mfma_f32_16x16x32_bf16 v[12:15], v[72:75], v[242:245], v[12:15]
	v_mfma_f32_16x16x32_bf16 v[8:11], v[76:79], v[238:241], v[8:11]
	v_mfma_f32_16x16x32_bf16 v[8:11], v[80:83], v[242:245], v[8:11]
	v_mfma_f32_16x16x32_bf16 v[52:55], v[174:177], v[214:217], v[52:55]
	v_mfma_f32_16x16x32_bf16 v[52:55], v[182:185], v[218:221], v[52:55]
	v_mfma_f32_16x16x32_bf16 v[48:51], v[186:189], v[214:217], v[48:51]
	v_mfma_f32_16x16x32_bf16 v[48:51], v[210:213], v[218:221], v[48:51]
	v_mfma_f32_16x16x32_bf16 v[36:39], v[174:177], v[222:225], v[36:39]
	v_mfma_f32_16x16x32_bf16 v[36:39], v[182:185], v[226:229], v[36:39]
	v_mfma_f32_16x16x32_bf16 v[32:35], v[186:189], v[222:225], v[32:35]
	v_mfma_f32_16x16x32_bf16 v[32:35], v[210:213], v[226:229], v[32:35]
	v_mfma_f32_16x16x32_bf16 v[20:23], v[174:177], v[230:233], v[20:23]
	v_mfma_f32_16x16x32_bf16 v[20:23], v[182:185], v[234:237], v[20:23]
	v_mfma_f32_16x16x32_bf16 v[16:19], v[186:189], v[230:233], v[16:19]
	v_mfma_f32_16x16x32_bf16 v[16:19], v[210:213], v[234:237], v[16:19]
	v_mfma_f32_16x16x32_bf16 v[4:7], v[174:177], v[238:241], v[4:7]
	v_mfma_f32_16x16x32_bf16 v[4:7], v[182:185], v[242:245], v[4:7]
	v_mfma_f32_16x16x32_bf16 v[0:3], v[186:189], v[238:241], v[0:3]
	v_mfma_f32_16x16x32_bf16 v[0:3], v[210:213], v[242:245], v[0:3]
	s_setprio 0
	s_barrier
; #define PG8_STAGE(bufoff, gbase, voff) do { _Pragma("unroll") for (int _i = 0; _i < 2; ++_i) \
;         __builtin_amdgcn_global_load_lds((const unsigned*)((const char*)(gbase) + (voff)[_i]), (PG8_LAS unsigned*)(lds + (bufoff) + ldsw + _i * 8192), 16, 0, 0); } while (0)
; #define PG8_LDA(dst, b, h) do { _Pragma("unroll") for (int m = 0; m < 4; ++m) _Pragma("unroll") for (int k = 0; k < 2; ++k) dst[m][k] = *(const PG8_LAS bf16x8*)(lds + PG8_SA(b, h) + aoff + m * 2048 + k * 1024); } while (0)
; #define PG8_LDB(dst, b, h) do { _Pragma("unroll") for (int n = 0; n < 2; ++n) _Pragma("unroll") for (int k = 0; k < 2; ++k) dst[n][k] = *(const PG8_LAS bf16x8*)(lds + PG8_SB(b, h) + boff + n * 2048 + k * 1024); } while (0)
; #define PG8_MMA(ai, bj, At, Bt) do { __builtin_amdgcn_s_setprio(1); _Pragma("unroll") for (int m = 0; m < 4; ++m) _Pragma("unroll") for (int n = 0; n < 2; ++n) _Pragma("unroll") for (int k = 0; k < 2; ++k) \
;         acc[ai][bj][m][n] = __builtin_amdgcn_mfma_f32_16x16x32_bf16(Bt[n][k], At[m][k], acc[ai][bj][m][n], 0, 0, 0); __builtin_amdgcn_s_setprio(0); } while (0)
; #define PG8_WAIT_V(n) asm volatile("s_waitcnt vmcnt(" #n ")" ::: "memory")
; #define PG8_WAIT_L(n) asm volatile("s_waitcnt lgkmcnt(" #n ")" ::: "memory")
; #define PG8_BAR __builtin_amdgcn_s_barrier()
; #define PG8_SCHED __builtin_amdgcn_sched_barrier(0)
; template <class Epi, class Sched, bool ALIGN_EPI = false, bool SP2 = false>
; __device__ __forceinline__ void gemm_phase(PG8_LAS unsigned char* lds, const Gemm g, const Sched& S, const Epi& E) {
;     ...
;             PG8_LDB(B0, 1, 0); PG8_LDB(B1, 1, 1); PG8_SCHED; PG8_LDA(At, 1, 0); PG8_STAGE(PG8_SA(0, 1), a2 + hstep, voffA);
;             PG8_WAIT_V(8); PG8_WAIT_L(0); PG8_BAR; PG8_MMA(0, 0, At, B0); PG8_MMA(0, 1, At, B1); PG8_BAR; PG8_SCHED;
;             PG8_LDA(At, 1, 1); PG8_STAGE(PG8_SB(1, 0), b3, voffB); PG8_STAGE(PG8_SB(1, 1), b3 + hstep, voffB); PG8_STAGE(PG8_SA(1, 0), a3, voffA);
;             PG8_WAIT_V(8); PG8_WAIT_L(0); PG8_BAR; PG8_MMA(1, 0, At, B0); PG8_MMA(1, 1, At, B1); PG8_BAR; PG8_SCHED;
	ds_read_b128 v[68:71], v254 offset:32768
	ds_read_b128 v[72:75], v254 offset:33792
	ds_read_b128 v[76:79], v254 offset:34816
	ds_read_b128 v[80:83], v254 offset:35840
	ds_read_b128 v[174:177], v254 offset:49152
	ds_read_b128 v[182:185], v254 offset:50176
	ds_read_b128 v[186:189], v254 offset:51200
	ds_read_b128 v[210:213], v254 offset:52224
	s_add_u32 s4, s4, 0x40000
	s_addc_u32 s5, s5, 0
	s_mov_b32 m0, s40
	ds_read_b128 v[214:217], v179 offset:32768
	ds_read_b128 v[218:221], v179 offset:33792
	ds_read_b128 v[222:225], v179 offset:34816
	ds_read_b128 v[226:229], v179 offset:35840
	ds_read_b128 v[230:233], v179 offset:36864
	ds_read_b128 v[234:237], v179 offset:37888
	ds_read_b128 v[238:241], v179 offset:38912
	ds_read_b128 v[242:245], v179 offset:39936
	global_load_lds_dwordx4 v168, s[4:5]
	s_mov_b32 m0, s41
	s_nop 0
	global_load_lds_dwordx4 v164, s[4:5]
	s_waitcnt vmcnt(8)
	s_waitcnt lgkmcnt(0)
	s_barrier
	s_setprio 1
	v_mfma_f32_16x16x32_bf16 v[140:143], v[68:71], v[214:217], v[140:143]
	v_mfma_f32_16x16x32_bf16 v[140:143], v[72:75], v[218:221], v[140:143]
	v_mfma_f32_16x16x32_bf16 v[136:139], v[76:79], v[214:217], v[136:139]
	v_mfma_f32_16x16x32_bf16 v[136:139], v[80:83], v[218:221], v[136:139]
	v_mfma_f32_16x16x32_bf16 v[124:127], v[68:71], v[222:225], v[124:127]
	v_mfma_f32_16x16x32_bf16 v[124:127], v[72:75], v[226:229], v[124:127]
	v_mfma_f32_16x16x32_bf16 v[120:123], v[76:79], v[222:225], v[120:123]
	v_mfma_f32_16x16x32_bf16 v[120:123], v[80:83], v[226:229], v[120:123]
	v_mfma_f32_16x16x32_bf16 v[108:111], v[68:71], v[230:233], v[108:111]
	v_mfma_f32_16x16x32_bf16 v[108:111], v[72:75], v[234:237], v[108:111]
	v_mfma_f32_16x16x32_bf16 v[104:107], v[76:79], v[230:233], v[104:107]
	v_mfma_f32_16x16x32_bf16 v[104:107], v[80:83], v[234:237], v[104:107]
	v_mfma_f32_16x16x32_bf16 v[92:95], v[68:71], v[238:241], v[92:95]
	v_mfma_f32_16x16x32_bf16 v[92:95], v[72:75], v[242:245], v[92:95]
	v_mfma_f32_16x16x32_bf16 v[88:91], v[76:79], v[238:241], v[88:91]
	v_mfma_f32_16x16x32_bf16 v[88:91], v[80:83], v[242:245], v[88:91]
	v_mfma_f32_16x16x32_bf16 v[132:135], v[174:177], v[214:217], v[132:135]
	v_mfma_f32_16x16x32_bf16 v[132:135], v[182:185], v[218:221], v[132:135]
	v_mfma_f32_16x16x32_bf16 v[128:131], v[186:189], v[214:217], v[128:131]
	v_mfma_f32_16x16x32_bf16 v[128:131], v[210:213], v[218:221], v[128:131]
	v_mfma_f32_16x16x32_bf16 v[116:119], v[174:177], v[222:225], v[116:119]
	v_mfma_f32_16x16x32_bf16 v[116:119], v[182:185], v[226:229], v[116:119]
	v_mfma_f32_16x16x32_bf16 v[112:115], v[186:189], v[222:225], v[112:115]
	v_mfma_f32_16x16x32_bf16 v[112:115], v[210:213], v[226:229], v[112:115]
	v_mfma_f32_16x16x32_bf16 v[100:103], v[174:177], v[230:233], v[100:103]
	v_mfma_f32_16x16x32_bf16 v[100:103], v[182:185], v[234:237], v[100:103]
	v_mfma_f32_16x16x32_bf16 v[96:99], v[186:189], v[230:233], v[96:99]
	v_mfma_f32_16x16x32_bf16 v[96:99], v[210:213], v[234:237], v[96:99]
	v_mfma_f32_16x16x32_bf16 v[84:87], v[174:177], v[238:241], v[84:87]
	v_mfma_f32_16x16x32_bf16 v[84:87], v[182:185], v[242:245], v[84:87]
	v_mfma_f32_16x16x32_bf16 v[64:67], v[186:189], v[238:241], v[64:67]
	v_mfma_f32_16x16x32_bf16 v[64:67], v[210:213], v[242:245], v[64:67]
	s_setprio 0
	s_barrier
	s_mov_b32 m0, s45
	s_add_u32 s2, s2, 0x40080
	s_addc_u32 s3, s3, 0
	ds_read_b128 v[214:217], v179 offset:49152
	ds_read_b128 v[218:221], v179 offset:50176
	ds_read_b128 v[222:225], v179 offset:51200
	ds_read_b128 v[226:229], v179 offset:52224
	ds_read_b128 v[230:233], v179 offset:53248
	ds_read_b128 v[234:237], v179 offset:54272
	ds_read_b128 v[238:241], v179 offset:55296
	ds_read_b128 v[242:245], v179 offset:56320
	s_add_u32 s98, s2, 0xfffc0000
	s_addc_u32 s99, s3, -1
	global_load_lds_dwordx4 v166, s[98:99]
	s_mov_b32 m0, s46
	s_nop 0
	global_load_lds_dwordx4 v162, s[98:99]
	s_mov_b32 m0, s49
	s_nop 0
	global_load_lds_dwordx4 v166, s[2:3]
	s_mov_b32 m0, s50
	s_nop 0
	global_load_lds_dwordx4 v162, s[2:3]
	s_mov_b32 m0, s47
	s_nop 0
	s_add_u32 s100, s4, 0xfffc0080
	s_addc_u32 s101, s5, -1
	global_load_lds_dwordx4 v168, s[100:101]
	s_mov_b32 m0, s48
	s_nop 0
	global_load_lds_dwordx4 v164, s[100:101]
	s_waitcnt vmcnt(8)
	s_waitcnt lgkmcnt(0)
	s_barrier
	s_setprio 1
	v_mfma_f32_16x16x32_bf16 v[60:63], v[68:71], v[214:217], v[60:63]
	v_mfma_f32_16x16x32_bf16 v[60:63], v[72:75], v[218:221], v[60:63]
	v_mfma_f32_16x16x32_bf16 v[56:59], v[76:79], v[214:217], v[56:59]
	v_mfma_f32_16x16x32_bf16 v[56:59], v[80:83], v[218:221], v[56:59]
	v_mfma_f32_16x16x32_bf16 v[44:47], v[68:71], v[222:225], v[44:47]
	v_mfma_f32_16x16x32_bf16 v[44:47], v[72:75], v[226:229], v[44:47]
	v_mfma_f32_16x16x32_bf16 v[40:43], v[76:79], v[222:225], v[40:43]
	v_mfma_f32_16x16x32_bf16 v[40:43], v[80:83], v[226:229], v[40:43]
	v_mfma_f32_16x16x32_bf16 v[28:31], v[68:71], v[230:233], v[28:31]
	v_mfma_f32_16x16x32_bf16 v[28:31], v[72:75], v[234:237], v[28:31]
	v_mfma_f32_16x16x32_bf16 v[24:27], v[76:79], v[230:233], v[24:27]
	v_mfma_f32_16x16x32_bf16 v[24:27], v[80:83], v[234:237], v[24:27]
	v_mfma_f32_16x16x32_bf16 v[12:15], v[68:71], v[238:241], v[12:15]
	v_mfma_f32_16x16x32_bf16 v[12:15], v[72:75], v[242:245], v[12:15]
	v_mfma_f32_16x16x32_bf16 v[8:11], v[76:79], v[238:241], v[8:11]
	v_mfma_f32_16x16x32_bf16 v[8:11], v[80:83], v[242:245], v[8:11]
	v_mfma_f32_16x16x32_bf16 v[52:55], v[174:177], v[214:217], v[52:55]
	v_mfma_f32_16x16x32_bf16 v[52:55], v[182:185], v[218:221], v[52:55]
	v_mfma_f32_16x16x32_bf16 v[48:51], v[186:189], v[214:217], v[48:51]
	v_mfma_f32_16x16x32_bf16 v[48:51], v[210:213], v[218:221], v[48:51]
	v_mfma_f32_16x16x32_bf16 v[36:39], v[174:177], v[222:225], v[36:39]
	v_mfma_f32_16x16x32_bf16 v[36:39], v[182:185], v[226:229], v[36:39]
	v_mfma_f32_16x16x32_bf16 v[32:35], v[186:189], v[222:225], v[32:35]
	v_mfma_f32_16x16x32_bf16 v[32:35], v[210:213], v[226:229], v[32:35]
	v_mfma_f32_16x16x32_bf16 v[20:23], v[174:177], v[230:233], v[20:23]
	v_mfma_f32_16x16x32_bf16 v[20:23], v[182:185], v[234:237], v[20:23]
	v_mfma_f32_16x16x32_bf16 v[16:19], v[186:189], v[230:233], v[16:19]
	v_mfma_f32_16x16x32_bf16 v[16:19], v[210:213], v[234:237], v[16:19]
	v_mfma_f32_16x16x32_bf16 v[4:7], v[174:177], v[238:241], v[4:7]
	v_mfma_f32_16x16x32_bf16 v[4:7], v[182:185], v[242:245], v[4:7]
	v_mfma_f32_16x16x32_bf16 v[0:3], v[186:189], v[238:241], v[0:3]
	v_mfma_f32_16x16x32_bf16 v[0:3], v[210:213], v[242:245], v[0:3]
	s_setprio 0
	s_barrier
	s_add_i32 s56, s56, 2
	s_add_u32 s0, s0, 0x100
	s_addc_u32 s1, s1, 0
	s_add_u32 s54, s54, 0x100
	s_addc_u32 s55, s55, 0
	s_cmp_gt_u32 s56, 13
	s_cbranch_scc0 .LBB0_327
	s_and_b64 vcc, exec, s[22:23]
	s_cbranch_vccz .LBB0_330
	s_barrier

; #define PG8_STAGE(bufoff, gbase, voff) do { _Pragma("unroll") for (int _i = 0; _i < 2; ++_i) \
;         __builtin_amdgcn_global_load_lds((const unsigned*)((const char*)(gbase) + (voff)[_i]), (PG8_LAS unsigned*)(lds + (bufoff) + ldsw + _i * 8192), 16, 0, 0); } while (0)
; #define PG8_LDA(dst, b, h) do { _Pragma("unroll") for (int m = 0; m < 4; ++m) _Pragma("unroll") for (int k = 0; k < 2; ++k) dst[m][k] = *(const PG8_LAS bf16x8*)(lds + PG8_SA(b, h) + aoff + m * 2048 + k * 1024); } while (0)
; #define PG8_LDB(dst, b, h) do { _Pragma("unroll") for (int n = 0; n < 2; ++n) _Pragma("unroll") for (int k = 0; k < 2; ++k) dst[n][k] = *(const PG8_LAS bf16x8*)(lds + PG8_SB(b, h) + boff + n * 2048 + k * 1024); } while (0)
; #define PG8_MMA(ai, bj, At, Bt) do { __builtin_amdgcn_s_setprio(1); _Pragma("unroll") for (int m = 0; m < 4; ++m) _Pragma("unroll") for (int n = 0; n < 2; ++n) _Pragma("unroll") for (int k = 0; k < 2; ++k) \
;         acc[ai][bj][m][n] = __builtin_amdgcn_mfma_f32_16x16x32_bf16(Bt[n][k], At[m][k], acc[ai][bj][m][n], 0, 0, 0); __builtin_amdgcn_s_setprio(0); } while (0)
; #define PG8_WAIT_V(n) asm volatile("s_waitcnt vmcnt(" #n ")" ::: "memory")
; #define PG8_WAIT_L(n) asm volatile("s_waitcnt lgkmcnt(" #n ")" ::: "memory")
; template <class Epi, class Sched, bool ALIGN_EPI = false, bool SP2 = false>
; __device__ __forceinline__ void gemm_phase(PG8_LAS unsigned char* lds, const Gemm g, const Sched& S, const Epi& E) {
;     ...
;             const bool last = (t == nt - 2);
;             const char* a1 = cA + (size_t)(t + 1) * kstep;
;             const char* a2 = last ? nA : cA + (size_t)(t + 2) * kstep; const char* b2 = last ? nB : cB + (size_t)(t + 2) * kstep;
;             const char* a3 = a2 + kstep; const char* b3 = b2 + kstep;
;             if (last && has_next) S.a_ready(nxt);
;             if constexpr (SP2) {
;             PG8_LDB(B0, 0, 0); PG8_LDB(B1, 0, 1); PG8_SCHED; PG8_LDA(At, 0, 0); PG8_STAGE(PG8_SA(1, 1), a1 + hstep, voffA);
;             PG8_WAIT_V(8); PG8_WAIT_L(0); PG8_BAR; PG8_MMA(0, 0, At, B0); PG8_MMA(0, 1, At, B1); PG8_BAR; PG8_SCHED;
;             PG8_LDA(At, 0, 1); PG8_STAGE(PG8_SB(0, 0), b2, voffB); PG8_STAGE(PG8_SB(0, 1), b2 + hstep, voffB); PG8_STAGE(PG8_SA(0, 0), a2, voffA);
;             PG8_WAIT_V(8); PG8_WAIT_L(0); PG8_BAR; PG8_MMA(1, 0, At, B0); PG8_MMA(1, 1, At, B1); PG8_BAR; PG8_SCHED;
.Lup_peel:
	ds_read_b128 v[140:143], v254
	ds_read_b128 v[168:171], v254 offset:1024
	ds_read_b128 v[172:175], v254 offset:2048
	ds_read_b128 v[176:179], v254 offset:3072
	ds_read_b128 v[180:183], v254 offset:16384
	ds_read_b128 v[184:187], v254 offset:17408
	ds_read_b128 v[188:191], v254 offset:18432
	ds_read_b128 v[210:213], v254 offset:19456
	s_add_u32 s16, s14, 0xfffc0080
	s_addc_u32 s17, s15, -1
	s_cmp_eq_u32 s53, 12
	s_cselect_b32 s19, s7, s17
	s_cselect_b32 s18, s49, s16
	s_cselect_b32 s17, s5, s52
	s_cselect_b32 s16, s50, s51
	s_mov_b32 m0, s43
	ds_read_b128 v[214:217], v165
	ds_read_b128 v[218:221], v165 offset:1024
	ds_read_b128 v[222:225], v165 offset:2048
	ds_read_b128 v[226:229], v165 offset:3072
	ds_read_b128 v[230:233], v165 offset:4096
	ds_read_b128 v[234:237], v165 offset:5120
	ds_read_b128 v[238:241], v165 offset:6144
	ds_read_b128 v[242:245], v165 offset:7168
	global_load_lds_dwordx4 v136, s[14:15]
	s_mov_b32 m0, s44
	s_nop 0
	global_load_lds_dwordx4 v138, s[14:15]
	s_waitcnt vmcnt(8)
	s_waitcnt lgkmcnt(0)
	s_barrier
	s_setprio 1
	v_mfma_f32_16x16x32_bf16 v[124:127], v[140:143], v[214:217], 0
	v_mfma_f32_16x16x32_bf16 v[124:127], v[168:171], v[218:221], v[124:127]
	v_mfma_f32_16x16x32_bf16 v[116:119], v[172:175], v[214:217], 0
	v_mfma_f32_16x16x32_bf16 v[116:119], v[176:179], v[218:221], v[116:119]
	v_mfma_f32_16x16x32_bf16 v[108:111], v[140:143], v[222:225], 0
	v_mfma_f32_16x16x32_bf16 v[108:111], v[168:171], v[226:229], v[108:111]
	v_mfma_f32_16x16x32_bf16 v[100:103], v[172:175], v[222:225], 0
	v_mfma_f32_16x16x32_bf16 v[100:103], v[176:179], v[226:229], v[100:103]
	v_mfma_f32_16x16x32_bf16 v[92:95], v[140:143], v[230:233], 0
	v_mfma_f32_16x16x32_bf16 v[92:95], v[168:171], v[234:237], v[92:95]
	v_mfma_f32_16x16x32_bf16 v[84:87], v[172:175], v[230:233], 0
	v_mfma_f32_16x16x32_bf16 v[84:87], v[176:179], v[234:237], v[84:87]
	v_mfma_f32_16x16x32_bf16 v[76:79], v[140:143], v[238:241], 0
	v_mfma_f32_16x16x32_bf16 v[76:79], v[168:171], v[242:245], v[76:79]
	v_mfma_f32_16x16x32_bf16 v[68:71], v[172:175], v[238:241], 0
	v_mfma_f32_16x16x32_bf16 v[68:71], v[176:179], v[242:245], v[68:71]
	v_mfma_f32_16x16x32_bf16 v[120:123], v[180:183], v[214:217], 0
	v_mfma_f32_16x16x32_bf16 v[120:123], v[184:187], v[218:221], v[120:123]
	v_mfma_f32_16x16x32_bf16 v[112:115], v[188:191], v[214:217], 0
	v_mfma_f32_16x16x32_bf16 v[112:115], v[210:213], v[218:221], v[112:115]
	v_mfma_f32_16x16x32_bf16 v[104:107], v[180:183], v[222:225], 0
	v_mfma_f32_16x16x32_bf16 v[104:107], v[184:187], v[226:229], v[104:107]
	v_mfma_f32_16x16x32_bf16 v[96:99], v[188:191], v[222:225], 0
	v_mfma_f32_16x16x32_bf16 v[96:99], v[210:213], v[226:229], v[96:99]
	v_mfma_f32_16x16x32_bf16 v[88:91], v[180:183], v[230:233], 0
	v_mfma_f32_16x16x32_bf16 v[88:91], v[184:187], v[234:237], v[88:91]
	v_mfma_f32_16x16x32_bf16 v[80:83], v[188:191], v[230:233], 0
	v_mfma_f32_16x16x32_bf16 v[80:83], v[210:213], v[234:237], v[80:83]
	v_mfma_f32_16x16x32_bf16 v[72:75], v[180:183], v[238:241], 0
	v_mfma_f32_16x16x32_bf16 v[72:75], v[184:187], v[242:245], v[72:75]
	v_mfma_f32_16x16x32_bf16 v[64:67], v[188:191], v[238:241], 0
	v_mfma_f32_16x16x32_bf16 v[64:67], v[210:213], v[242:245], v[64:67]
	s_setprio 0
	s_barrier
	s_mov_b32 m0, s27
	s_add_u32 s54, s16, 0x40000
	s_addc_u32 s55, s17, 0
	ds_read_b128 v[214:217], v165 offset:16384
	ds_read_b128 v[218:221], v165 offset:17408
	ds_read_b128 v[222:225], v165 offset:18432
	ds_read_b128 v[226:229], v165 offset:19456
	ds_read_b128 v[230:233], v165 offset:20480
	ds_read_b128 v[234:237], v165 offset:21504
	ds_read_b128 v[238:241], v165 offset:22528
	ds_read_b128 v[242:245], v165 offset:23552
	global_load_lds_dwordx4 v132, s[16:17]
	s_mov_b32 m0, s28
	s_nop 0
	global_load_lds_dwordx4 v128, s[16:17]
	s_mov_b32 m0, s29
	s_nop 0
	global_load_lds_dwordx4 v132, s[54:55]
	s_mov_b32 m0, s30
	s_nop 0
	global_load_lds_dwordx4 v128, s[54:55]
	s_mov_b32 m0, s22
	s_nop 0
	global_load_lds_dwordx4 v134, s[18:19]
	s_mov_b32 m0, s31
	s_nop 0
	global_load_lds_dwordx4 v130, s[18:19]
	s_waitcnt vmcnt(8)
	s_waitcnt lgkmcnt(0)
	s_barrier
	s_setprio 1
	v_mfma_f32_16x16x32_bf16 v[60:63], v[140:143], v[214:217], 0
	v_mfma_f32_16x16x32_bf16 v[60:63], v[168:171], v[218:221], v[60:63]
	v_mfma_f32_16x16x32_bf16 v[52:55], v[172:175], v[214:217], 0
	v_mfma_f32_16x16x32_bf16 v[52:55], v[176:179], v[218:221], v[52:55]
	v_mfma_f32_16x16x32_bf16 v[44:47], v[140:143], v[222:225], 0
	v_mfma_f32_16x16x32_bf16 v[44:47], v[168:171], v[226:229], v[44:47]
	v_mfma_f32_16x16x32_bf16 v[36:39], v[172:175], v[222:225], 0
	v_mfma_f32_16x16x32_bf16 v[36:39], v[176:179], v[226:229], v[36:39]
	v_mfma_f32_16x16x32_bf16 v[28:31], v[140:143], v[230:233], 0
	v_mfma_f32_16x16x32_bf16 v[28:31], v[168:171], v[234:237], v[28:31]
	v_mfma_f32_16x16x32_bf16 v[20:23], v[172:175], v[230:233], 0
	v_mfma_f32_16x16x32_bf16 v[20:23], v[176:179], v[234:237], v[20:23]
	v_mfma_f32_16x16x32_bf16 v[12:15], v[140:143], v[238:241], 0
	v_mfma_f32_16x16x32_bf16 v[12:15], v[168:171], v[242:245], v[12:15]
	v_mfma_f32_16x16x32_bf16 v[4:7], v[172:175], v[238:241], 0
	v_mfma_f32_16x16x32_bf16 v[4:7], v[176:179], v[242:245], v[4:7]
	v_mfma_f32_16x16x32_bf16 v[56:59], v[180:183], v[214:217], 0
	v_mfma_f32_16x16x32_bf16 v[56:59], v[184:187], v[218:221], v[56:59]
	v_mfma_f32_16x16x32_bf16 v[48:51], v[188:191], v[214:217], 0
	v_mfma_f32_16x16x32_bf16 v[48:51], v[210:213], v[218:221], v[48:51]
	v_mfma_f32_16x16x32_bf16 v[40:43], v[180:183], v[222:225], 0
	v_mfma_f32_16x16x32_bf16 v[40:43], v[184:187], v[226:229], v[40:43]
	v_mfma_f32_16x16x32_bf16 v[32:35], v[188:191], v[222:225], 0
	v_mfma_f32_16x16x32_bf16 v[32:35], v[210:213], v[226:229], v[32:35]
	v_mfma_f32_16x16x32_bf16 v[24:27], v[180:183], v[230:233], 0
	v_mfma_f32_16x16x32_bf16 v[24:27], v[184:187], v[234:237], v[24:27]
	v_mfma_f32_16x16x32_bf16 v[16:19], v[188:191], v[230:233], 0
	v_mfma_f32_16x16x32_bf16 v[16:19], v[210:213], v[234:237], v[16:19]
	v_mfma_f32_16x16x32_bf16 v[8:11], v[180:183], v[238:241], 0
	v_mfma_f32_16x16x32_bf16 v[8:11], v[184:187], v[242:245], v[8:11]
	v_mfma_f32_16x16x32_bf16 v[0:3], v[188:191], v[238:241], 0
	v_mfma_f32_16x16x32_bf16 v[0:3], v[210:213], v[242:245], v[0:3]
	s_setprio 0
	s_barrier
; #define PG8_STAGE(bufoff, gbase, voff) do { _Pragma("unroll") for (int _i = 0; _i < 2; ++_i) \
;         __builtin_amdgcn_global_load_lds((const unsigned*)((const char*)(gbase) + (voff)[_i]), (PG8_LAS unsigned*)(lds + (bufoff) + ldsw + _i * 8192), 16, 0, 0); } while (0)
; #define PG8_LDA(dst, b, h) do { _Pragma("unroll") for (int m = 0; m < 4; ++m) _Pragma("unroll") for (int k = 0; k < 2; ++k) dst[m][k] = *(const PG8_LAS bf16x8*)(lds + PG8_SA(b, h) + aoff + m * 2048 + k * 1024); } while (0)
; #define PG8_LDB(dst, b, h) do { _Pragma("unroll") for (int n = 0; n < 2; ++n) _Pragma("unroll") for (int k = 0; k < 2; ++k) dst[n][k] = *(const PG8_LAS bf16x8*)(lds + PG8_SB(b, h) + boff + n * 2048 + k * 1024); } while (0)
; #define PG8_MMA(ai, bj, At, Bt) do { __builtin_amdgcn_s_setprio(1); _Pragma("unroll") for (int m = 0; m < 4; ++m) _Pragma("unroll") for (int n = 0; n < 2; ++n) _Pragma("unroll") for (int k = 0; k < 2; ++k) \
;         acc[ai][bj][m][n] = __builtin_amdgcn_mfma_f32_16x16x32_bf16(Bt[n][k], At[m][k], acc[ai][bj][m][n], 0, 0, 0); __builtin_amdgcn_s_setprio(0); } while (0)
; #define PG8_WAIT_V(n) asm volatile("s_waitcnt vmcnt(" #n ")" ::: "memory")
; #define PG8_WAIT_L(n) asm volatile("s_waitcnt lgkmcnt(" #n ")" ::: "memory")
; #define PG8_BAR __builtin_amdgcn_s_barrier()
; #define PG8_SCHED __builtin_amdgcn_sched_barrier(0)
; template <class Epi, class Sched, bool ALIGN_EPI = false, bool SP2 = false>
; __device__ __forceinline__ void gemm_phase(PG8_LAS unsigned char* lds, const Gemm g, const Sched& S, const Epi& E) {
;     ...
;             PG8_LDB(B0, 1, 0); PG8_LDB(B1, 1, 1); PG8_SCHED; PG8_LDA(At, 1, 0); PG8_STAGE(PG8_SA(0, 1), a2 + hstep, voffA);
;             PG8_WAIT_V(8); PG8_WAIT_L(0); PG8_BAR; PG8_MMA(0, 0, At, B0); PG8_MMA(0, 1, At, B1); PG8_BAR; PG8_SCHED;
;             PG8_LDA(At, 1, 1); PG8_STAGE(PG8_SB(1, 0), b3, voffB); PG8_STAGE(PG8_SB(1, 1), b3 + hstep, voffB); PG8_STAGE(PG8_SA(1, 0), a3, voffA);
;             PG8_WAIT_V(8); PG8_WAIT_L(0); PG8_BAR; PG8_MMA(1, 0, At, B0); PG8_MMA(1, 1, At, B1); PG8_BAR; PG8_SCHED;
	ds_read_b128 v[140:143], v254 offset:32768
	ds_read_b128 v[168:171], v254 offset:33792
	ds_read_b128 v[172:175], v254 offset:34816
	ds_read_b128 v[176:179], v254 offset:35840
	ds_read_b128 v[180:183], v254 offset:49152
	ds_read_b128 v[184:187], v254 offset:50176
	ds_read_b128 v[188:191], v254 offset:51200
	ds_read_b128 v[210:213], v254 offset:52224
	s_add_u32 s18, s18, 0x40000
	s_addc_u32 s19, s19, 0
	s_mov_b32 m0, s33
	ds_read_b128 v[214:217], v165 offset:32768
	ds_read_b128 v[218:221], v165 offset:33792
	ds_read_b128 v[222:225], v165 offset:34816
	ds_read_b128 v[226:229], v165 offset:35840
	ds_read_b128 v[230:233], v165 offset:36864
	ds_read_b128 v[234:237], v165 offset:37888
	ds_read_b128 v[238:241], v165 offset:38912
	ds_read_b128 v[242:245], v165 offset:39936
	global_load_lds_dwordx4 v134, s[18:19]
	s_mov_b32 m0, s34
	s_nop 0
	global_load_lds_dwordx4 v130, s[18:19]
	s_waitcnt vmcnt(8)
	s_waitcnt lgkmcnt(0)
	s_barrier
	s_setprio 1
	v_mfma_f32_16x16x32_bf16 v[124:127], v[140:143], v[214:217], v[124:127]
	v_mfma_f32_16x16x32_bf16 v[124:127], v[168:171], v[218:221], v[124:127]
	v_mfma_f32_16x16x32_bf16 v[116:119], v[172:175], v[214:217], v[116:119]
	v_mfma_f32_16x16x32_bf16 v[116:119], v[176:179], v[218:221], v[116:119]
	v_mfma_f32_16x16x32_bf16 v[108:111], v[140:143], v[222:225], v[108:111]
	v_mfma_f32_16x16x32_bf16 v[108:111], v[168:171], v[226:229], v[108:111]
	v_mfma_f32_16x16x32_bf16 v[100:103], v[172:175], v[222:225], v[100:103]
	v_mfma_f32_16x16x32_bf16 v[100:103], v[176:179], v[226:229], v[100:103]
	v_mfma_f32_16x16x32_bf16 v[92:95], v[140:143], v[230:233], v[92:95]
	v_mfma_f32_16x16x32_bf16 v[92:95], v[168:171], v[234:237], v[92:95]
	v_mfma_f32_16x16x32_bf16 v[84:87], v[172:175], v[230:233], v[84:87]
	v_mfma_f32_16x16x32_bf16 v[84:87], v[176:179], v[234:237], v[84:87]
	v_mfma_f32_16x16x32_bf16 v[76:79], v[140:143], v[238:241], v[76:79]
	v_mfma_f32_16x16x32_bf16 v[76:79], v[168:171], v[242:245], v[76:79]
	v_mfma_f32_16x16x32_bf16 v[68:71], v[172:175], v[238:241], v[68:71]
	v_mfma_f32_16x16x32_bf16 v[68:71], v[176:179], v[242:245], v[68:71]
	v_mfma_f32_16x16x32_bf16 v[120:123], v[180:183], v[214:217], v[120:123]
	v_mfma_f32_16x16x32_bf16 v[120:123], v[184:187], v[218:221], v[120:123]
	v_mfma_f32_16x16x32_bf16 v[112:115], v[188:191], v[214:217], v[112:115]
	v_mfma_f32_16x16x32_bf16 v[112:115], v[210:213], v[218:221], v[112:115]
	v_mfma_f32_16x16x32_bf16 v[104:107], v[180:183], v[222:225], v[104:107]
	v_mfma_f32_16x16x32_bf16 v[104:107], v[184:187], v[226:229], v[104:107]
	v_mfma_f32_16x16x32_bf16 v[96:99], v[188:191], v[222:225], v[96:99]
	v_mfma_f32_16x16x32_bf16 v[96:99], v[210:213], v[226:229], v[96:99]
	v_mfma_f32_16x16x32_bf16 v[88:91], v[180:183], v[230:233], v[88:91]
	v_mfma_f32_16x16x32_bf16 v[88:91], v[184:187], v[234:237], v[88:91]
	v_mfma_f32_16x16x32_bf16 v[80:83], v[188:191], v[230:233], v[80:83]
	v_mfma_f32_16x16x32_bf16 v[80:83], v[210:213], v[234:237], v[80:83]
	v_mfma_f32_16x16x32_bf16 v[72:75], v[180:183], v[238:241], v[72:75]
	v_mfma_f32_16x16x32_bf16 v[72:75], v[184:187], v[242:245], v[72:75]
	v_mfma_f32_16x16x32_bf16 v[64:67], v[188:191], v[238:241], v[64:67]
	v_mfma_f32_16x16x32_bf16 v[64:67], v[210:213], v[242:245], v[64:67]
	s_setprio 0
	s_barrier
	s_mov_b32 m0, s37
	s_add_u32 s16, s16, 0x40080
	s_addc_u32 s17, s17, 0
	ds_read_b128 v[214:217], v165 offset:49152
	ds_read_b128 v[218:221], v165 offset:50176
	ds_read_b128 v[222:225], v165 offset:51200
	ds_read_b128 v[226:229], v165 offset:52224
	ds_read_b128 v[230:233], v165 offset:53248
	ds_read_b128 v[234:237], v165 offset:54272
	ds_read_b128 v[238:241], v165 offset:55296
	ds_read_b128 v[242:245], v165 offset:56320
	s_add_u32 s98, s16, 0xfffc0000
	s_addc_u32 s99, s17, -1
	global_load_lds_dwordx4 v132, s[98:99]
	s_mov_b32 m0, s38
	s_nop 0
	global_load_lds_dwordx4 v128, s[98:99]
	s_mov_b32 m0, s41
	s_nop 0
	global_load_lds_dwordx4 v132, s[16:17]
	s_mov_b32 m0, s42
	s_nop 0
	global_load_lds_dwordx4 v128, s[16:17]
	s_mov_b32 m0, s39
	s_nop 0
	s_add_u32 s100, s18, 0xfffc0080
	s_addc_u32 s101, s19, -1
	global_load_lds_dwordx4 v134, s[100:101]
	s_mov_b32 m0, s40
	s_nop 0
	global_load_lds_dwordx4 v130, s[100:101]
	s_waitcnt vmcnt(8)
	s_waitcnt lgkmcnt(0)
	s_barrier
	s_setprio 1
	v_mfma_f32_16x16x32_bf16 v[60:63], v[140:143], v[214:217], v[60:63]
	v_mfma_f32_16x16x32_bf16 v[60:63], v[168:171], v[218:221], v[60:63]
	v_mfma_f32_16x16x32_bf16 v[52:55], v[172:175], v[214:217], v[52:55]
	v_mfma_f32_16x16x32_bf16 v[52:55], v[176:179], v[218:221], v[52:55]
	v_mfma_f32_16x16x32_bf16 v[44:47], v[140:143], v[222:225], v[44:47]
	v_mfma_f32_16x16x32_bf16 v[44:47], v[168:171], v[226:229], v[44:47]
	v_mfma_f32_16x16x32_bf16 v[36:39], v[172:175], v[222:225], v[36:39]
	v_mfma_f32_16x16x32_bf16 v[36:39], v[176:179], v[226:229], v[36:39]
	v_mfma_f32_16x16x32_bf16 v[28:31], v[140:143], v[230:233], v[28:31]
	v_mfma_f32_16x16x32_bf16 v[28:31], v[168:171], v[234:237], v[28:31]
	v_mfma_f32_16x16x32_bf16 v[20:23], v[172:175], v[230:233], v[20:23]
	v_mfma_f32_16x16x32_bf16 v[20:23], v[176:179], v[234:237], v[20:23]
	v_mfma_f32_16x16x32_bf16 v[12:15], v[140:143], v[238:241], v[12:15]
	v_mfma_f32_16x16x32_bf16 v[12:15], v[168:171], v[242:245], v[12:15]
	v_mfma_f32_16x16x32_bf16 v[4:7], v[172:175], v[238:241], v[4:7]
	v_mfma_f32_16x16x32_bf16 v[4:7], v[176:179], v[242:245], v[4:7]
	v_mfma_f32_16x16x32_bf16 v[56:59], v[180:183], v[214:217], v[56:59]
	v_mfma_f32_16x16x32_bf16 v[56:59], v[184:187], v[218:221], v[56:59]
	v_mfma_f32_16x16x32_bf16 v[48:51], v[188:191], v[214:217], v[48:51]
	v_mfma_f32_16x16x32_bf16 v[48:51], v[210:213], v[218:221], v[48:51]
	v_mfma_f32_16x16x32_bf16 v[40:43], v[180:183], v[222:225], v[40:43]
	v_mfma_f32_16x16x32_bf16 v[40:43], v[184:187], v[226:229], v[40:43]
	v_mfma_f32_16x16x32_bf16 v[32:35], v[188:191], v[222:225], v[32:35]
	v_mfma_f32_16x16x32_bf16 v[32:35], v[210:213], v[226:229], v[32:35]
	v_mfma_f32_16x16x32_bf16 v[24:27], v[180:183], v[230:233], v[24:27]
	v_mfma_f32_16x16x32_bf16 v[24:27], v[184:187], v[234:237], v[24:27]
	v_mfma_f32_16x16x32_bf16 v[16:19], v[188:191], v[230:233], v[16:19]
	v_mfma_f32_16x16x32_bf16 v[16:19], v[210:213], v[234:237], v[16:19]
	v_mfma_f32_16x16x32_bf16 v[8:11], v[180:183], v[238:241], v[8:11]
	v_mfma_f32_16x16x32_bf16 v[8:11], v[184:187], v[242:245], v[8:11]
	v_mfma_f32_16x16x32_bf16 v[0:3], v[188:191], v[238:241], v[0:3]
	v_mfma_f32_16x16x32_bf16 v[0:3], v[210:213], v[242:245], v[0:3]
	s_setprio 0
	s_barrier
	s_add_i32 s53, s53, 2
	s_add_u32 s14, s14, 0x100
	s_addc_u32 s15, s15, 0
	s_add_u32 s51, s51, 0x100
	s_addc_u32 s52, s52, 0
	s_cmp_gt_u32 s53, 13
; #define PG8_STAGE(bufoff, gbase, voff) do { _Pragma("unroll") for (int _i = 0; _i < 2; ++_i) \
;         __builtin_amdgcn_global_load_lds((const unsigned*)((const char*)(gbase) + (voff)[_i]), (PG8_LAS unsigned*)(lds + (bufoff) + ldsw + _i * 8192), 16, 0, 0); } while (0)
; #define PG8_LDA(dst, b, h) do { _Pragma("unroll") for (int m = 0; m < 4; ++m) _Pragma("unroll") for (int k = 0; k < 2; ++k) dst[m][k] = *(const PG8_LAS bf16x8*)(lds + PG8_SA(b, h) + aoff + m * 2048 + k * 1024); } while (0)
; #define PG8_LDB(dst, b, h) do { _Pragma("unroll") for (int n = 0; n < 2; ++n) _Pragma("unroll") for (int k = 0; k < 2; ++k) dst[n][k] = *(const PG8_LAS bf16x8*)(lds + PG8_SB(b, h) + boff + n * 2048 + k * 1024); } while (0)
; #define PG8_MMA(ai, bj, At, Bt) do { __builtin_amdgcn_s_setprio(1); _Pragma("unroll") for (int m = 0; m < 4; ++m) _Pragma("unroll") for (int n = 0; n < 2; ++n) _Pragma("unroll") for (int k = 0; k < 2; ++k) \
;         acc[ai][bj][m][n] = __builtin_amdgcn_mfma_f32_16x16x32_bf16(Bt[n][k], At[m][k], acc[ai][bj][m][n], 0, 0, 0); __builtin_amdgcn_s_setprio(0); } while (0)
; #define PG8_WAIT_V(n) asm volatile("s_waitcnt vmcnt(" #n ")" ::: "memory")
; #define PG8_WAIT_L(n) asm volatile("s_waitcnt lgkmcnt(" #n ")" ::: "memory")
; template <class Epi, class Sched, bool ALIGN_EPI = false, bool SP2 = false>
; __device__ __forceinline__ void gemm_phase(PG8_LAS unsigned char* lds, const Gemm g, const Sched& S, const Epi& E) {
;     ...
;             const bool last = (t == nt - 2);
;             const char* a1 = cA + (size_t)(t + 1) * kstep;
;             const char* a2 = last ? nA : cA + (size_t)(t + 2) * kstep; const char* b2 = last ? nB : cB + (size_t)(t + 2) * kstep;
;             const char* a3 = a2 + kstep; const char* b3 = b2 + kstep;
;             if (last && has_next) S.a_ready(nxt);
;             if constexpr (SP2) {
;             PG8_LDB(B0, 0, 0); PG8_LDB(B1, 0, 1); PG8_SCHED; PG8_LDA(At, 0, 0); PG8_STAGE(PG8_SA(1, 1), a1 + hstep, voffA);
;             PG8_WAIT_V(8); PG8_WAIT_L(0); PG8_BAR; PG8_MMA(0, 0, At, B0); PG8_MMA(0, 1, At, B1); PG8_BAR; PG8_SCHED;
;             PG8_LDA(At, 0, 1); PG8_STAGE(PG8_SB(0, 0), b2, voffB); PG8_STAGE(PG8_SB(0, 1), b2 + hstep, voffB); PG8_STAGE(PG8_SA(0, 0), a2, voffA);
;             PG8_WAIT_V(8); PG8_WAIT_L(0); PG8_BAR; PG8_MMA(1, 0, At, B0); PG8_MMA(1, 1, At, B1); PG8_BAR; PG8_SCHED;
.LBB0_446:
	ds_read_b128 v[140:143], v254
	ds_read_b128 v[168:171], v254 offset:1024
	ds_read_b128 v[172:175], v254 offset:2048
	ds_read_b128 v[176:179], v254 offset:3072
	ds_read_b128 v[180:183], v254 offset:16384
	ds_read_b128 v[184:187], v254 offset:17408
	ds_read_b128 v[188:191], v254 offset:18432
	ds_read_b128 v[210:213], v254 offset:19456
	s_add_u32 s16, s14, 0xfffc0080
	s_addc_u32 s17, s15, -1
	s_cmp_eq_u32 s53, 12
	s_cselect_b32 s19, s7, s17
	s_cselect_b32 s18, s49, s16
	s_cselect_b32 s17, s5, s52
	s_cselect_b32 s16, s50, s51
	s_mov_b32 m0, s43
	ds_read_b128 v[214:217], v165
	ds_read_b128 v[218:221], v165 offset:1024
	ds_read_b128 v[222:225], v165 offset:2048
	ds_read_b128 v[226:229], v165 offset:3072
	ds_read_b128 v[230:233], v165 offset:4096
	ds_read_b128 v[234:237], v165 offset:5120
	ds_read_b128 v[238:241], v165 offset:6144
	ds_read_b128 v[242:245], v165 offset:7168
	global_load_lds_dwordx4 v136, s[14:15]
	s_mov_b32 m0, s44
	s_nop 0
	global_load_lds_dwordx4 v138, s[14:15]
	s_waitcnt vmcnt(8)
	s_waitcnt lgkmcnt(0)
	s_barrier
	s_setprio 1
	v_mfma_f32_16x16x32_bf16 v[124:127], v[140:143], v[214:217], v[124:127]
	v_mfma_f32_16x16x32_bf16 v[124:127], v[168:171], v[218:221], v[124:127]
	v_mfma_f32_16x16x32_bf16 v[116:119], v[172:175], v[214:217], v[116:119]
	v_mfma_f32_16x16x32_bf16 v[116:119], v[176:179], v[218:221], v[116:119]
	v_mfma_f32_16x16x32_bf16 v[108:111], v[140:143], v[222:225], v[108:111]
	v_mfma_f32_16x16x32_bf16 v[108:111], v[168:171], v[226:229], v[108:111]
	v_mfma_f32_16x16x32_bf16 v[100:103], v[172:175], v[222:225], v[100:103]
	v_mfma_f32_16x16x32_bf16 v[100:103], v[176:179], v[226:229], v[100:103]
	v_mfma_f32_16x16x32_bf16 v[92:95], v[140:143], v[230:233], v[92:95]
	v_mfma_f32_16x16x32_bf16 v[92:95], v[168:171], v[234:237], v[92:95]
	v_mfma_f32_16x16x32_bf16 v[84:87], v[172:175], v[230:233], v[84:87]
	v_mfma_f32_16x16x32_bf16 v[84:87], v[176:179], v[234:237], v[84:87]
	v_mfma_f32_16x16x32_bf16 v[76:79], v[140:143], v[238:241], v[76:79]
	v_mfma_f32_16x16x32_bf16 v[76:79], v[168:171], v[242:245], v[76:79]
	v_mfma_f32_16x16x32_bf16 v[68:71], v[172:175], v[238:241], v[68:71]
	v_mfma_f32_16x16x32_bf16 v[68:71], v[176:179], v[242:245], v[68:71]
	v_mfma_f32_16x16x32_bf16 v[120:123], v[180:183], v[214:217], v[120:123]
	v_mfma_f32_16x16x32_bf16 v[120:123], v[184:187], v[218:221], v[120:123]
	v_mfma_f32_16x16x32_bf16 v[112:115], v[188:191], v[214:217], v[112:115]
	v_mfma_f32_16x16x32_bf16 v[112:115], v[210:213], v[218:221], v[112:115]
	v_mfma_f32_16x16x32_bf16 v[104:107], v[180:183], v[222:225], v[104:107]
	v_mfma_f32_16x16x32_bf16 v[104:107], v[184:187], v[226:229], v[104:107]
	v_mfma_f32_16x16x32_bf16 v[96:99], v[188:191], v[222:225], v[96:99]
	v_mfma_f32_16x16x32_bf16 v[96:99], v[210:213], v[226:229], v[96:99]
	v_mfma_f32_16x16x32_bf16 v[88:91], v[180:183], v[230:233], v[88:91]
	v_mfma_f32_16x16x32_bf16 v[88:91], v[184:187], v[234:237], v[88:91]
	v_mfma_f32_16x16x32_bf16 v[80:83], v[188:191], v[230:233], v[80:83]
	v_mfma_f32_16x16x32_bf16 v[80:83], v[210:213], v[234:237], v[80:83]
	v_mfma_f32_16x16x32_bf16 v[72:75], v[180:183], v[238:241], v[72:75]
	v_mfma_f32_16x16x32_bf16 v[72:75], v[184:187], v[242:245], v[72:75]
	v_mfma_f32_16x16x32_bf16 v[64:67], v[188:191], v[238:241], v[64:67]
	v_mfma_f32_16x16x32_bf16 v[64:67], v[210:213], v[242:245], v[64:67]
	s_setprio 0
	s_barrier
	s_mov_b32 m0, s27
	s_add_u32 s54, s16, 0x40000
	s_addc_u32 s55, s17, 0
	ds_read_b128 v[214:217], v165 offset:16384
	ds_read_b128 v[218:221], v165 offset:17408
	ds_read_b128 v[222:225], v165 offset:18432
	ds_read_b128 v[226:229], v165 offset:19456
	ds_read_b128 v[230:233], v165 offset:20480
	ds_read_b128 v[234:237], v165 offset:21504
	ds_read_b128 v[238:241], v165 offset:22528
	ds_read_b128 v[242:245], v165 offset:23552
	global_load_lds_dwordx4 v132, s[16:17]
	s_mov_b32 m0, s28
	s_nop 0
	global_load_lds_dwordx4 v128, s[16:17]
	s_mov_b32 m0, s29
	s_nop 0
	global_load_lds_dwordx4 v132, s[54:55]
	s_mov_b32 m0, s30
	s_nop 0
	global_load_lds_dwordx4 v128, s[54:55]
	s_mov_b32 m0, s22
	s_nop 0
	global_load_lds_dwordx4 v134, s[18:19]
	s_mov_b32 m0, s31
	s_nop 0
	global_load_lds_dwordx4 v130, s[18:19]
	s_waitcnt vmcnt(8)
	s_waitcnt lgkmcnt(0)
	s_barrier
	s_setprio 1
	v_mfma_f32_16x16x32_bf16 v[60:63], v[140:143], v[214:217], v[60:63]
	v_mfma_f32_16x16x32_bf16 v[60:63], v[168:171], v[218:221], v[60:63]
	v_mfma_f32_16x16x32_bf16 v[52:55], v[172:175], v[214:217], v[52:55]
	v_mfma_f32_16x16x32_bf16 v[52:55], v[176:179], v[218:221], v[52:55]
	v_mfma_f32_16x16x32_bf16 v[44:47], v[140:143], v[222:225], v[44:47]
	v_mfma_f32_16x16x32_bf16 v[44:47], v[168:171], v[226:229], v[44:47]
	v_mfma_f32_16x16x32_bf16 v[36:39], v[172:175], v[222:225], v[36:39]
	v_mfma_f32_16x16x32_bf16 v[36:39], v[176:179], v[226:229], v[36:39]
	v_mfma_f32_16x16x32_bf16 v[28:31], v[140:143], v[230:233], v[28:31]
	v_mfma_f32_16x16x32_bf16 v[28:31], v[168:171], v[234:237], v[28:31]
	v_mfma_f32_16x16x32_bf16 v[20:23], v[172:175], v[230:233], v[20:23]
	v_mfma_f32_16x16x32_bf16 v[20:23], v[176:179], v[234:237], v[20:23]
	v_mfma_f32_16x16x32_bf16 v[12:15], v[140:143], v[238:241], v[12:15]
	v_mfma_f32_16x16x32_bf16 v[12:15], v[168:171], v[242:245], v[12:15]
	v_mfma_f32_16x16x32_bf16 v[4:7], v[172:175], v[238:241], v[4:7]
	v_mfma_f32_16x16x32_bf16 v[4:7], v[176:179], v[242:245], v[4:7]
	v_mfma_f32_16x16x32_bf16 v[56:59], v[180:183], v[214:217], v[56:59]
	v_mfma_f32_16x16x32_bf16 v[56:59], v[184:187], v[218:221], v[56:59]
	v_mfma_f32_16x16x32_bf16 v[48:51], v[188:191], v[214:217], v[48:51]
	v_mfma_f32_16x16x32_bf16 v[48:51], v[210:213], v[218:221], v[48:51]
	v_mfma_f32_16x16x32_bf16 v[40:43], v[180:183], v[222:225], v[40:43]
	v_mfma_f32_16x16x32_bf16 v[40:43], v[184:187], v[226:229], v[40:43]
	v_mfma_f32_16x16x32_bf16 v[32:35], v[188:191], v[222:225], v[32:35]
	v_mfma_f32_16x16x32_bf16 v[32:35], v[210:213], v[226:229], v[32:35]
	v_mfma_f32_16x16x32_bf16 v[24:27], v[180:183], v[230:233], v[24:27]
	v_mfma_f32_16x16x32_bf16 v[24:27], v[184:187], v[234:237], v[24:27]
	v_mfma_f32_16x16x32_bf16 v[16:19], v[188:191], v[230:233], v[16:19]
	v_mfma_f32_16x16x32_bf16 v[16:19], v[210:213], v[234:237], v[16:19]
	v_mfma_f32_16x16x32_bf16 v[8:11], v[180:183], v[238:241], v[8:11]
	v_mfma_f32_16x16x32_bf16 v[8:11], v[184:187], v[242:245], v[8:11]
	v_mfma_f32_16x16x32_bf16 v[0:3], v[188:191], v[238:241], v[0:3]
	v_mfma_f32_16x16x32_bf16 v[0:3], v[210:213], v[242:245], v[0:3]
	s_setprio 0
	s_barrier
; #define PG8_STAGE(bufoff, gbase, voff) do { _Pragma("unroll") for (int _i = 0; _i < 2; ++_i) \
;         __builtin_amdgcn_global_load_lds((const unsigned*)((const char*)(gbase) + (voff)[_i]), (PG8_LAS unsigned*)(lds + (bufoff) + ldsw + _i * 8192), 16, 0, 0); } while (0)
; #define PG8_LDA(dst, b, h) do { _Pragma("unroll") for (int m = 0; m < 4; ++m) _Pragma("unroll") for (int k = 0; k < 2; ++k) dst[m][k] = *(const PG8_LAS bf16x8*)(lds + PG8_SA(b, h) + aoff + m * 2048 + k * 1024); } while (0)
; #define PG8_LDB(dst, b, h) do { _Pragma("unroll") for (int n = 0; n < 2; ++n) _Pragma("unroll") for (int k = 0; k < 2; ++k) dst[n][k] = *(const PG8_LAS bf16x8*)(lds + PG8_SB(b, h) + boff + n * 2048 + k * 1024); } while (0)
; #define PG8_MMA(ai, bj, At, Bt) do { __builtin_amdgcn_s_setprio(1); _Pragma("unroll") for (int m = 0; m < 4; ++m) _Pragma("unroll") for (int n = 0; n < 2; ++n) _Pragma("unroll") for (int k = 0; k < 2; ++k) \
;         acc[ai][bj][m][n] = __builtin_amdgcn_mfma_f32_16x16x32_bf16(Bt[n][k], At[m][k], acc[ai][bj][m][n], 0, 0, 0); __builtin_amdgcn_s_setprio(0); } while (0)
; #define PG8_WAIT_V(n) asm volatile("s_waitcnt vmcnt(" #n ")" ::: "memory")
; #define PG8_WAIT_L(n) asm volatile("s_waitcnt lgkmcnt(" #n ")" ::: "memory")
; #define PG8_BAR __builtin_amdgcn_s_barrier()
; #define PG8_SCHED __builtin_amdgcn_sched_barrier(0)
; template <class Epi, class Sched, bool ALIGN_EPI = false, bool SP2 = false>
; __device__ __forceinline__ void gemm_phase(PG8_LAS unsigned char* lds, const Gemm g, const Sched& S, const Epi& E) {
;     ...
;             PG8_LDB(B0, 1, 0); PG8_LDB(B1, 1, 1); PG8_SCHED; PG8_LDA(At, 1, 0); PG8_STAGE(PG8_SA(0, 1), a2 + hstep, voffA);
;             PG8_WAIT_V(8); PG8_WAIT_L(0); PG8_BAR; PG8_MMA(0, 0, At, B0); PG8_MMA(0, 1, At, B1); PG8_BAR; PG8_SCHED;
;             PG8_LDA(At, 1, 1); PG8_STAGE(PG8_SB(1, 0), b3, voffB); PG8_STAGE(PG8_SB(1, 1), b3 + hstep, voffB); PG8_STAGE(PG8_SA(1, 0), a3, voffA);
;             PG8_WAIT_V(8); PG8_WAIT_L(0); PG8_BAR; PG8_MMA(1, 0, At, B0); PG8_MMA(1, 1, At, B1); PG8_BAR; PG8_SCHED;
	ds_read_b128 v[140:143], v254 offset:32768
	ds_read_b128 v[168:171], v254 offset:33792
	ds_read_b128 v[172:175], v254 offset:34816
	ds_read_b128 v[176:179], v254 offset:35840
	ds_read_b128 v[180:183], v254 offset:49152
	ds_read_b128 v[184:187], v254 offset:50176
	ds_read_b128 v[188:191], v254 offset:51200
	ds_read_b128 v[210:213], v254 offset:52224
	s_add_u32 s18, s18, 0x40000
	s_addc_u32 s19, s19, 0
	s_mov_b32 m0, s33
	ds_read_b128 v[214:217], v165 offset:32768
	ds_read_b128 v[218:221], v165 offset:33792
	ds_read_b128 v[222:225], v165 offset:34816
	ds_read_b128 v[226:229], v165 offset:35840
	ds_read_b128 v[230:233], v165 offset:36864
	ds_read_b128 v[234:237], v165 offset:37888
	ds_read_b128 v[238:241], v165 offset:38912
	ds_read_b128 v[242:245], v165 offset:39936
	global_load_lds_dwordx4 v134, s[18:19]
	s_mov_b32 m0, s34
	s_nop 0
	global_load_lds_dwordx4 v130, s[18:19]
	s_waitcnt vmcnt(8)
	s_waitcnt lgkmcnt(0)
	s_barrier
	s_setprio 1
	v_mfma_f32_16x16x32_bf16 v[124:127], v[140:143], v[214:217], v[124:127]
	v_mfma_f32_16x16x32_bf16 v[124:127], v[168:171], v[218:221], v[124:127]
	v_mfma_f32_16x16x32_bf16 v[116:119], v[172:175], v[214:217], v[116:119]
	v_mfma_f32_16x16x32_bf16 v[116:119], v[176:179], v[218:221], v[116:119]
	v_mfma_f32_16x16x32_bf16 v[108:111], v[140:143], v[222:225], v[108:111]
	v_mfma_f32_16x16x32_bf16 v[108:111], v[168:171], v[226:229], v[108:111]
	v_mfma_f32_16x16x32_bf16 v[100:103], v[172:175], v[222:225], v[100:103]
	v_mfma_f32_16x16x32_bf16 v[100:103], v[176:179], v[226:229], v[100:103]
	v_mfma_f32_16x16x32_bf16 v[92:95], v[140:143], v[230:233], v[92:95]
	v_mfma_f32_16x16x32_bf16 v[92:95], v[168:171], v[234:237], v[92:95]
	v_mfma_f32_16x16x32_bf16 v[84:87], v[172:175], v[230:233], v[84:87]
	v_mfma_f32_16x16x32_bf16 v[84:87], v[176:179], v[234:237], v[84:87]
	v_mfma_f32_16x16x32_bf16 v[76:79], v[140:143], v[238:241], v[76:79]
	v_mfma_f32_16x16x32_bf16 v[76:79], v[168:171], v[242:245], v[76:79]
	v_mfma_f32_16x16x32_bf16 v[68:71], v[172:175], v[238:241], v[68:71]
	v_mfma_f32_16x16x32_bf16 v[68:71], v[176:179], v[242:245], v[68:71]
	v_mfma_f32_16x16x32_bf16 v[120:123], v[180:183], v[214:217], v[120:123]
	v_mfma_f32_16x16x32_bf16 v[120:123], v[184:187], v[218:221], v[120:123]
	v_mfma_f32_16x16x32_bf16 v[112:115], v[188:191], v[214:217], v[112:115]
	v_mfma_f32_16x16x32_bf16 v[112:115], v[210:213], v[218:221], v[112:115]
	v_mfma_f32_16x16x32_bf16 v[104:107], v[180:183], v[222:225], v[104:107]
	v_mfma_f32_16x16x32_bf16 v[104:107], v[184:187], v[226:229], v[104:107]
	v_mfma_f32_16x16x32_bf16 v[96:99], v[188:191], v[222:225], v[96:99]
	v_mfma_f32_16x16x32_bf16 v[96:99], v[210:213], v[226:229], v[96:99]
	v_mfma_f32_16x16x32_bf16 v[88:91], v[180:183], v[230:233], v[88:91]
	v_mfma_f32_16x16x32_bf16 v[88:91], v[184:187], v[234:237], v[88:91]
	v_mfma_f32_16x16x32_bf16 v[80:83], v[188:191], v[230:233], v[80:83]
	v_mfma_f32_16x16x32_bf16 v[80:83], v[210:213], v[234:237], v[80:83]
	v_mfma_f32_16x16x32_bf16 v[72:75], v[180:183], v[238:241], v[72:75]
	v_mfma_f32_16x16x32_bf16 v[72:75], v[184:187], v[242:245], v[72:75]
	v_mfma_f32_16x16x32_bf16 v[64:67], v[188:191], v[238:241], v[64:67]
	v_mfma_f32_16x16x32_bf16 v[64:67], v[210:213], v[242:245], v[64:67]
	s_setprio 0
	s_barrier
	s_mov_b32 m0, s37
	s_add_u32 s16, s16, 0x40080
	s_addc_u32 s17, s17, 0
	ds_read_b128 v[214:217], v165 offset:49152
	ds_read_b128 v[218:221], v165 offset:50176
	ds_read_b128 v[222:225], v165 offset:51200
	ds_read_b128 v[226:229], v165 offset:52224
	ds_read_b128 v[230:233], v165 offset:53248
	ds_read_b128 v[234:237], v165 offset:54272
	ds_read_b128 v[238:241], v165 offset:55296
	ds_read_b128 v[242:245], v165 offset:56320
	s_add_u32 s98, s16, 0xfffc0000
	s_addc_u32 s99, s17, -1
	global_load_lds_dwordx4 v132, s[98:99]
	s_mov_b32 m0, s38
	s_nop 0
	global_load_lds_dwordx4 v128, s[98:99]
	s_mov_b32 m0, s41
	s_nop 0
	global_load_lds_dwordx4 v132, s[16:17]
	s_mov_b32 m0, s42
	s_nop 0
	global_load_lds_dwordx4 v128, s[16:17]
	s_mov_b32 m0, s39
	s_nop 0
	s_add_u32 s100, s18, 0xfffc0080
	s_addc_u32 s101, s19, -1
	global_load_lds_dwordx4 v134, s[100:101]
	s_mov_b32 m0, s40
	s_nop 0
	global_load_lds_dwordx4 v130, s[100:101]
	s_waitcnt vmcnt(8)
	s_waitcnt lgkmcnt(0)
	s_barrier
	s_setprio 1
	v_mfma_f32_16x16x32_bf16 v[60:63], v[140:143], v[214:217], v[60:63]
	v_mfma_f32_16x16x32_bf16 v[60:63], v[168:171], v[218:221], v[60:63]
	v_mfma_f32_16x16x32_bf16 v[52:55], v[172:175], v[214:217], v[52:55]
	v_mfma_f32_16x16x32_bf16 v[52:55], v[176:179], v[218:221], v[52:55]
	v_mfma_f32_16x16x32_bf16 v[44:47], v[140:143], v[222:225], v[44:47]
	v_mfma_f32_16x16x32_bf16 v[44:47], v[168:171], v[226:229], v[44:47]
	v_mfma_f32_16x16x32_bf16 v[36:39], v[172:175], v[222:225], v[36:39]
	v_mfma_f32_16x16x32_bf16 v[36:39], v[176:179], v[226:229], v[36:39]
	v_mfma_f32_16x16x32_bf16 v[28:31], v[140:143], v[230:233], v[28:31]
	v_mfma_f32_16x16x32_bf16 v[28:31], v[168:171], v[234:237], v[28:31]
	v_mfma_f32_16x16x32_bf16 v[20:23], v[172:175], v[230:233], v[20:23]
	v_mfma_f32_16x16x32_bf16 v[20:23], v[176:179], v[234:237], v[20:23]
	v_mfma_f32_16x16x32_bf16 v[12:15], v[140:143], v[238:241], v[12:15]
	v_mfma_f32_16x16x32_bf16 v[12:15], v[168:171], v[242:245], v[12:15]
	v_mfma_f32_16x16x32_bf16 v[4:7], v[172:175], v[238:241], v[4:7]
	v_mfma_f32_16x16x32_bf16 v[4:7], v[176:179], v[242:245], v[4:7]
	v_mfma_f32_16x16x32_bf16 v[56:59], v[180:183], v[214:217], v[56:59]
	v_mfma_f32_16x16x32_bf16 v[56:59], v[184:187], v[218:221], v[56:59]
	v_mfma_f32_16x16x32_bf16 v[48:51], v[188:191], v[214:217], v[48:51]
	v_mfma_f32_16x16x32_bf16 v[48:51], v[210:213], v[218:221], v[48:51]
	v_mfma_f32_16x16x32_bf16 v[40:43], v[180:183], v[222:225], v[40:43]
	v_mfma_f32_16x16x32_bf16 v[40:43], v[184:187], v[226:229], v[40:43]
	v_mfma_f32_16x16x32_bf16 v[32:35], v[188:191], v[222:225], v[32:35]
	v_mfma_f32_16x16x32_bf16 v[32:35], v[210:213], v[226:229], v[32:35]
	v_mfma_f32_16x16x32_bf16 v[24:27], v[180:183], v[230:233], v[24:27]
	v_mfma_f32_16x16x32_bf16 v[24:27], v[184:187], v[234:237], v[24:27]
	v_mfma_f32_16x16x32_bf16 v[16:19], v[188:191], v[230:233], v[16:19]
	v_mfma_f32_16x16x32_bf16 v[16:19], v[210:213], v[234:237], v[16:19]
	v_mfma_f32_16x16x32_bf16 v[8:11], v[180:183], v[238:241], v[8:11]
	v_mfma_f32_16x16x32_bf16 v[8:11], v[184:187], v[242:245], v[8:11]
	v_mfma_f32_16x16x32_bf16 v[0:3], v[188:191], v[238:241], v[0:3]
	v_mfma_f32_16x16x32_bf16 v[0:3], v[210:213], v[242:245], v[0:3]
	s_setprio 0
	s_barrier
	s_add_i32 s53, s53, 2
	s_add_u32 s14, s14, 0x100
	s_addc_u32 s15, s15, 0
	s_add_u32 s51, s51, 0x100
	s_addc_u32 s52, s52, 0
	s_cmp_gt_u32 s53, 13
	s_cbranch_scc0 .LBB0_446
	s_and_b64 vcc, exec, s[2:3]
	s_cbranch_vccz .LBB0_449
	s_barrier

; #define PG8_STAGE(bufoff, gbase, voff) do { _Pragma("unroll") for (int _i = 0; _i < 2; ++_i) \
;         __builtin_amdgcn_global_load_lds((const unsigned*)((const char*)(gbase) + (voff)[_i]), (PG8_LAS unsigned*)(lds + (bufoff) + ldsw + _i * 8192), 16, 0, 0); } while (0)
; #define PG8_LDA(dst, b, h) do { _Pragma("unroll") for (int m = 0; m < 4; ++m) _Pragma("unroll") for (int k = 0; k < 2; ++k) dst[m][k] = *(const PG8_LAS bf16x8*)(lds + PG8_SA(b, h) + aoff + m * 2048 + k * 1024); } while (0)
; #define PG8_LDB(dst, b, h) do { _Pragma("unroll") for (int n = 0; n < 2; ++n) _Pragma("unroll") for (int k = 0; k < 2; ++k) dst[n][k] = *(const PG8_LAS bf16x8*)(lds + PG8_SB(b, h) + boff + n * 2048 + k * 1024); } while (0)
; #define PG8_MMA(ai, bj, At, Bt) do { __builtin_amdgcn_s_setprio(1); _Pragma("unroll") for (int m = 0; m < 4; ++m) _Pragma("unroll") for (int n = 0; n < 2; ++n) _Pragma("unroll") for (int k = 0; k < 2; ++k) \
;         acc[ai][bj][m][n] = __builtin_amdgcn_mfma_f32_16x16x32_bf16(Bt[n][k], At[m][k], acc[ai][bj][m][n], 0, 0, 0); __builtin_amdgcn_s_setprio(0); } while (0)
; #define PG8_WAIT_V(n) asm volatile("s_waitcnt vmcnt(" #n ")" ::: "memory")
; #define PG8_WAIT_L(n) asm volatile("s_waitcnt lgkmcnt(" #n ")" ::: "memory")
; template <class Epi, class Sched, bool ALIGN_EPI = false, bool SP2 = false>
; __device__ __forceinline__ void gemm_phase(PG8_LAS unsigned char* lds, const Gemm g, const Sched& S, const Epi& E) {
;     ...
;             const bool last = (t == nt - 2);
;             const char* a1 = cA + (size_t)(t + 1) * kstep;
;             const char* a2 = last ? nA : cA + (size_t)(t + 2) * kstep; const char* b2 = last ? nB : cB + (size_t)(t + 2) * kstep;
;             const char* a3 = a2 + kstep; const char* b3 = b2 + kstep;
;             if (last && has_next) S.a_ready(nxt);
;             if constexpr (SP2) {
;             PG8_LDB(B0, 0, 0); PG8_LDB(B1, 0, 1); PG8_SCHED; PG8_LDA(At, 0, 0); PG8_STAGE(PG8_SA(1, 1), a1 + hstep, voffA);
;             PG8_WAIT_V(8); PG8_WAIT_L(0); PG8_BAR; PG8_MMA(0, 0, At, B0); PG8_MMA(0, 1, At, B1); PG8_BAR; PG8_SCHED;
;             PG8_LDA(At, 0, 1); PG8_STAGE(PG8_SB(0, 0), b2, voffB); PG8_STAGE(PG8_SB(0, 1), b2 + hstep, voffB); PG8_STAGE(PG8_SA(0, 0), a2, voffA);
;             PG8_WAIT_V(8); PG8_WAIT_L(0); PG8_BAR; PG8_MMA(1, 0, At, B0); PG8_MMA(1, 1, At, B1); PG8_BAR; PG8_SCHED;
.Ldn_peel:
	ds_read_b128 v[128:131], v254
	ds_read_b128 v[132:135], v254 offset:1024
	ds_read_b128 v[136:139], v254 offset:2048
	ds_read_b128 v[140:143], v254 offset:3072
	ds_read_b128 v[174:177], v254 offset:16384
	ds_read_b128 v[184:187], v254 offset:17408
	ds_read_b128 v[188:191], v254 offset:18432
	ds_read_b128 v[210:213], v254 offset:19456
	s_add_u32 s2, s0, 0x100
	s_addc_u32 s3, s1, 0
	s_cmp_eq_u32 s13, 40
	s_cselect_b32 s7, s27, s3
	s_cselect_b32 s6, s26, s2
	s_cselect_b32 s5, s37, s11
	s_cselect_b32 s4, s36, s10
	s_add_i32 m0, s29, 0xc000
	ds_read_b128 v[214:217], v181
	ds_read_b128 v[218:221], v181 offset:1024
	ds_read_b128 v[222:225], v181 offset:2048
	ds_read_b128 v[226:229], v181 offset:3072
	ds_read_b128 v[230:233], v181 offset:4096
	ds_read_b128 v[234:237], v181 offset:5120
	ds_read_b128 v[238:241], v181 offset:6144
	ds_read_b128 v[242:245], v181 offset:7168
	global_load_lds_dwordx4 v170, s[0:1]
	s_add_i32 m0, s29, 0xe000
	s_nop 0
	global_load_lds_dwordx4 v172, s[0:1]
	s_waitcnt vmcnt(8)
	s_waitcnt lgkmcnt(0)
	s_barrier
	s_setprio 1
	v_mfma_f32_16x16x32_bf16 v[124:127], v[128:131], v[214:217], 0
	v_mfma_f32_16x16x32_bf16 v[124:127], v[132:135], v[218:221], v[124:127]
	v_mfma_f32_16x16x32_bf16 v[120:123], v[136:139], v[214:217], 0
	v_mfma_f32_16x16x32_bf16 v[120:123], v[140:143], v[218:221], v[120:123]
	v_mfma_f32_16x16x32_bf16 v[108:111], v[128:131], v[222:225], 0
	v_mfma_f32_16x16x32_bf16 v[108:111], v[132:135], v[226:229], v[108:111]
	v_mfma_f32_16x16x32_bf16 v[104:107], v[136:139], v[222:225], 0
	v_mfma_f32_16x16x32_bf16 v[104:107], v[140:143], v[226:229], v[104:107]
	v_mfma_f32_16x16x32_bf16 v[92:95], v[128:131], v[230:233], 0
	v_mfma_f32_16x16x32_bf16 v[92:95], v[132:135], v[234:237], v[92:95]
	v_mfma_f32_16x16x32_bf16 v[88:91], v[136:139], v[230:233], 0
	v_mfma_f32_16x16x32_bf16 v[88:91], v[140:143], v[234:237], v[88:91]
	v_mfma_f32_16x16x32_bf16 v[76:79], v[128:131], v[238:241], 0
	v_mfma_f32_16x16x32_bf16 v[76:79], v[132:135], v[242:245], v[76:79]
	v_mfma_f32_16x16x32_bf16 v[72:75], v[136:139], v[238:241], 0
	v_mfma_f32_16x16x32_bf16 v[72:75], v[140:143], v[242:245], v[72:75]
	v_mfma_f32_16x16x32_bf16 v[116:119], v[174:177], v[214:217], 0
	v_mfma_f32_16x16x32_bf16 v[116:119], v[184:187], v[218:221], v[116:119]
	v_mfma_f32_16x16x32_bf16 v[112:115], v[188:191], v[214:217], 0
	v_mfma_f32_16x16x32_bf16 v[112:115], v[210:213], v[218:221], v[112:115]
	v_mfma_f32_16x16x32_bf16 v[100:103], v[174:177], v[222:225], 0
	v_mfma_f32_16x16x32_bf16 v[100:103], v[184:187], v[226:229], v[100:103]
	v_mfma_f32_16x16x32_bf16 v[96:99], v[188:191], v[222:225], 0
	v_mfma_f32_16x16x32_bf16 v[96:99], v[210:213], v[226:229], v[96:99]
	v_mfma_f32_16x16x32_bf16 v[84:87], v[174:177], v[230:233], 0
	v_mfma_f32_16x16x32_bf16 v[84:87], v[184:187], v[234:237], v[84:87]
	v_mfma_f32_16x16x32_bf16 v[80:83], v[188:191], v[230:233], 0
	v_mfma_f32_16x16x32_bf16 v[80:83], v[210:213], v[234:237], v[80:83]
	v_mfma_f32_16x16x32_bf16 v[68:71], v[174:177], v[238:241], 0
	v_mfma_f32_16x16x32_bf16 v[68:71], v[184:187], v[242:245], v[68:71]
	v_mfma_f32_16x16x32_bf16 v[64:67], v[188:191], v[238:241], 0
	v_mfma_f32_16x16x32_bf16 v[64:67], v[210:213], v[242:245], v[64:67]
	s_setprio 0
	s_barrier
	s_mov_b32 m0, s35
	s_add_u32 s0, s4, 0xb0000
	s_addc_u32 s1, s5, 0
	ds_read_b128 v[214:217], v181 offset:16384
	ds_read_b128 v[218:221], v181 offset:17408
	ds_read_b128 v[222:225], v181 offset:18432
	ds_read_b128 v[226:229], v181 offset:19456
	ds_read_b128 v[230:233], v181 offset:20480
	ds_read_b128 v[234:237], v181 offset:21504
	ds_read_b128 v[238:241], v181 offset:22528
	ds_read_b128 v[242:245], v181 offset:23552
	global_load_lds_dwordx4 v166, s[4:5]
	s_mov_b32 m0, s38
	s_nop 0
	global_load_lds_dwordx4 v162, s[4:5]
	s_mov_b32 m0, s39
	s_nop 0
	global_load_lds_dwordx4 v166, s[0:1]
	s_mov_b32 m0, s40
	s_nop 0
	global_load_lds_dwordx4 v162, s[0:1]
	s_mov_b32 m0, s29
	s_nop 0
	global_load_lds_dwordx4 v168, s[6:7]
	s_mov_b32 m0, s41
	s_nop 0
	global_load_lds_dwordx4 v164, s[6:7]
	s_waitcnt vmcnt(8)
	s_waitcnt lgkmcnt(0)
	s_barrier
	s_setprio 1
	v_mfma_f32_16x16x32_bf16 v[60:63], v[128:131], v[214:217], 0
	v_mfma_f32_16x16x32_bf16 v[60:63], v[132:135], v[218:221], v[60:63]
	v_mfma_f32_16x16x32_bf16 v[56:59], v[136:139], v[214:217], 0
	v_mfma_f32_16x16x32_bf16 v[56:59], v[140:143], v[218:221], v[56:59]
	v_mfma_f32_16x16x32_bf16 v[44:47], v[128:131], v[222:225], 0
	v_mfma_f32_16x16x32_bf16 v[44:47], v[132:135], v[226:229], v[44:47]
	v_mfma_f32_16x16x32_bf16 v[40:43], v[136:139], v[222:225], 0
	v_mfma_f32_16x16x32_bf16 v[40:43], v[140:143], v[226:229], v[40:43]
	v_mfma_f32_16x16x32_bf16 v[28:31], v[128:131], v[230:233], 0
	v_mfma_f32_16x16x32_bf16 v[28:31], v[132:135], v[234:237], v[28:31]
	v_mfma_f32_16x16x32_bf16 v[24:27], v[136:139], v[230:233], 0
	v_mfma_f32_16x16x32_bf16 v[24:27], v[140:143], v[234:237], v[24:27]
	v_mfma_f32_16x16x32_bf16 v[12:15], v[128:131], v[238:241], 0
	v_mfma_f32_16x16x32_bf16 v[12:15], v[132:135], v[242:245], v[12:15]
	v_mfma_f32_16x16x32_bf16 v[8:11], v[136:139], v[238:241], 0
	v_mfma_f32_16x16x32_bf16 v[8:11], v[140:143], v[242:245], v[8:11]
	v_mfma_f32_16x16x32_bf16 v[52:55], v[174:177], v[214:217], 0
	v_mfma_f32_16x16x32_bf16 v[52:55], v[184:187], v[218:221], v[52:55]
	v_mfma_f32_16x16x32_bf16 v[48:51], v[188:191], v[214:217], 0
	v_mfma_f32_16x16x32_bf16 v[48:51], v[210:213], v[218:221], v[48:51]
	v_mfma_f32_16x16x32_bf16 v[36:39], v[174:177], v[222:225], 0
	v_mfma_f32_16x16x32_bf16 v[36:39], v[184:187], v[226:229], v[36:39]
	v_mfma_f32_16x16x32_bf16 v[32:35], v[188:191], v[222:225], 0
	v_mfma_f32_16x16x32_bf16 v[32:35], v[210:213], v[226:229], v[32:35]
	v_mfma_f32_16x16x32_bf16 v[20:23], v[174:177], v[230:233], 0
	v_mfma_f32_16x16x32_bf16 v[20:23], v[184:187], v[234:237], v[20:23]
	v_mfma_f32_16x16x32_bf16 v[16:19], v[188:191], v[230:233], 0
	v_mfma_f32_16x16x32_bf16 v[16:19], v[210:213], v[234:237], v[16:19]
	v_mfma_f32_16x16x32_bf16 v[4:7], v[174:177], v[238:241], 0
	v_mfma_f32_16x16x32_bf16 v[4:7], v[184:187], v[242:245], v[4:7]
	v_mfma_f32_16x16x32_bf16 v[0:3], v[188:191], v[238:241], 0
	v_mfma_f32_16x16x32_bf16 v[0:3], v[210:213], v[242:245], v[0:3]
	s_setprio 0
	s_barrier
; #define PG8_STAGE(bufoff, gbase, voff) do { _Pragma("unroll") for (int _i = 0; _i < 2; ++_i) \
;         __builtin_amdgcn_global_load_lds((const unsigned*)((const char*)(gbase) + (voff)[_i]), (PG8_LAS unsigned*)(lds + (bufoff) + ldsw + _i * 8192), 16, 0, 0); } while (0)
; #define PG8_LDA(dst, b, h) do { _Pragma("unroll") for (int m = 0; m < 4; ++m) _Pragma("unroll") for (int k = 0; k < 2; ++k) dst[m][k] = *(const PG8_LAS bf16x8*)(lds + PG8_SA(b, h) + aoff + m * 2048 + k * 1024); } while (0)
; #define PG8_LDB(dst, b, h) do { _Pragma("unroll") for (int n = 0; n < 2; ++n) _Pragma("unroll") for (int k = 0; k < 2; ++k) dst[n][k] = *(const PG8_LAS bf16x8*)(lds + PG8_SB(b, h) + boff + n * 2048 + k * 1024); } while (0)
; #define PG8_MMA(ai, bj, At, Bt) do { __builtin_amdgcn_s_setprio(1); _Pragma("unroll") for (int m = 0; m < 4; ++m) _Pragma("unroll") for (int n = 0; n < 2; ++n) _Pragma("unroll") for (int k = 0; k < 2; ++k) \
;         acc[ai][bj][m][n] = __builtin_amdgcn_mfma_f32_16x16x32_bf16(Bt[n][k], At[m][k], acc[ai][bj][m][n], 0, 0, 0); __builtin_amdgcn_s_setprio(0); } while (0)
; #define PG8_WAIT_V(n) asm volatile("s_waitcnt vmcnt(" #n ")" ::: "memory")
; #define PG8_WAIT_L(n) asm volatile("s_waitcnt lgkmcnt(" #n ")" ::: "memory")
; #define PG8_BAR __builtin_amdgcn_s_barrier()
; #define PG8_SCHED __builtin_amdgcn_sched_barrier(0)
; template <class Epi, class Sched, bool ALIGN_EPI = false, bool SP2 = false>
; __device__ __forceinline__ void gemm_phase(PG8_LAS unsigned char* lds, const Gemm g, const Sched& S, const Epi& E) {
;     ...
;             PG8_LDB(B0, 1, 0); PG8_LDB(B1, 1, 1); PG8_SCHED; PG8_LDA(At, 1, 0); PG8_STAGE(PG8_SA(0, 1), a2 + hstep, voffA);
;             PG8_WAIT_V(8); PG8_WAIT_L(0); PG8_BAR; PG8_MMA(0, 0, At, B0); PG8_MMA(0, 1, At, B1); PG8_BAR; PG8_SCHED;
;             PG8_LDA(At, 1, 1); PG8_STAGE(PG8_SB(1, 0), b3, voffB); PG8_STAGE(PG8_SB(1, 1), b3 + hstep, voffB); PG8_STAGE(PG8_SA(1, 0), a3, voffA);
;             PG8_WAIT_V(8); PG8_WAIT_L(0); PG8_BAR; PG8_MMA(1, 0, At, B0); PG8_MMA(1, 1, At, B1); PG8_BAR; PG8_SCHED;
	ds_read_b128 v[128:131], v254 offset:32768
	ds_read_b128 v[132:135], v254 offset:33792
	ds_read_b128 v[136:139], v254 offset:34816
	ds_read_b128 v[140:143], v254 offset:35840
	ds_read_b128 v[174:177], v254 offset:49152
	ds_read_b128 v[184:187], v254 offset:50176
	ds_read_b128 v[188:191], v254 offset:51200
	ds_read_b128 v[210:213], v254 offset:52224
	s_add_u32 s0, s6, 0xb0000
	s_addc_u32 s1, s7, 0
	s_mov_b32 m0, s42
	ds_read_b128 v[214:217], v181 offset:32768
	ds_read_b128 v[218:221], v181 offset:33792
	ds_read_b128 v[222:225], v181 offset:34816
	ds_read_b128 v[226:229], v181 offset:35840
	ds_read_b128 v[230:233], v181 offset:36864
	ds_read_b128 v[234:237], v181 offset:37888
	ds_read_b128 v[238:241], v181 offset:38912
	ds_read_b128 v[242:245], v181 offset:39936
	global_load_lds_dwordx4 v168, s[0:1]
	s_mov_b32 m0, s43
	s_nop 0
	global_load_lds_dwordx4 v164, s[0:1]
	s_waitcnt vmcnt(8)
	s_waitcnt lgkmcnt(0)
	s_barrier
	s_setprio 1
	v_mfma_f32_16x16x32_bf16 v[124:127], v[128:131], v[214:217], v[124:127]
	v_mfma_f32_16x16x32_bf16 v[124:127], v[132:135], v[218:221], v[124:127]
	v_mfma_f32_16x16x32_bf16 v[120:123], v[136:139], v[214:217], v[120:123]
	v_mfma_f32_16x16x32_bf16 v[120:123], v[140:143], v[218:221], v[120:123]
	v_mfma_f32_16x16x32_bf16 v[108:111], v[128:131], v[222:225], v[108:111]
	v_mfma_f32_16x16x32_bf16 v[108:111], v[132:135], v[226:229], v[108:111]
	v_mfma_f32_16x16x32_bf16 v[104:107], v[136:139], v[222:225], v[104:107]
	v_mfma_f32_16x16x32_bf16 v[104:107], v[140:143], v[226:229], v[104:107]
	v_mfma_f32_16x16x32_bf16 v[92:95], v[128:131], v[230:233], v[92:95]
	v_mfma_f32_16x16x32_bf16 v[92:95], v[132:135], v[234:237], v[92:95]
	v_mfma_f32_16x16x32_bf16 v[88:91], v[136:139], v[230:233], v[88:91]
	v_mfma_f32_16x16x32_bf16 v[88:91], v[140:143], v[234:237], v[88:91]
	v_mfma_f32_16x16x32_bf16 v[76:79], v[128:131], v[238:241], v[76:79]
	v_mfma_f32_16x16x32_bf16 v[76:79], v[132:135], v[242:245], v[76:79]
	v_mfma_f32_16x16x32_bf16 v[72:75], v[136:139], v[238:241], v[72:75]
	v_mfma_f32_16x16x32_bf16 v[72:75], v[140:143], v[242:245], v[72:75]
	v_mfma_f32_16x16x32_bf16 v[116:119], v[174:177], v[214:217], v[116:119]
	v_mfma_f32_16x16x32_bf16 v[116:119], v[184:187], v[218:221], v[116:119]
	v_mfma_f32_16x16x32_bf16 v[112:115], v[188:191], v[214:217], v[112:115]
	v_mfma_f32_16x16x32_bf16 v[112:115], v[210:213], v[218:221], v[112:115]
	v_mfma_f32_16x16x32_bf16 v[100:103], v[174:177], v[222:225], v[100:103]
	v_mfma_f32_16x16x32_bf16 v[100:103], v[184:187], v[226:229], v[100:103]
	v_mfma_f32_16x16x32_bf16 v[96:99], v[188:191], v[222:225], v[96:99]
	v_mfma_f32_16x16x32_bf16 v[96:99], v[210:213], v[226:229], v[96:99]
	v_mfma_f32_16x16x32_bf16 v[84:87], v[174:177], v[230:233], v[84:87]
	v_mfma_f32_16x16x32_bf16 v[84:87], v[184:187], v[234:237], v[84:87]
	v_mfma_f32_16x16x32_bf16 v[80:83], v[188:191], v[230:233], v[80:83]
	v_mfma_f32_16x16x32_bf16 v[80:83], v[210:213], v[234:237], v[80:83]
	v_mfma_f32_16x16x32_bf16 v[68:71], v[174:177], v[238:241], v[68:71]
	v_mfma_f32_16x16x32_bf16 v[68:71], v[184:187], v[242:245], v[68:71]
	v_mfma_f32_16x16x32_bf16 v[64:67], v[188:191], v[238:241], v[64:67]
	v_mfma_f32_16x16x32_bf16 v[64:67], v[210:213], v[242:245], v[64:67]
	s_setprio 0
	s_barrier
	s_mov_b32 m0, s47
	s_add_u32 s0, s4, 0xb0080
	s_addc_u32 s1, s5, 0
	ds_read_b128 v[214:217], v181 offset:49152
	ds_read_b128 v[218:221], v181 offset:50176
	ds_read_b128 v[222:225], v181 offset:51200
	ds_read_b128 v[226:229], v181 offset:52224
	ds_read_b128 v[230:233], v181 offset:53248
	ds_read_b128 v[234:237], v181 offset:54272
	ds_read_b128 v[238:241], v181 offset:55296
	ds_read_b128 v[242:245], v181 offset:56320
	s_add_u32 s98, s4, 0x80
	s_addc_u32 s99, s5, 0
	global_load_lds_dwordx4 v166, s[98:99]
	s_mov_b32 m0, s48
	s_nop 0
	global_load_lds_dwordx4 v162, s[98:99]
	s_mov_b32 m0, s51
	s_nop 0
	global_load_lds_dwordx4 v166, s[0:1]
	s_mov_b32 m0, s52
	s_nop 0
	global_load_lds_dwordx4 v162, s[0:1]
	s_mov_b32 m0, s49
	s_nop 0
	s_add_u32 s100, s6, 0x80
	s_addc_u32 s101, s7, 0
	global_load_lds_dwordx4 v168, s[100:101]
	s_mov_b32 m0, s50
	s_nop 0
	global_load_lds_dwordx4 v164, s[100:101]
	s_waitcnt vmcnt(8)
	s_waitcnt lgkmcnt(0)
	s_barrier
	s_setprio 1
	v_mfma_f32_16x16x32_bf16 v[60:63], v[128:131], v[214:217], v[60:63]
	v_mfma_f32_16x16x32_bf16 v[60:63], v[132:135], v[218:221], v[60:63]
	v_mfma_f32_16x16x32_bf16 v[56:59], v[136:139], v[214:217], v[56:59]
	v_mfma_f32_16x16x32_bf16 v[56:59], v[140:143], v[218:221], v[56:59]
	v_mfma_f32_16x16x32_bf16 v[44:47], v[128:131], v[222:225], v[44:47]
	v_mfma_f32_16x16x32_bf16 v[44:47], v[132:135], v[226:229], v[44:47]
	v_mfma_f32_16x16x32_bf16 v[40:43], v[136:139], v[222:225], v[40:43]
	v_mfma_f32_16x16x32_bf16 v[40:43], v[140:143], v[226:229], v[40:43]
	v_mfma_f32_16x16x32_bf16 v[28:31], v[128:131], v[230:233], v[28:31]
	v_mfma_f32_16x16x32_bf16 v[28:31], v[132:135], v[234:237], v[28:31]
	v_mfma_f32_16x16x32_bf16 v[24:27], v[136:139], v[230:233], v[24:27]
	v_mfma_f32_16x16x32_bf16 v[24:27], v[140:143], v[234:237], v[24:27]
	v_mfma_f32_16x16x32_bf16 v[12:15], v[128:131], v[238:241], v[12:15]
	v_mfma_f32_16x16x32_bf16 v[12:15], v[132:135], v[242:245], v[12:15]
	v_mfma_f32_16x16x32_bf16 v[8:11], v[136:139], v[238:241], v[8:11]
	v_mfma_f32_16x16x32_bf16 v[8:11], v[140:143], v[242:245], v[8:11]
	v_mfma_f32_16x16x32_bf16 v[52:55], v[174:177], v[214:217], v[52:55]
	v_mfma_f32_16x16x32_bf16 v[52:55], v[184:187], v[218:221], v[52:55]
	v_mfma_f32_16x16x32_bf16 v[48:51], v[188:191], v[214:217], v[48:51]
	v_mfma_f32_16x16x32_bf16 v[48:51], v[210:213], v[218:221], v[48:51]
	v_mfma_f32_16x16x32_bf16 v[36:39], v[174:177], v[222:225], v[36:39]
	v_mfma_f32_16x16x32_bf16 v[36:39], v[184:187], v[226:229], v[36:39]
	v_mfma_f32_16x16x32_bf16 v[32:35], v[188:191], v[222:225], v[32:35]
	v_mfma_f32_16x16x32_bf16 v[32:35], v[210:213], v[226:229], v[32:35]
	v_mfma_f32_16x16x32_bf16 v[20:23], v[174:177], v[230:233], v[20:23]
	v_mfma_f32_16x16x32_bf16 v[20:23], v[184:187], v[234:237], v[20:23]
	v_mfma_f32_16x16x32_bf16 v[16:19], v[188:191], v[230:233], v[16:19]
	v_mfma_f32_16x16x32_bf16 v[16:19], v[210:213], v[234:237], v[16:19]
	v_mfma_f32_16x16x32_bf16 v[4:7], v[174:177], v[238:241], v[4:7]
	v_mfma_f32_16x16x32_bf16 v[4:7], v[184:187], v[242:245], v[4:7]
	v_mfma_f32_16x16x32_bf16 v[0:3], v[188:191], v[238:241], v[0:3]
	v_mfma_f32_16x16x32_bf16 v[0:3], v[210:213], v[242:245], v[0:3]
	s_setprio 0
	s_barrier
	s_add_i32 s13, s13, 2
	s_add_u32 s10, s10, 0x100
	s_addc_u32 s11, s11, 0
	s_cmp_gt_u32 s13, 41
	s_mov_b64 s[0:1], s[2:3]
; #define PG8_STAGE(bufoff, gbase, voff) do { _Pragma("unroll") for (int _i = 0; _i < 2; ++_i) \
;         __builtin_amdgcn_global_load_lds((const unsigned*)((const char*)(gbase) + (voff)[_i]), (PG8_LAS unsigned*)(lds + (bufoff) + ldsw + _i * 8192), 16, 0, 0); } while (0)
; #define PG8_LDA(dst, b, h) do { _Pragma("unroll") for (int m = 0; m < 4; ++m) _Pragma("unroll") for (int k = 0; k < 2; ++k) dst[m][k] = *(const PG8_LAS bf16x8*)(lds + PG8_SA(b, h) + aoff + m * 2048 + k * 1024); } while (0)
; #define PG8_LDB(dst, b, h) do { _Pragma("unroll") for (int n = 0; n < 2; ++n) _Pragma("unroll") for (int k = 0; k < 2; ++k) dst[n][k] = *(const PG8_LAS bf16x8*)(lds + PG8_SB(b, h) + boff + n * 2048 + k * 1024); } while (0)
; #define PG8_MMA(ai, bj, At, Bt) do { __builtin_amdgcn_s_setprio(1); _Pragma("unroll") for (int m = 0; m < 4; ++m) _Pragma("unroll") for (int n = 0; n < 2; ++n) _Pragma("unroll") for (int k = 0; k < 2; ++k) \
;         acc[ai][bj][m][n] = __builtin_amdgcn_mfma_f32_16x16x32_bf16(Bt[n][k], At[m][k], acc[ai][bj][m][n], 0, 0, 0); __builtin_amdgcn_s_setprio(0); } while (0)
; #define PG8_WAIT_V(n) asm volatile("s_waitcnt vmcnt(" #n ")" ::: "memory")
; #define PG8_WAIT_L(n) asm volatile("s_waitcnt lgkmcnt(" #n ")" ::: "memory")
; template <class Epi, class Sched, bool ALIGN_EPI = false, bool SP2 = false>
; __device__ __forceinline__ void gemm_phase(PG8_LAS unsigned char* lds, const Gemm g, const Sched& S, const Epi& E) {
;     ...
;             const bool last = (t == nt - 2);
;             const char* a1 = cA + (size_t)(t + 1) * kstep;
;             const char* a2 = last ? nA : cA + (size_t)(t + 2) * kstep; const char* b2 = last ? nB : cB + (size_t)(t + 2) * kstep;
;             const char* a3 = a2 + kstep; const char* b3 = b2 + kstep;
;             if (last && has_next) S.a_ready(nxt);
;             if constexpr (SP2) {
;             PG8_LDB(B0, 0, 0); PG8_LDB(B1, 0, 1); PG8_SCHED; PG8_LDA(At, 0, 0); PG8_STAGE(PG8_SA(1, 1), a1 + hstep, voffA);
;             PG8_WAIT_V(8); PG8_WAIT_L(0); PG8_BAR; PG8_MMA(0, 0, At, B0); PG8_MMA(0, 1, At, B1); PG8_BAR; PG8_SCHED;
;             PG8_LDA(At, 0, 1); PG8_STAGE(PG8_SB(0, 0), b2, voffB); PG8_STAGE(PG8_SB(0, 1), b2 + hstep, voffB); PG8_STAGE(PG8_SA(0, 0), a2, voffA);
;             PG8_WAIT_V(8); PG8_WAIT_L(0); PG8_BAR; PG8_MMA(1, 0, At, B0); PG8_MMA(1, 1, At, B1); PG8_BAR; PG8_SCHED;
.LBB0_545:
	ds_read_b128 v[128:131], v254
	ds_read_b128 v[132:135], v254 offset:1024
	ds_read_b128 v[136:139], v254 offset:2048
	ds_read_b128 v[140:143], v254 offset:3072
	ds_read_b128 v[174:177], v254 offset:16384
	ds_read_b128 v[184:187], v254 offset:17408
	ds_read_b128 v[188:191], v254 offset:18432
	ds_read_b128 v[210:213], v254 offset:19456
	s_add_u32 s2, s0, 0x100
	s_addc_u32 s3, s1, 0
	s_cmp_eq_u32 s13, 40
	s_cselect_b32 s7, s27, s3
	s_cselect_b32 s6, s26, s2
	s_cselect_b32 s5, s37, s11
	s_cselect_b32 s4, s36, s10
	s_add_i32 m0, s29, 0xc000
	ds_read_b128 v[214:217], v181
	ds_read_b128 v[218:221], v181 offset:1024
	ds_read_b128 v[222:225], v181 offset:2048
	ds_read_b128 v[226:229], v181 offset:3072
	ds_read_b128 v[230:233], v181 offset:4096
	ds_read_b128 v[234:237], v181 offset:5120
	ds_read_b128 v[238:241], v181 offset:6144
	ds_read_b128 v[242:245], v181 offset:7168
	global_load_lds_dwordx4 v170, s[0:1]
	s_add_i32 m0, s29, 0xe000
	s_nop 0
	global_load_lds_dwordx4 v172, s[0:1]
	s_waitcnt vmcnt(8)
	s_waitcnt lgkmcnt(0)
	s_barrier
	s_setprio 1
	v_mfma_f32_16x16x32_bf16 v[124:127], v[128:131], v[214:217], v[124:127]
	v_mfma_f32_16x16x32_bf16 v[124:127], v[132:135], v[218:221], v[124:127]
	v_mfma_f32_16x16x32_bf16 v[120:123], v[136:139], v[214:217], v[120:123]
	v_mfma_f32_16x16x32_bf16 v[120:123], v[140:143], v[218:221], v[120:123]
	v_mfma_f32_16x16x32_bf16 v[108:111], v[128:131], v[222:225], v[108:111]
	v_mfma_f32_16x16x32_bf16 v[108:111], v[132:135], v[226:229], v[108:111]
	v_mfma_f32_16x16x32_bf16 v[104:107], v[136:139], v[222:225], v[104:107]
	v_mfma_f32_16x16x32_bf16 v[104:107], v[140:143], v[226:229], v[104:107]
	v_mfma_f32_16x16x32_bf16 v[92:95], v[128:131], v[230:233], v[92:95]
	v_mfma_f32_16x16x32_bf16 v[92:95], v[132:135], v[234:237], v[92:95]
	v_mfma_f32_16x16x32_bf16 v[88:91], v[136:139], v[230:233], v[88:91]
	v_mfma_f32_16x16x32_bf16 v[88:91], v[140:143], v[234:237], v[88:91]
	v_mfma_f32_16x16x32_bf16 v[76:79], v[128:131], v[238:241], v[76:79]
	v_mfma_f32_16x16x32_bf16 v[76:79], v[132:135], v[242:245], v[76:79]
	v_mfma_f32_16x16x32_bf16 v[72:75], v[136:139], v[238:241], v[72:75]
	v_mfma_f32_16x16x32_bf16 v[72:75], v[140:143], v[242:245], v[72:75]
	v_mfma_f32_16x16x32_bf16 v[116:119], v[174:177], v[214:217], v[116:119]
	v_mfma_f32_16x16x32_bf16 v[116:119], v[184:187], v[218:221], v[116:119]
	v_mfma_f32_16x16x32_bf16 v[112:115], v[188:191], v[214:217], v[112:115]
	v_mfma_f32_16x16x32_bf16 v[112:115], v[210:213], v[218:221], v[112:115]
	v_mfma_f32_16x16x32_bf16 v[100:103], v[174:177], v[222:225], v[100:103]
	v_mfma_f32_16x16x32_bf16 v[100:103], v[184:187], v[226:229], v[100:103]
	v_mfma_f32_16x16x32_bf16 v[96:99], v[188:191], v[222:225], v[96:99]
	v_mfma_f32_16x16x32_bf16 v[96:99], v[210:213], v[226:229], v[96:99]
	v_mfma_f32_16x16x32_bf16 v[84:87], v[174:177], v[230:233], v[84:87]
	v_mfma_f32_16x16x32_bf16 v[84:87], v[184:187], v[234:237], v[84:87]
	v_mfma_f32_16x16x32_bf16 v[80:83], v[188:191], v[230:233], v[80:83]
	v_mfma_f32_16x16x32_bf16 v[80:83], v[210:213], v[234:237], v[80:83]
	v_mfma_f32_16x16x32_bf16 v[68:71], v[174:177], v[238:241], v[68:71]
	v_mfma_f32_16x16x32_bf16 v[68:71], v[184:187], v[242:245], v[68:71]
	v_mfma_f32_16x16x32_bf16 v[64:67], v[188:191], v[238:241], v[64:67]
	v_mfma_f32_16x16x32_bf16 v[64:67], v[210:213], v[242:245], v[64:67]
	s_setprio 0
	s_barrier
	s_mov_b32 m0, s35
	s_add_u32 s0, s4, 0xb0000
	s_addc_u32 s1, s5, 0
	ds_read_b128 v[214:217], v181 offset:16384
	ds_read_b128 v[218:221], v181 offset:17408
	ds_read_b128 v[222:225], v181 offset:18432
	ds_read_b128 v[226:229], v181 offset:19456
	ds_read_b128 v[230:233], v181 offset:20480
	ds_read_b128 v[234:237], v181 offset:21504
	ds_read_b128 v[238:241], v181 offset:22528
	ds_read_b128 v[242:245], v181 offset:23552
	global_load_lds_dwordx4 v166, s[4:5]
	s_mov_b32 m0, s38
	s_nop 0
	global_load_lds_dwordx4 v162, s[4:5]
	s_mov_b32 m0, s39
	s_nop 0
	global_load_lds_dwordx4 v166, s[0:1]
	s_mov_b32 m0, s40
	s_nop 0
	global_load_lds_dwordx4 v162, s[0:1]
	s_mov_b32 m0, s29
	s_nop 0
	global_load_lds_dwordx4 v168, s[6:7]
	s_mov_b32 m0, s41
	s_nop 0
	global_load_lds_dwordx4 v164, s[6:7]
	s_waitcnt vmcnt(8)
	s_waitcnt lgkmcnt(0)
	s_barrier
	s_setprio 1
	v_mfma_f32_16x16x32_bf16 v[60:63], v[128:131], v[214:217], v[60:63]
	v_mfma_f32_16x16x32_bf16 v[60:63], v[132:135], v[218:221], v[60:63]
	v_mfma_f32_16x16x32_bf16 v[56:59], v[136:139], v[214:217], v[56:59]
	v_mfma_f32_16x16x32_bf16 v[56:59], v[140:143], v[218:221], v[56:59]
	v_mfma_f32_16x16x32_bf16 v[44:47], v[128:131], v[222:225], v[44:47]
	v_mfma_f32_16x16x32_bf16 v[44:47], v[132:135], v[226:229], v[44:47]
	v_mfma_f32_16x16x32_bf16 v[40:43], v[136:139], v[222:225], v[40:43]
	v_mfma_f32_16x16x32_bf16 v[40:43], v[140:143], v[226:229], v[40:43]
	v_mfma_f32_16x16x32_bf16 v[28:31], v[128:131], v[230:233], v[28:31]
	v_mfma_f32_16x16x32_bf16 v[28:31], v[132:135], v[234:237], v[28:31]
	v_mfma_f32_16x16x32_bf16 v[24:27], v[136:139], v[230:233], v[24:27]
	v_mfma_f32_16x16x32_bf16 v[24:27], v[140:143], v[234:237], v[24:27]
	v_mfma_f32_16x16x32_bf16 v[12:15], v[128:131], v[238:241], v[12:15]
	v_mfma_f32_16x16x32_bf16 v[12:15], v[132:135], v[242:245], v[12:15]
	v_mfma_f32_16x16x32_bf16 v[8:11], v[136:139], v[238:241], v[8:11]
	v_mfma_f32_16x16x32_bf16 v[8:11], v[140:143], v[242:245], v[8:11]
	v_mfma_f32_16x16x32_bf16 v[52:55], v[174:177], v[214:217], v[52:55]
	v_mfma_f32_16x16x32_bf16 v[52:55], v[184:187], v[218:221], v[52:55]
	v_mfma_f32_16x16x32_bf16 v[48:51], v[188:191], v[214:217], v[48:51]
	v_mfma_f32_16x16x32_bf16 v[48:51], v[210:213], v[218:221], v[48:51]
	v_mfma_f32_16x16x32_bf16 v[36:39], v[174:177], v[222:225], v[36:39]
	v_mfma_f32_16x16x32_bf16 v[36:39], v[184:187], v[226:229], v[36:39]
	v_mfma_f32_16x16x32_bf16 v[32:35], v[188:191], v[222:225], v[32:35]
	v_mfma_f32_16x16x32_bf16 v[32:35], v[210:213], v[226:229], v[32:35]
	v_mfma_f32_16x16x32_bf16 v[20:23], v[174:177], v[230:233], v[20:23]
	v_mfma_f32_16x16x32_bf16 v[20:23], v[184:187], v[234:237], v[20:23]
	v_mfma_f32_16x16x32_bf16 v[16:19], v[188:191], v[230:233], v[16:19]
	v_mfma_f32_16x16x32_bf16 v[16:19], v[210:213], v[234:237], v[16:19]
	v_mfma_f32_16x16x32_bf16 v[4:7], v[174:177], v[238:241], v[4:7]
	v_mfma_f32_16x16x32_bf16 v[4:7], v[184:187], v[242:245], v[4:7]
	v_mfma_f32_16x16x32_bf16 v[0:3], v[188:191], v[238:241], v[0:3]
	v_mfma_f32_16x16x32_bf16 v[0:3], v[210:213], v[242:245], v[0:3]
	s_setprio 0
	s_barrier
; #define PG8_STAGE(bufoff, gbase, voff) do { _Pragma("unroll") for (int _i = 0; _i < 2; ++_i) \
;         __builtin_amdgcn_global_load_lds((const unsigned*)((const char*)(gbase) + (voff)[_i]), (PG8_LAS unsigned*)(lds + (bufoff) + ldsw + _i * 8192), 16, 0, 0); } while (0)
; #define PG8_LDA(dst, b, h) do { _Pragma("unroll") for (int m = 0; m < 4; ++m) _Pragma("unroll") for (int k = 0; k < 2; ++k) dst[m][k] = *(const PG8_LAS bf16x8*)(lds + PG8_SA(b, h) + aoff + m * 2048 + k * 1024); } while (0)
; #define PG8_LDB(dst, b, h) do { _Pragma("unroll") for (int n = 0; n < 2; ++n) _Pragma("unroll") for (int k = 0; k < 2; ++k) dst[n][k] = *(const PG8_LAS bf16x8*)(lds + PG8_SB(b, h) + boff + n * 2048 + k * 1024); } while (0)
; #define PG8_MMA(ai, bj, At, Bt) do { __builtin_amdgcn_s_setprio(1); _Pragma("unroll") for (int m = 0; m < 4; ++m) _Pragma("unroll") for (int n = 0; n < 2; ++n) _Pragma("unroll") for (int k = 0; k < 2; ++k) \
;         acc[ai][bj][m][n] = __builtin_amdgcn_mfma_f32_16x16x32_bf16(Bt[n][k], At[m][k], acc[ai][bj][m][n], 0, 0, 0); __builtin_amdgcn_s_setprio(0); } while (0)
; #define PG8_WAIT_V(n) asm volatile("s_waitcnt vmcnt(" #n ")" ::: "memory")
; #define PG8_WAIT_L(n) asm volatile("s_waitcnt lgkmcnt(" #n ")" ::: "memory")
; #define PG8_BAR __builtin_amdgcn_s_barrier()
; #define PG8_SCHED __builtin_amdgcn_sched_barrier(0)
; template <class Epi, class Sched, bool ALIGN_EPI = false, bool SP2 = false>
; __device__ __forceinline__ void gemm_phase(PG8_LAS unsigned char* lds, const Gemm g, const Sched& S, const Epi& E) {
;     ...
;             PG8_LDB(B0, 1, 0); PG8_LDB(B1, 1, 1); PG8_SCHED; PG8_LDA(At, 1, 0); PG8_STAGE(PG8_SA(0, 1), a2 + hstep, voffA);
;             PG8_WAIT_V(8); PG8_WAIT_L(0); PG8_BAR; PG8_MMA(0, 0, At, B0); PG8_MMA(0, 1, At, B1); PG8_BAR; PG8_SCHED;
;             PG8_LDA(At, 1, 1); PG8_STAGE(PG8_SB(1, 0), b3, voffB); PG8_STAGE(PG8_SB(1, 1), b3 + hstep, voffB); PG8_STAGE(PG8_SA(1, 0), a3, voffA);
;             PG8_WAIT_V(8); PG8_WAIT_L(0); PG8_BAR; PG8_MMA(1, 0, At, B0); PG8_MMA(1, 1, At, B1); PG8_BAR; PG8_SCHED;
;     ...
;         if constexpr (ALIGN_EPI) { if (wr == 0) PG8_BAR; }
	ds_read_b128 v[128:131], v254 offset:32768
	ds_read_b128 v[132:135], v254 offset:33792
	ds_read_b128 v[136:139], v254 offset:34816
	ds_read_b128 v[140:143], v254 offset:35840
	ds_read_b128 v[174:177], v254 offset:49152
	ds_read_b128 v[184:187], v254 offset:50176
	ds_read_b128 v[188:191], v254 offset:51200
	ds_read_b128 v[210:213], v254 offset:52224
	s_add_u32 s0, s6, 0xb0000
	s_addc_u32 s1, s7, 0
	s_mov_b32 m0, s42
	ds_read_b128 v[214:217], v181 offset:32768
	ds_read_b128 v[218:221], v181 offset:33792
	ds_read_b128 v[222:225], v181 offset:34816
	ds_read_b128 v[226:229], v181 offset:35840
	ds_read_b128 v[230:233], v181 offset:36864
	ds_read_b128 v[234:237], v181 offset:37888
	ds_read_b128 v[238:241], v181 offset:38912
	ds_read_b128 v[242:245], v181 offset:39936
	global_load_lds_dwordx4 v168, s[0:1]
	s_mov_b32 m0, s43
	s_nop 0
	global_load_lds_dwordx4 v164, s[0:1]
	s_waitcnt vmcnt(8)
	s_waitcnt lgkmcnt(0)
	s_barrier
	s_setprio 1
	v_mfma_f32_16x16x32_bf16 v[124:127], v[128:131], v[214:217], v[124:127]
	v_mfma_f32_16x16x32_bf16 v[124:127], v[132:135], v[218:221], v[124:127]
	v_mfma_f32_16x16x32_bf16 v[120:123], v[136:139], v[214:217], v[120:123]
	v_mfma_f32_16x16x32_bf16 v[120:123], v[140:143], v[218:221], v[120:123]
	v_mfma_f32_16x16x32_bf16 v[108:111], v[128:131], v[222:225], v[108:111]
	v_mfma_f32_16x16x32_bf16 v[108:111], v[132:135], v[226:229], v[108:111]
	v_mfma_f32_16x16x32_bf16 v[104:107], v[136:139], v[222:225], v[104:107]
	v_mfma_f32_16x16x32_bf16 v[104:107], v[140:143], v[226:229], v[104:107]
	v_mfma_f32_16x16x32_bf16 v[92:95], v[128:131], v[230:233], v[92:95]
	v_mfma_f32_16x16x32_bf16 v[92:95], v[132:135], v[234:237], v[92:95]
	v_mfma_f32_16x16x32_bf16 v[88:91], v[136:139], v[230:233], v[88:91]
	v_mfma_f32_16x16x32_bf16 v[88:91], v[140:143], v[234:237], v[88:91]
	v_mfma_f32_16x16x32_bf16 v[76:79], v[128:131], v[238:241], v[76:79]
	v_mfma_f32_16x16x32_bf16 v[76:79], v[132:135], v[242:245], v[76:79]
	v_mfma_f32_16x16x32_bf16 v[72:75], v[136:139], v[238:241], v[72:75]
	v_mfma_f32_16x16x32_bf16 v[72:75], v[140:143], v[242:245], v[72:75]
	v_mfma_f32_16x16x32_bf16 v[116:119], v[174:177], v[214:217], v[116:119]
	v_mfma_f32_16x16x32_bf16 v[116:119], v[184:187], v[218:221], v[116:119]
	v_mfma_f32_16x16x32_bf16 v[112:115], v[188:191], v[214:217], v[112:115]
	v_mfma_f32_16x16x32_bf16 v[112:115], v[210:213], v[218:221], v[112:115]
	v_mfma_f32_16x16x32_bf16 v[100:103], v[174:177], v[222:225], v[100:103]
	v_mfma_f32_16x16x32_bf16 v[100:103], v[184:187], v[226:229], v[100:103]
	v_mfma_f32_16x16x32_bf16 v[96:99], v[188:191], v[222:225], v[96:99]
	v_mfma_f32_16x16x32_bf16 v[96:99], v[210:213], v[226:229], v[96:99]
	v_mfma_f32_16x16x32_bf16 v[84:87], v[174:177], v[230:233], v[84:87]
	v_mfma_f32_16x16x32_bf16 v[84:87], v[184:187], v[234:237], v[84:87]
	v_mfma_f32_16x16x32_bf16 v[80:83], v[188:191], v[230:233], v[80:83]
	v_mfma_f32_16x16x32_bf16 v[80:83], v[210:213], v[234:237], v[80:83]
	v_mfma_f32_16x16x32_bf16 v[68:71], v[174:177], v[238:241], v[68:71]
	v_mfma_f32_16x16x32_bf16 v[68:71], v[184:187], v[242:245], v[68:71]
	v_mfma_f32_16x16x32_bf16 v[64:67], v[188:191], v[238:241], v[64:67]
	v_mfma_f32_16x16x32_bf16 v[64:67], v[210:213], v[242:245], v[64:67]
	s_setprio 0
	s_barrier
	s_mov_b32 m0, s47
	s_add_u32 s0, s4, 0xb0080
	s_addc_u32 s1, s5, 0
	ds_read_b128 v[214:217], v181 offset:49152
	ds_read_b128 v[218:221], v181 offset:50176
	ds_read_b128 v[222:225], v181 offset:51200
	ds_read_b128 v[226:229], v181 offset:52224
	ds_read_b128 v[230:233], v181 offset:53248
	ds_read_b128 v[234:237], v181 offset:54272
	ds_read_b128 v[238:241], v181 offset:55296
	ds_read_b128 v[242:245], v181 offset:56320
	s_add_u32 s98, s4, 0x80
	s_addc_u32 s99, s5, 0
	global_load_lds_dwordx4 v166, s[98:99]
	s_mov_b32 m0, s48
	s_nop 0
	global_load_lds_dwordx4 v162, s[98:99]
	s_mov_b32 m0, s51
	s_nop 0
	global_load_lds_dwordx4 v166, s[0:1]
	s_mov_b32 m0, s52
	s_nop 0
	global_load_lds_dwordx4 v162, s[0:1]
	s_mov_b32 m0, s49
	s_nop 0
	s_add_u32 s100, s6, 0x80
	s_addc_u32 s101, s7, 0
	global_load_lds_dwordx4 v168, s[100:101]
	s_mov_b32 m0, s50
	s_nop 0
	global_load_lds_dwordx4 v164, s[100:101]
	s_waitcnt vmcnt(8)
	s_waitcnt lgkmcnt(0)
	s_barrier
	s_setprio 1
	v_mfma_f32_16x16x32_bf16 v[60:63], v[128:131], v[214:217], v[60:63]
	v_mfma_f32_16x16x32_bf16 v[60:63], v[132:135], v[218:221], v[60:63]
	v_mfma_f32_16x16x32_bf16 v[56:59], v[136:139], v[214:217], v[56:59]
	v_mfma_f32_16x16x32_bf16 v[56:59], v[140:143], v[218:221], v[56:59]
	v_mfma_f32_16x16x32_bf16 v[44:47], v[128:131], v[222:225], v[44:47]
	v_mfma_f32_16x16x32_bf16 v[44:47], v[132:135], v[226:229], v[44:47]
	v_mfma_f32_16x16x32_bf16 v[40:43], v[136:139], v[222:225], v[40:43]
	v_mfma_f32_16x16x32_bf16 v[40:43], v[140:143], v[226:229], v[40:43]
	v_mfma_f32_16x16x32_bf16 v[28:31], v[128:131], v[230:233], v[28:31]
	v_mfma_f32_16x16x32_bf16 v[28:31], v[132:135], v[234:237], v[28:31]
	v_mfma_f32_16x16x32_bf16 v[24:27], v[136:139], v[230:233], v[24:27]
	v_mfma_f32_16x16x32_bf16 v[24:27], v[140:143], v[234:237], v[24:27]
	v_mfma_f32_16x16x32_bf16 v[12:15], v[128:131], v[238:241], v[12:15]
	v_mfma_f32_16x16x32_bf16 v[12:15], v[132:135], v[242:245], v[12:15]
	v_mfma_f32_16x16x32_bf16 v[8:11], v[136:139], v[238:241], v[8:11]
	v_mfma_f32_16x16x32_bf16 v[8:11], v[140:143], v[242:245], v[8:11]
	v_mfma_f32_16x16x32_bf16 v[52:55], v[174:177], v[214:217], v[52:55]
	v_mfma_f32_16x16x32_bf16 v[52:55], v[184:187], v[218:221], v[52:55]
	v_mfma_f32_16x16x32_bf16 v[48:51], v[188:191], v[214:217], v[48:51]
	v_mfma_f32_16x16x32_bf16 v[48:51], v[210:213], v[218:221], v[48:51]
	v_mfma_f32_16x16x32_bf16 v[36:39], v[174:177], v[222:225], v[36:39]
	v_mfma_f32_16x16x32_bf16 v[36:39], v[184:187], v[226:229], v[36:39]
	v_mfma_f32_16x16x32_bf16 v[32:35], v[188:191], v[222:225], v[32:35]
	v_mfma_f32_16x16x32_bf16 v[32:35], v[210:213], v[226:229], v[32:35]
	v_mfma_f32_16x16x32_bf16 v[20:23], v[174:177], v[230:233], v[20:23]
	v_mfma_f32_16x16x32_bf16 v[20:23], v[184:187], v[234:237], v[20:23]
	v_mfma_f32_16x16x32_bf16 v[16:19], v[188:191], v[230:233], v[16:19]
	v_mfma_f32_16x16x32_bf16 v[16:19], v[210:213], v[234:237], v[16:19]
	v_mfma_f32_16x16x32_bf16 v[4:7], v[174:177], v[238:241], v[4:7]
	v_mfma_f32_16x16x32_bf16 v[4:7], v[184:187], v[242:245], v[4:7]
	v_mfma_f32_16x16x32_bf16 v[0:3], v[188:191], v[238:241], v[0:3]
	v_mfma_f32_16x16x32_bf16 v[0:3], v[210:213], v[242:245], v[0:3]
	s_setprio 0
	s_barrier
	s_add_i32 s13, s13, 2
	s_add_u32 s10, s10, 0x100
	s_addc_u32 s11, s11, 0
	s_cmp_gt_u32 s13, 41
	s_mov_b64 s[0:1], s[2:3]
	s_cbranch_scc0 .LBB0_545
	s_and_b64 vcc, exec, s[22:23]
	s_cbranch_vccz .LBB0_548
	s_barrier

; #define PG8_STAGE(bufoff, gbase, voff) do { _Pragma("unroll") for (int _i = 0; _i < 2; ++_i) \
;         __builtin_amdgcn_global_load_lds((const unsigned*)((const char*)(gbase) + (voff)[_i]), (PG8_LAS unsigned*)(lds + (bufoff) + ldsw + _i * 8192), 16, 0, 0); } while (0)
; #define PG8_LDA(dst, b, h) do { _Pragma("unroll") for (int m = 0; m < 4; ++m) _Pragma("unroll") for (int k = 0; k < 2; ++k) dst[m][k] = *(const PG8_LAS bf16x8*)(lds + PG8_SA(b, h) + aoff + m * 2048 + k * 1024); } while (0)
; #define PG8_LDB(dst, b, h) do { _Pragma("unroll") for (int n = 0; n < 2; ++n) _Pragma("unroll") for (int k = 0; k < 2; ++k) dst[n][k] = *(const PG8_LAS bf16x8*)(lds + PG8_SB(b, h) + boff + n * 2048 + k * 1024); } while (0)
; #define PG8_MMA(ai, bj, At, Bt) do { __builtin_amdgcn_s_setprio(1); _Pragma("unroll") for (int m = 0; m < 4; ++m) _Pragma("unroll") for (int n = 0; n < 2; ++n) _Pragma("unroll") for (int k = 0; k < 2; ++k) \
;         acc[ai][bj][m][n] = __builtin_amdgcn_mfma_f32_16x16x32_bf16(Bt[n][k], At[m][k], acc[ai][bj][m][n], 0, 0, 0); __builtin_amdgcn_s_setprio(0); } while (0)
; #define PG8_WAIT_V(n) asm volatile("s_waitcnt vmcnt(" #n ")" ::: "memory")
; #define PG8_WAIT_L(n) asm volatile("s_waitcnt lgkmcnt(" #n ")" ::: "memory")
; #define PG8_BAR __builtin_amdgcn_s_barrier()
; template <class Epi, class Sched, bool ALIGN_EPI = false, bool SP2 = false>
; __device__ __forceinline__ void gemm_phase(PG8_LAS unsigned char* lds, const Gemm g, const Sched& S, const Epi& E) {
;     ...
;             const char* a1 = cA + (size_t)(t + 1) * kstep;
;             const char* a2 = last ? nA : cA + (size_t)(t + 2) * kstep; const char* b2 = last ? nB : cB + (size_t)(t + 2) * kstep;
;             const char* a3 = a2 + kstep; const char* b3 = b2 + kstep;
;             if (last && has_next) S.a_ready(nxt);
;             if constexpr (SP2) {
;             PG8_LDB(B0, 0, 0); PG8_LDB(B1, 0, 1); PG8_SCHED; PG8_LDA(At, 0, 0); PG8_STAGE(PG8_SA(1, 1), a1 + hstep, voffA);
;             PG8_WAIT_V(8); PG8_WAIT_L(0); PG8_BAR; PG8_MMA(0, 0, At, B0); PG8_MMA(0, 1, At, B1); PG8_BAR; PG8_SCHED;
;             PG8_LDA(At, 0, 1); PG8_STAGE(PG8_SB(0, 0), b2, voffB); PG8_STAGE(PG8_SB(0, 1), b2 + hstep, voffB); PG8_STAGE(PG8_SA(0, 0), a2, voffA);
;             PG8_WAIT_V(8); PG8_WAIT_L(0); PG8_BAR; PG8_MMA(1, 0, At, B0); PG8_MMA(1, 1, At, B1); PG8_BAR; PG8_SCHED;
.Lsgi_peel:
	ds_read_b128 v[140:143], v254
	ds_read_b128 v[162:165], v254 offset:1024
	ds_read_b128 v[166:169], v254 offset:2048
	ds_read_b128 v[170:173], v254 offset:3072
	ds_read_b128 v[180:183], v254 offset:16384
	ds_read_b128 v[184:187], v254 offset:17408
	ds_read_b128 v[188:191], v254 offset:18432
	ds_read_b128 v[210:213], v254 offset:19456
	s_add_u32 s2, s0, 0xfffc0080
	s_addc_u32 s3, s1, -1
	s_cmp_eq_u32 s55, 12
	s_cselect_b32 s5, s13, s3
	s_cselect_b32 s4, s25, s2
	s_cselect_b32 s3, s23, s39
	s_cselect_b32 s2, s33, s38
	s_add_i32 m0, s6, 0xc000
	ds_read_b128 v[214:217], v178
	ds_read_b128 v[218:221], v178 offset:1024
	ds_read_b128 v[222:225], v178 offset:2048
	ds_read_b128 v[226:229], v178 offset:3072
	ds_read_b128 v[230:233], v178 offset:4096
	ds_read_b128 v[234:237], v178 offset:5120
	ds_read_b128 v[238:241], v178 offset:6144
	ds_read_b128 v[242:245], v178 offset:7168
	global_load_lds_dwordx4 v136, s[0:1]
	s_add_i32 m0, s6, 0xe000
	s_nop 0
	global_load_lds_dwordx4 v138, s[0:1]
	s_waitcnt vmcnt(8)
	s_waitcnt lgkmcnt(0)
	s_barrier
	s_setprio 1
	v_mfma_f32_16x16x32_bf16 v[124:127], v[140:143], v[214:217], 0
	v_mfma_f32_16x16x32_bf16 v[124:127], v[162:165], v[218:221], v[124:127]
	v_mfma_f32_16x16x32_bf16 v[120:123], v[166:169], v[214:217], 0
	v_mfma_f32_16x16x32_bf16 v[120:123], v[170:173], v[218:221], v[120:123]
	v_mfma_f32_16x16x32_bf16 v[108:111], v[140:143], v[222:225], 0
	v_mfma_f32_16x16x32_bf16 v[108:111], v[162:165], v[226:229], v[108:111]
	v_mfma_f32_16x16x32_bf16 v[104:107], v[166:169], v[222:225], 0
	v_mfma_f32_16x16x32_bf16 v[104:107], v[170:173], v[226:229], v[104:107]
	v_mfma_f32_16x16x32_bf16 v[92:95], v[140:143], v[230:233], 0
	v_mfma_f32_16x16x32_bf16 v[92:95], v[162:165], v[234:237], v[92:95]
	v_mfma_f32_16x16x32_bf16 v[88:91], v[166:169], v[230:233], 0
	v_mfma_f32_16x16x32_bf16 v[88:91], v[170:173], v[234:237], v[88:91]
	v_mfma_f32_16x16x32_bf16 v[76:79], v[140:143], v[238:241], 0
	v_mfma_f32_16x16x32_bf16 v[76:79], v[162:165], v[242:245], v[76:79]
	v_mfma_f32_16x16x32_bf16 v[72:75], v[166:169], v[238:241], 0
	v_mfma_f32_16x16x32_bf16 v[72:75], v[170:173], v[242:245], v[72:75]
	v_mfma_f32_16x16x32_bf16 v[116:119], v[180:183], v[214:217], 0
	v_mfma_f32_16x16x32_bf16 v[116:119], v[184:187], v[218:221], v[116:119]
	v_mfma_f32_16x16x32_bf16 v[112:115], v[188:191], v[214:217], 0
	v_mfma_f32_16x16x32_bf16 v[112:115], v[210:213], v[218:221], v[112:115]
	v_mfma_f32_16x16x32_bf16 v[100:103], v[180:183], v[222:225], 0
	v_mfma_f32_16x16x32_bf16 v[100:103], v[184:187], v[226:229], v[100:103]
	v_mfma_f32_16x16x32_bf16 v[96:99], v[188:191], v[222:225], 0
	v_mfma_f32_16x16x32_bf16 v[96:99], v[210:213], v[226:229], v[96:99]
	v_mfma_f32_16x16x32_bf16 v[84:87], v[180:183], v[230:233], 0
	v_mfma_f32_16x16x32_bf16 v[84:87], v[184:187], v[234:237], v[84:87]
	v_mfma_f32_16x16x32_bf16 v[80:83], v[188:191], v[230:233], 0
	v_mfma_f32_16x16x32_bf16 v[80:83], v[210:213], v[234:237], v[80:83]
	v_mfma_f32_16x16x32_bf16 v[68:71], v[180:183], v[238:241], 0
	v_mfma_f32_16x16x32_bf16 v[68:71], v[184:187], v[242:245], v[68:71]
	v_mfma_f32_16x16x32_bf16 v[64:67], v[188:191], v[238:241], 0
	v_mfma_f32_16x16x32_bf16 v[64:67], v[210:213], v[242:245], v[64:67]
	s_setprio 0
	s_barrier
	s_mov_b32 m0, s31
	s_add_u32 s56, s2, 0x40000
	s_addc_u32 s57, s3, 0
	ds_read_b128 v[214:217], v178 offset:16384
	ds_read_b128 v[218:221], v178 offset:17408
	ds_read_b128 v[222:225], v178 offset:18432
	ds_read_b128 v[226:229], v178 offset:19456
	ds_read_b128 v[230:233], v178 offset:20480
	ds_read_b128 v[234:237], v178 offset:21504
	ds_read_b128 v[238:241], v178 offset:22528
	ds_read_b128 v[242:245], v178 offset:23552
	global_load_lds_dwordx4 v132, s[2:3]
	s_mov_b32 m0, s34
	s_nop 0
	global_load_lds_dwordx4 v128, s[2:3]
	s_mov_b32 m0, s35
	s_nop 0
	global_load_lds_dwordx4 v132, s[56:57]
	s_mov_b32 m0, s40
	s_nop 0
	global_load_lds_dwordx4 v128, s[56:57]
	s_mov_b32 m0, s6
	s_nop 0
	global_load_lds_dwordx4 v134, s[4:5]
	s_mov_b32 m0, s41
	s_nop 0
	global_load_lds_dwordx4 v130, s[4:5]
	s_waitcnt vmcnt(8)
	s_waitcnt lgkmcnt(0)
	s_barrier
	s_setprio 1
	v_mfma_f32_16x16x32_bf16 v[60:63], v[140:143], v[214:217], 0
	v_mfma_f32_16x16x32_bf16 v[60:63], v[162:165], v[218:221], v[60:63]
	v_mfma_f32_16x16x32_bf16 v[56:59], v[166:169], v[214:217], 0
	v_mfma_f32_16x16x32_bf16 v[56:59], v[170:173], v[218:221], v[56:59]
	v_mfma_f32_16x16x32_bf16 v[44:47], v[140:143], v[222:225], 0
	v_mfma_f32_16x16x32_bf16 v[44:47], v[162:165], v[226:229], v[44:47]
	v_mfma_f32_16x16x32_bf16 v[40:43], v[166:169], v[222:225], 0
	v_mfma_f32_16x16x32_bf16 v[40:43], v[170:173], v[226:229], v[40:43]
	v_mfma_f32_16x16x32_bf16 v[28:31], v[140:143], v[230:233], 0
	v_mfma_f32_16x16x32_bf16 v[28:31], v[162:165], v[234:237], v[28:31]
	v_mfma_f32_16x16x32_bf16 v[24:27], v[166:169], v[230:233], 0
	v_mfma_f32_16x16x32_bf16 v[24:27], v[170:173], v[234:237], v[24:27]
	v_mfma_f32_16x16x32_bf16 v[12:15], v[140:143], v[238:241], 0
	v_mfma_f32_16x16x32_bf16 v[12:15], v[162:165], v[242:245], v[12:15]
	v_mfma_f32_16x16x32_bf16 v[8:11], v[166:169], v[238:241], 0
	v_mfma_f32_16x16x32_bf16 v[8:11], v[170:173], v[242:245], v[8:11]
	v_mfma_f32_16x16x32_bf16 v[52:55], v[180:183], v[214:217], 0
	v_mfma_f32_16x16x32_bf16 v[52:55], v[184:187], v[218:221], v[52:55]
	v_mfma_f32_16x16x32_bf16 v[48:51], v[188:191], v[214:217], 0
	v_mfma_f32_16x16x32_bf16 v[48:51], v[210:213], v[218:221], v[48:51]
	v_mfma_f32_16x16x32_bf16 v[36:39], v[180:183], v[222:225], 0
	v_mfma_f32_16x16x32_bf16 v[36:39], v[184:187], v[226:229], v[36:39]
	v_mfma_f32_16x16x32_bf16 v[32:35], v[188:191], v[222:225], 0
	v_mfma_f32_16x16x32_bf16 v[32:35], v[210:213], v[226:229], v[32:35]
	v_mfma_f32_16x16x32_bf16 v[20:23], v[180:183], v[230:233], 0
	v_mfma_f32_16x16x32_bf16 v[20:23], v[184:187], v[234:237], v[20:23]
	v_mfma_f32_16x16x32_bf16 v[16:19], v[188:191], v[230:233], 0
	v_mfma_f32_16x16x32_bf16 v[16:19], v[210:213], v[234:237], v[16:19]
	v_mfma_f32_16x16x32_bf16 v[4:7], v[180:183], v[238:241], 0
	v_mfma_f32_16x16x32_bf16 v[4:7], v[184:187], v[242:245], v[4:7]
	v_mfma_f32_16x16x32_bf16 v[0:3], v[188:191], v[238:241], 0
	v_mfma_f32_16x16x32_bf16 v[0:3], v[210:213], v[242:245], v[0:3]
	s_setprio 0
	s_barrier
; #define PG8_STAGE(bufoff, gbase, voff) do { _Pragma("unroll") for (int _i = 0; _i < 2; ++_i) \
;         __builtin_amdgcn_global_load_lds((const unsigned*)((const char*)(gbase) + (voff)[_i]), (PG8_LAS unsigned*)(lds + (bufoff) + ldsw + _i * 8192), 16, 0, 0); } while (0)
; #define PG8_LDA(dst, b, h) do { _Pragma("unroll") for (int m = 0; m < 4; ++m) _Pragma("unroll") for (int k = 0; k < 2; ++k) dst[m][k] = *(const PG8_LAS bf16x8*)(lds + PG8_SA(b, h) + aoff + m * 2048 + k * 1024); } while (0)
; #define PG8_LDB(dst, b, h) do { _Pragma("unroll") for (int n = 0; n < 2; ++n) _Pragma("unroll") for (int k = 0; k < 2; ++k) dst[n][k] = *(const PG8_LAS bf16x8*)(lds + PG8_SB(b, h) + boff + n * 2048 + k * 1024); } while (0)
; #define PG8_MMA(ai, bj, At, Bt) do { __builtin_amdgcn_s_setprio(1); _Pragma("unroll") for (int m = 0; m < 4; ++m) _Pragma("unroll") for (int n = 0; n < 2; ++n) _Pragma("unroll") for (int k = 0; k < 2; ++k) \
;         acc[ai][bj][m][n] = __builtin_amdgcn_mfma_f32_16x16x32_bf16(Bt[n][k], At[m][k], acc[ai][bj][m][n], 0, 0, 0); __builtin_amdgcn_s_setprio(0); } while (0)
; #define PG8_WAIT_V(n) asm volatile("s_waitcnt vmcnt(" #n ")" ::: "memory")
; #define PG8_WAIT_L(n) asm volatile("s_waitcnt lgkmcnt(" #n ")" ::: "memory")
; #define PG8_BAR __builtin_amdgcn_s_barrier()
; #define PG8_SCHED __builtin_amdgcn_sched_barrier(0)
; template <class Epi, class Sched, bool ALIGN_EPI = false, bool SP2 = false>
; __device__ __forceinline__ void gemm_phase(PG8_LAS unsigned char* lds, const Gemm g, const Sched& S, const Epi& E) {
;     ...
;             PG8_LDB(B0, 1, 0); PG8_LDB(B1, 1, 1); PG8_SCHED; PG8_LDA(At, 1, 0); PG8_STAGE(PG8_SA(0, 1), a2 + hstep, voffA);
;             PG8_WAIT_V(8); PG8_WAIT_L(0); PG8_BAR; PG8_MMA(0, 0, At, B0); PG8_MMA(0, 1, At, B1); PG8_BAR; PG8_SCHED;
;             PG8_LDA(At, 1, 1); PG8_STAGE(PG8_SB(1, 0), b3, voffB); PG8_STAGE(PG8_SB(1, 1), b3 + hstep, voffB); PG8_STAGE(PG8_SA(1, 0), a3, voffA);
;             PG8_WAIT_V(8); PG8_WAIT_L(0); PG8_BAR; PG8_MMA(1, 0, At, B0); PG8_MMA(1, 1, At, B1); PG8_BAR; PG8_SCHED;
	ds_read_b128 v[140:143], v254 offset:32768
	ds_read_b128 v[162:165], v254 offset:33792
	ds_read_b128 v[166:169], v254 offset:34816
	ds_read_b128 v[170:173], v254 offset:35840
	ds_read_b128 v[180:183], v254 offset:49152
	ds_read_b128 v[184:187], v254 offset:50176
	ds_read_b128 v[188:191], v254 offset:51200
	ds_read_b128 v[210:213], v254 offset:52224
	s_add_u32 s4, s4, 0x40000
	s_addc_u32 s5, s5, 0
	s_mov_b32 m0, s42
	ds_read_b128 v[214:217], v178 offset:32768
	ds_read_b128 v[218:221], v178 offset:33792
	ds_read_b128 v[222:225], v178 offset:34816
	ds_read_b128 v[226:229], v178 offset:35840
	ds_read_b128 v[230:233], v178 offset:36864
	ds_read_b128 v[234:237], v178 offset:37888
	ds_read_b128 v[238:241], v178 offset:38912
	ds_read_b128 v[242:245], v178 offset:39936
	global_load_lds_dwordx4 v134, s[4:5]
	s_mov_b32 m0, s43
	s_nop 0
	global_load_lds_dwordx4 v130, s[4:5]
	s_waitcnt vmcnt(8)
	s_waitcnt lgkmcnt(0)
	s_barrier
	s_setprio 1
	v_mfma_f32_16x16x32_bf16 v[124:127], v[140:143], v[214:217], v[124:127]
	v_mfma_f32_16x16x32_bf16 v[124:127], v[162:165], v[218:221], v[124:127]
	v_mfma_f32_16x16x32_bf16 v[120:123], v[166:169], v[214:217], v[120:123]
	v_mfma_f32_16x16x32_bf16 v[120:123], v[170:173], v[218:221], v[120:123]
	v_mfma_f32_16x16x32_bf16 v[108:111], v[140:143], v[222:225], v[108:111]
	v_mfma_f32_16x16x32_bf16 v[108:111], v[162:165], v[226:229], v[108:111]
	v_mfma_f32_16x16x32_bf16 v[104:107], v[166:169], v[222:225], v[104:107]
	v_mfma_f32_16x16x32_bf16 v[104:107], v[170:173], v[226:229], v[104:107]
	v_mfma_f32_16x16x32_bf16 v[92:95], v[140:143], v[230:233], v[92:95]
	v_mfma_f32_16x16x32_bf16 v[92:95], v[162:165], v[234:237], v[92:95]
	v_mfma_f32_16x16x32_bf16 v[88:91], v[166:169], v[230:233], v[88:91]
	v_mfma_f32_16x16x32_bf16 v[88:91], v[170:173], v[234:237], v[88:91]
	v_mfma_f32_16x16x32_bf16 v[76:79], v[140:143], v[238:241], v[76:79]
	v_mfma_f32_16x16x32_bf16 v[76:79], v[162:165], v[242:245], v[76:79]
	v_mfma_f32_16x16x32_bf16 v[72:75], v[166:169], v[238:241], v[72:75]
	v_mfma_f32_16x16x32_bf16 v[72:75], v[170:173], v[242:245], v[72:75]
	v_mfma_f32_16x16x32_bf16 v[116:119], v[180:183], v[214:217], v[116:119]
	v_mfma_f32_16x16x32_bf16 v[116:119], v[184:187], v[218:221], v[116:119]
	v_mfma_f32_16x16x32_bf16 v[112:115], v[188:191], v[214:217], v[112:115]
	v_mfma_f32_16x16x32_bf16 v[112:115], v[210:213], v[218:221], v[112:115]
	v_mfma_f32_16x16x32_bf16 v[100:103], v[180:183], v[222:225], v[100:103]
	v_mfma_f32_16x16x32_bf16 v[100:103], v[184:187], v[226:229], v[100:103]
	v_mfma_f32_16x16x32_bf16 v[96:99], v[188:191], v[222:225], v[96:99]
	v_mfma_f32_16x16x32_bf16 v[96:99], v[210:213], v[226:229], v[96:99]
	v_mfma_f32_16x16x32_bf16 v[84:87], v[180:183], v[230:233], v[84:87]
	v_mfma_f32_16x16x32_bf16 v[84:87], v[184:187], v[234:237], v[84:87]
	v_mfma_f32_16x16x32_bf16 v[80:83], v[188:191], v[230:233], v[80:83]
	v_mfma_f32_16x16x32_bf16 v[80:83], v[210:213], v[234:237], v[80:83]
	v_mfma_f32_16x16x32_bf16 v[68:71], v[180:183], v[238:241], v[68:71]
	v_mfma_f32_16x16x32_bf16 v[68:71], v[184:187], v[242:245], v[68:71]
	v_mfma_f32_16x16x32_bf16 v[64:67], v[188:191], v[238:241], v[64:67]
	v_mfma_f32_16x16x32_bf16 v[64:67], v[210:213], v[242:245], v[64:67]
	s_setprio 0
	s_barrier
	s_mov_b32 m0, s48
	s_add_u32 s2, s2, 0x40080
	s_addc_u32 s3, s3, 0
	ds_read_b128 v[214:217], v178 offset:49152
	ds_read_b128 v[218:221], v178 offset:50176
	ds_read_b128 v[222:225], v178 offset:51200
	ds_read_b128 v[226:229], v178 offset:52224
	ds_read_b128 v[230:233], v178 offset:53248
	ds_read_b128 v[234:237], v178 offset:54272
	ds_read_b128 v[238:241], v178 offset:55296
	ds_read_b128 v[242:245], v178 offset:56320
	s_add_u32 s98, s2, 0xfffc0000
	s_addc_u32 s99, s3, -1
	global_load_lds_dwordx4 v132, s[98:99]
	s_mov_b32 m0, s49
	s_nop 0
	global_load_lds_dwordx4 v128, s[98:99]
	s_mov_b32 m0, s52
	s_nop 0
	global_load_lds_dwordx4 v132, s[2:3]
	s_mov_b32 m0, s53
	s_nop 0
	global_load_lds_dwordx4 v128, s[2:3]
	s_mov_b32 m0, s50
	s_nop 0
	s_add_u32 s100, s4, 0xfffc0080
	s_addc_u32 s101, s5, -1
	global_load_lds_dwordx4 v134, s[100:101]
	s_mov_b32 m0, s51
	s_nop 0
	global_load_lds_dwordx4 v130, s[100:101]
	s_waitcnt vmcnt(8)
	s_waitcnt lgkmcnt(0)
	s_barrier
	s_setprio 1
	v_mfma_f32_16x16x32_bf16 v[60:63], v[140:143], v[214:217], v[60:63]
	v_mfma_f32_16x16x32_bf16 v[60:63], v[162:165], v[218:221], v[60:63]
	v_mfma_f32_16x16x32_bf16 v[56:59], v[166:169], v[214:217], v[56:59]
	v_mfma_f32_16x16x32_bf16 v[56:59], v[170:173], v[218:221], v[56:59]
	v_mfma_f32_16x16x32_bf16 v[44:47], v[140:143], v[222:225], v[44:47]
	v_mfma_f32_16x16x32_bf16 v[44:47], v[162:165], v[226:229], v[44:47]
	v_mfma_f32_16x16x32_bf16 v[40:43], v[166:169], v[222:225], v[40:43]
	v_mfma_f32_16x16x32_bf16 v[40:43], v[170:173], v[226:229], v[40:43]
	v_mfma_f32_16x16x32_bf16 v[28:31], v[140:143], v[230:233], v[28:31]
	v_mfma_f32_16x16x32_bf16 v[28:31], v[162:165], v[234:237], v[28:31]
	v_mfma_f32_16x16x32_bf16 v[24:27], v[166:169], v[230:233], v[24:27]
	v_mfma_f32_16x16x32_bf16 v[24:27], v[170:173], v[234:237], v[24:27]
	v_mfma_f32_16x16x32_bf16 v[12:15], v[140:143], v[238:241], v[12:15]
	v_mfma_f32_16x16x32_bf16 v[12:15], v[162:165], v[242:245], v[12:15]
	v_mfma_f32_16x16x32_bf16 v[8:11], v[166:169], v[238:241], v[8:11]
	v_mfma_f32_16x16x32_bf16 v[8:11], v[170:173], v[242:245], v[8:11]
	v_mfma_f32_16x16x32_bf16 v[52:55], v[180:183], v[214:217], v[52:55]
	v_mfma_f32_16x16x32_bf16 v[52:55], v[184:187], v[218:221], v[52:55]
	v_mfma_f32_16x16x32_bf16 v[48:51], v[188:191], v[214:217], v[48:51]
	v_mfma_f32_16x16x32_bf16 v[48:51], v[210:213], v[218:221], v[48:51]
	v_mfma_f32_16x16x32_bf16 v[36:39], v[180:183], v[222:225], v[36:39]
	v_mfma_f32_16x16x32_bf16 v[36:39], v[184:187], v[226:229], v[36:39]
	v_mfma_f32_16x16x32_bf16 v[32:35], v[188:191], v[222:225], v[32:35]
	v_mfma_f32_16x16x32_bf16 v[32:35], v[210:213], v[226:229], v[32:35]
	v_mfma_f32_16x16x32_bf16 v[20:23], v[180:183], v[230:233], v[20:23]
	v_mfma_f32_16x16x32_bf16 v[20:23], v[184:187], v[234:237], v[20:23]
	v_mfma_f32_16x16x32_bf16 v[16:19], v[188:191], v[230:233], v[16:19]
	v_mfma_f32_16x16x32_bf16 v[16:19], v[210:213], v[234:237], v[16:19]
	v_mfma_f32_16x16x32_bf16 v[4:7], v[180:183], v[238:241], v[4:7]
	v_mfma_f32_16x16x32_bf16 v[4:7], v[184:187], v[242:245], v[4:7]
	v_mfma_f32_16x16x32_bf16 v[0:3], v[188:191], v[238:241], v[0:3]
	v_mfma_f32_16x16x32_bf16 v[0:3], v[210:213], v[242:245], v[0:3]
	s_setprio 0
	s_barrier
	s_add_i32 s55, s55, 2
	s_add_u32 s0, s0, 0x100
	s_addc_u32 s1, s1, 0
	s_add_u32 s38, s38, 0x100
	s_addc_u32 s39, s39, 0
	s_cmp_gt_u32 s55, 13
; #define PG8_STAGE(bufoff, gbase, voff) do { _Pragma("unroll") for (int _i = 0; _i < 2; ++_i) \
;         __builtin_amdgcn_global_load_lds((const unsigned*)((const char*)(gbase) + (voff)[_i]), (PG8_LAS unsigned*)(lds + (bufoff) + ldsw + _i * 8192), 16, 0, 0); } while (0)
; #define PG8_LDA(dst, b, h) do { _Pragma("unroll") for (int m = 0; m < 4; ++m) _Pragma("unroll") for (int k = 0; k < 2; ++k) dst[m][k] = *(const PG8_LAS bf16x8*)(lds + PG8_SA(b, h) + aoff + m * 2048 + k * 1024); } while (0)
; #define PG8_LDB(dst, b, h) do { _Pragma("unroll") for (int n = 0; n < 2; ++n) _Pragma("unroll") for (int k = 0; k < 2; ++k) dst[n][k] = *(const PG8_LAS bf16x8*)(lds + PG8_SB(b, h) + boff + n * 2048 + k * 1024); } while (0)
; #define PG8_MMA(ai, bj, At, Bt) do { __builtin_amdgcn_s_setprio(1); _Pragma("unroll") for (int m = 0; m < 4; ++m) _Pragma("unroll") for (int n = 0; n < 2; ++n) _Pragma("unroll") for (int k = 0; k < 2; ++k) \
;         acc[ai][bj][m][n] = __builtin_amdgcn_mfma_f32_16x16x32_bf16(Bt[n][k], At[m][k], acc[ai][bj][m][n], 0, 0, 0); __builtin_amdgcn_s_setprio(0); } while (0)
; #define PG8_WAIT_V(n) asm volatile("s_waitcnt vmcnt(" #n ")" ::: "memory")
; #define PG8_WAIT_L(n) asm volatile("s_waitcnt lgkmcnt(" #n ")" ::: "memory")
; #define PG8_BAR __builtin_amdgcn_s_barrier()
; template <class Epi, class Sched, bool ALIGN_EPI = false, bool SP2 = false>
; __device__ __forceinline__ void gemm_phase(PG8_LAS unsigned char* lds, const Gemm g, const Sched& S, const Epi& E) {
;     ...
;             const char* a1 = cA + (size_t)(t + 1) * kstep;
;             const char* a2 = last ? nA : cA + (size_t)(t + 2) * kstep; const char* b2 = last ? nB : cB + (size_t)(t + 2) * kstep;
;             const char* a3 = a2 + kstep; const char* b3 = b2 + kstep;
;             if (last && has_next) S.a_ready(nxt);
;             if constexpr (SP2) {
;             PG8_LDB(B0, 0, 0); PG8_LDB(B1, 0, 1); PG8_SCHED; PG8_LDA(At, 0, 0); PG8_STAGE(PG8_SA(1, 1), a1 + hstep, voffA);
;             PG8_WAIT_V(8); PG8_WAIT_L(0); PG8_BAR; PG8_MMA(0, 0, At, B0); PG8_MMA(0, 1, At, B1); PG8_BAR; PG8_SCHED;
;             PG8_LDA(At, 0, 1); PG8_STAGE(PG8_SB(0, 0), b2, voffB); PG8_STAGE(PG8_SB(0, 1), b2 + hstep, voffB); PG8_STAGE(PG8_SA(0, 0), a2, voffA);
;             PG8_WAIT_V(8); PG8_WAIT_L(0); PG8_BAR; PG8_MMA(1, 0, At, B0); PG8_MMA(1, 1, At, B1); PG8_BAR; PG8_SCHED;
.LBB0_749:
	ds_read_b128 v[140:143], v254
	ds_read_b128 v[162:165], v254 offset:1024
	ds_read_b128 v[166:169], v254 offset:2048
	ds_read_b128 v[170:173], v254 offset:3072
	ds_read_b128 v[180:183], v254 offset:16384
	ds_read_b128 v[184:187], v254 offset:17408
	ds_read_b128 v[188:191], v254 offset:18432
	ds_read_b128 v[210:213], v254 offset:19456
	s_add_u32 s2, s0, 0xfffc0080
	s_addc_u32 s3, s1, -1
	s_cmp_eq_u32 s55, 12
	s_cselect_b32 s5, s13, s3
	s_cselect_b32 s4, s25, s2
	s_cselect_b32 s3, s23, s39
	s_cselect_b32 s2, s33, s38
	s_add_i32 m0, s6, 0xc000
	ds_read_b128 v[214:217], v178
	ds_read_b128 v[218:221], v178 offset:1024
	ds_read_b128 v[222:225], v178 offset:2048
	ds_read_b128 v[226:229], v178 offset:3072
	ds_read_b128 v[230:233], v178 offset:4096
	ds_read_b128 v[234:237], v178 offset:5120
	ds_read_b128 v[238:241], v178 offset:6144
	ds_read_b128 v[242:245], v178 offset:7168
	global_load_lds_dwordx4 v136, s[0:1]
	s_add_i32 m0, s6, 0xe000
	s_nop 0
	global_load_lds_dwordx4 v138, s[0:1]
	s_waitcnt vmcnt(8)
	s_waitcnt lgkmcnt(0)
	s_barrier
	s_setprio 1
	v_mfma_f32_16x16x32_bf16 v[124:127], v[140:143], v[214:217], v[124:127]
	v_mfma_f32_16x16x32_bf16 v[124:127], v[162:165], v[218:221], v[124:127]
	v_mfma_f32_16x16x32_bf16 v[120:123], v[166:169], v[214:217], v[120:123]
	v_mfma_f32_16x16x32_bf16 v[120:123], v[170:173], v[218:221], v[120:123]
	v_mfma_f32_16x16x32_bf16 v[108:111], v[140:143], v[222:225], v[108:111]
	v_mfma_f32_16x16x32_bf16 v[108:111], v[162:165], v[226:229], v[108:111]
	v_mfma_f32_16x16x32_bf16 v[104:107], v[166:169], v[222:225], v[104:107]
	v_mfma_f32_16x16x32_bf16 v[104:107], v[170:173], v[226:229], v[104:107]
	v_mfma_f32_16x16x32_bf16 v[92:95], v[140:143], v[230:233], v[92:95]
	v_mfma_f32_16x16x32_bf16 v[92:95], v[162:165], v[234:237], v[92:95]
	v_mfma_f32_16x16x32_bf16 v[88:91], v[166:169], v[230:233], v[88:91]
	v_mfma_f32_16x16x32_bf16 v[88:91], v[170:173], v[234:237], v[88:91]
	v_mfma_f32_16x16x32_bf16 v[76:79], v[140:143], v[238:241], v[76:79]
	v_mfma_f32_16x16x32_bf16 v[76:79], v[162:165], v[242:245], v[76:79]
	v_mfma_f32_16x16x32_bf16 v[72:75], v[166:169], v[238:241], v[72:75]
	v_mfma_f32_16x16x32_bf16 v[72:75], v[170:173], v[242:245], v[72:75]
	v_mfma_f32_16x16x32_bf16 v[116:119], v[180:183], v[214:217], v[116:119]
	v_mfma_f32_16x16x32_bf16 v[116:119], v[184:187], v[218:221], v[116:119]
	v_mfma_f32_16x16x32_bf16 v[112:115], v[188:191], v[214:217], v[112:115]
	v_mfma_f32_16x16x32_bf16 v[112:115], v[210:213], v[218:221], v[112:115]
	v_mfma_f32_16x16x32_bf16 v[100:103], v[180:183], v[222:225], v[100:103]
	v_mfma_f32_16x16x32_bf16 v[100:103], v[184:187], v[226:229], v[100:103]
	v_mfma_f32_16x16x32_bf16 v[96:99], v[188:191], v[222:225], v[96:99]
	v_mfma_f32_16x16x32_bf16 v[96:99], v[210:213], v[226:229], v[96:99]
	v_mfma_f32_16x16x32_bf16 v[84:87], v[180:183], v[230:233], v[84:87]
	v_mfma_f32_16x16x32_bf16 v[84:87], v[184:187], v[234:237], v[84:87]
	v_mfma_f32_16x16x32_bf16 v[80:83], v[188:191], v[230:233], v[80:83]
	v_mfma_f32_16x16x32_bf16 v[80:83], v[210:213], v[234:237], v[80:83]
	v_mfma_f32_16x16x32_bf16 v[68:71], v[180:183], v[238:241], v[68:71]
	v_mfma_f32_16x16x32_bf16 v[68:71], v[184:187], v[242:245], v[68:71]
	v_mfma_f32_16x16x32_bf16 v[64:67], v[188:191], v[238:241], v[64:67]
	v_mfma_f32_16x16x32_bf16 v[64:67], v[210:213], v[242:245], v[64:67]
	s_setprio 0
	s_barrier
	s_mov_b32 m0, s31
	s_add_u32 s56, s2, 0x40000
	s_addc_u32 s57, s3, 0
	ds_read_b128 v[214:217], v178 offset:16384
	ds_read_b128 v[218:221], v178 offset:17408
	ds_read_b128 v[222:225], v178 offset:18432
	ds_read_b128 v[226:229], v178 offset:19456
	ds_read_b128 v[230:233], v178 offset:20480
	ds_read_b128 v[234:237], v178 offset:21504
	ds_read_b128 v[238:241], v178 offset:22528
	ds_read_b128 v[242:245], v178 offset:23552
	global_load_lds_dwordx4 v132, s[2:3]
	s_mov_b32 m0, s34
	s_nop 0
	global_load_lds_dwordx4 v128, s[2:3]
	s_mov_b32 m0, s35
	s_nop 0
	global_load_lds_dwordx4 v132, s[56:57]
	s_mov_b32 m0, s40
	s_nop 0
	global_load_lds_dwordx4 v128, s[56:57]
	s_mov_b32 m0, s6
	s_nop 0
	global_load_lds_dwordx4 v134, s[4:5]
	s_mov_b32 m0, s41
	s_nop 0
	global_load_lds_dwordx4 v130, s[4:5]
	s_waitcnt vmcnt(8)
	s_waitcnt lgkmcnt(0)
	s_barrier
	s_setprio 1
	v_mfma_f32_16x16x32_bf16 v[60:63], v[140:143], v[214:217], v[60:63]
	v_mfma_f32_16x16x32_bf16 v[60:63], v[162:165], v[218:221], v[60:63]
	v_mfma_f32_16x16x32_bf16 v[56:59], v[166:169], v[214:217], v[56:59]
	v_mfma_f32_16x16x32_bf16 v[56:59], v[170:173], v[218:221], v[56:59]
	v_mfma_f32_16x16x32_bf16 v[44:47], v[140:143], v[222:225], v[44:47]
	v_mfma_f32_16x16x32_bf16 v[44:47], v[162:165], v[226:229], v[44:47]
	v_mfma_f32_16x16x32_bf16 v[40:43], v[166:169], v[222:225], v[40:43]
	v_mfma_f32_16x16x32_bf16 v[40:43], v[170:173], v[226:229], v[40:43]
	v_mfma_f32_16x16x32_bf16 v[28:31], v[140:143], v[230:233], v[28:31]
	v_mfma_f32_16x16x32_bf16 v[28:31], v[162:165], v[234:237], v[28:31]
	v_mfma_f32_16x16x32_bf16 v[24:27], v[166:169], v[230:233], v[24:27]
	v_mfma_f32_16x16x32_bf16 v[24:27], v[170:173], v[234:237], v[24:27]
	v_mfma_f32_16x16x32_bf16 v[12:15], v[140:143], v[238:241], v[12:15]
	v_mfma_f32_16x16x32_bf16 v[12:15], v[162:165], v[242:245], v[12:15]
	v_mfma_f32_16x16x32_bf16 v[8:11], v[166:169], v[238:241], v[8:11]
	v_mfma_f32_16x16x32_bf16 v[8:11], v[170:173], v[242:245], v[8:11]
	v_mfma_f32_16x16x32_bf16 v[52:55], v[180:183], v[214:217], v[52:55]
	v_mfma_f32_16x16x32_bf16 v[52:55], v[184:187], v[218:221], v[52:55]
	v_mfma_f32_16x16x32_bf16 v[48:51], v[188:191], v[214:217], v[48:51]
	v_mfma_f32_16x16x32_bf16 v[48:51], v[210:213], v[218:221], v[48:51]
	v_mfma_f32_16x16x32_bf16 v[36:39], v[180:183], v[222:225], v[36:39]
	v_mfma_f32_16x16x32_bf16 v[36:39], v[184:187], v[226:229], v[36:39]
	v_mfma_f32_16x16x32_bf16 v[32:35], v[188:191], v[222:225], v[32:35]
	v_mfma_f32_16x16x32_bf16 v[32:35], v[210:213], v[226:229], v[32:35]
	v_mfma_f32_16x16x32_bf16 v[20:23], v[180:183], v[230:233], v[20:23]
	v_mfma_f32_16x16x32_bf16 v[20:23], v[184:187], v[234:237], v[20:23]
	v_mfma_f32_16x16x32_bf16 v[16:19], v[188:191], v[230:233], v[16:19]
	v_mfma_f32_16x16x32_bf16 v[16:19], v[210:213], v[234:237], v[16:19]
	v_mfma_f32_16x16x32_bf16 v[4:7], v[180:183], v[238:241], v[4:7]
	v_mfma_f32_16x16x32_bf16 v[4:7], v[184:187], v[242:245], v[4:7]
	v_mfma_f32_16x16x32_bf16 v[0:3], v[188:191], v[238:241], v[0:3]
	v_mfma_f32_16x16x32_bf16 v[0:3], v[210:213], v[242:245], v[0:3]
	s_setprio 0
	s_barrier
; #define PG8_STAGE(bufoff, gbase, voff) do { _Pragma("unroll") for (int _i = 0; _i < 2; ++_i) \
;         __builtin_amdgcn_global_load_lds((const unsigned*)((const char*)(gbase) + (voff)[_i]), (PG8_LAS unsigned*)(lds + (bufoff) + ldsw + _i * 8192), 16, 0, 0); } while (0)
; #define PG8_LDA(dst, b, h) do { _Pragma("unroll") for (int m = 0; m < 4; ++m) _Pragma("unroll") for (int k = 0; k < 2; ++k) dst[m][k] = *(const PG8_LAS bf16x8*)(lds + PG8_SA(b, h) + aoff + m * 2048 + k * 1024); } while (0)
; #define PG8_LDB(dst, b, h) do { _Pragma("unroll") for (int n = 0; n < 2; ++n) _Pragma("unroll") for (int k = 0; k < 2; ++k) dst[n][k] = *(const PG8_LAS bf16x8*)(lds + PG8_SB(b, h) + boff + n * 2048 + k * 1024); } while (0)
; #define PG8_MMA(ai, bj, At, Bt) do { __builtin_amdgcn_s_setprio(1); _Pragma("unroll") for (int m = 0; m < 4; ++m) _Pragma("unroll") for (int n = 0; n < 2; ++n) _Pragma("unroll") for (int k = 0; k < 2; ++k) \
;         acc[ai][bj][m][n] = __builtin_amdgcn_mfma_f32_16x16x32_bf16(Bt[n][k], At[m][k], acc[ai][bj][m][n], 0, 0, 0); __builtin_amdgcn_s_setprio(0); } while (0)
; #define PG8_WAIT_V(n) asm volatile("s_waitcnt vmcnt(" #n ")" ::: "memory")
; #define PG8_WAIT_L(n) asm volatile("s_waitcnt lgkmcnt(" #n ")" ::: "memory")
; #define PG8_BAR __builtin_amdgcn_s_barrier()
; #define PG8_SCHED __builtin_amdgcn_sched_barrier(0)
; template <class Epi, class Sched, bool ALIGN_EPI = false, bool SP2 = false>
; __device__ __forceinline__ void gemm_phase(PG8_LAS unsigned char* lds, const Gemm g, const Sched& S, const Epi& E) {
;     ...
;             PG8_LDB(B0, 1, 0); PG8_LDB(B1, 1, 1); PG8_SCHED; PG8_LDA(At, 1, 0); PG8_STAGE(PG8_SA(0, 1), a2 + hstep, voffA);
;             PG8_WAIT_V(8); PG8_WAIT_L(0); PG8_BAR; PG8_MMA(0, 0, At, B0); PG8_MMA(0, 1, At, B1); PG8_BAR; PG8_SCHED;
;             PG8_LDA(At, 1, 1); PG8_STAGE(PG8_SB(1, 0), b3, voffB); PG8_STAGE(PG8_SB(1, 1), b3 + hstep, voffB); PG8_STAGE(PG8_SA(1, 0), a3, voffA);
;             PG8_WAIT_V(8); PG8_WAIT_L(0); PG8_BAR; PG8_MMA(1, 0, At, B0); PG8_MMA(1, 1, At, B1); PG8_BAR; PG8_SCHED;
	ds_read_b128 v[140:143], v254 offset:32768
	ds_read_b128 v[162:165], v254 offset:33792
	ds_read_b128 v[166:169], v254 offset:34816
	ds_read_b128 v[170:173], v254 offset:35840
	ds_read_b128 v[180:183], v254 offset:49152
	ds_read_b128 v[184:187], v254 offset:50176
	ds_read_b128 v[188:191], v254 offset:51200
	ds_read_b128 v[210:213], v254 offset:52224
	s_add_u32 s4, s4, 0x40000
	s_addc_u32 s5, s5, 0
	s_mov_b32 m0, s42
	ds_read_b128 v[214:217], v178 offset:32768
	ds_read_b128 v[218:221], v178 offset:33792
	ds_read_b128 v[222:225], v178 offset:34816
	ds_read_b128 v[226:229], v178 offset:35840
	ds_read_b128 v[230:233], v178 offset:36864
	ds_read_b128 v[234:237], v178 offset:37888
	ds_read_b128 v[238:241], v178 offset:38912
	ds_read_b128 v[242:245], v178 offset:39936
	global_load_lds_dwordx4 v134, s[4:5]
	s_mov_b32 m0, s43
	s_nop 0
	global_load_lds_dwordx4 v130, s[4:5]
	s_waitcnt vmcnt(8)
	s_waitcnt lgkmcnt(0)
	s_barrier
	s_setprio 1
	v_mfma_f32_16x16x32_bf16 v[124:127], v[140:143], v[214:217], v[124:127]
	v_mfma_f32_16x16x32_bf16 v[124:127], v[162:165], v[218:221], v[124:127]
	v_mfma_f32_16x16x32_bf16 v[120:123], v[166:169], v[214:217], v[120:123]
	v_mfma_f32_16x16x32_bf16 v[120:123], v[170:173], v[218:221], v[120:123]
	v_mfma_f32_16x16x32_bf16 v[108:111], v[140:143], v[222:225], v[108:111]
	v_mfma_f32_16x16x32_bf16 v[108:111], v[162:165], v[226:229], v[108:111]
	v_mfma_f32_16x16x32_bf16 v[104:107], v[166:169], v[222:225], v[104:107]
	v_mfma_f32_16x16x32_bf16 v[104:107], v[170:173], v[226:229], v[104:107]
	v_mfma_f32_16x16x32_bf16 v[92:95], v[140:143], v[230:233], v[92:95]
	v_mfma_f32_16x16x32_bf16 v[92:95], v[162:165], v[234:237], v[92:95]
	v_mfma_f32_16x16x32_bf16 v[88:91], v[166:169], v[230:233], v[88:91]
	v_mfma_f32_16x16x32_bf16 v[88:91], v[170:173], v[234:237], v[88:91]
	v_mfma_f32_16x16x32_bf16 v[76:79], v[140:143], v[238:241], v[76:79]
	v_mfma_f32_16x16x32_bf16 v[76:79], v[162:165], v[242:245], v[76:79]
	v_mfma_f32_16x16x32_bf16 v[72:75], v[166:169], v[238:241], v[72:75]
	v_mfma_f32_16x16x32_bf16 v[72:75], v[170:173], v[242:245], v[72:75]
	v_mfma_f32_16x16x32_bf16 v[116:119], v[180:183], v[214:217], v[116:119]
	v_mfma_f32_16x16x32_bf16 v[116:119], v[184:187], v[218:221], v[116:119]
	v_mfma_f32_16x16x32_bf16 v[112:115], v[188:191], v[214:217], v[112:115]
	v_mfma_f32_16x16x32_bf16 v[112:115], v[210:213], v[218:221], v[112:115]
	v_mfma_f32_16x16x32_bf16 v[100:103], v[180:183], v[222:225], v[100:103]
	v_mfma_f32_16x16x32_bf16 v[100:103], v[184:187], v[226:229], v[100:103]
	v_mfma_f32_16x16x32_bf16 v[96:99], v[188:191], v[222:225], v[96:99]
	v_mfma_f32_16x16x32_bf16 v[96:99], v[210:213], v[226:229], v[96:99]
	v_mfma_f32_16x16x32_bf16 v[84:87], v[180:183], v[230:233], v[84:87]
	v_mfma_f32_16x16x32_bf16 v[84:87], v[184:187], v[234:237], v[84:87]
	v_mfma_f32_16x16x32_bf16 v[80:83], v[188:191], v[230:233], v[80:83]
	v_mfma_f32_16x16x32_bf16 v[80:83], v[210:213], v[234:237], v[80:83]
	v_mfma_f32_16x16x32_bf16 v[68:71], v[180:183], v[238:241], v[68:71]
	v_mfma_f32_16x16x32_bf16 v[68:71], v[184:187], v[242:245], v[68:71]
	v_mfma_f32_16x16x32_bf16 v[64:67], v[188:191], v[238:241], v[64:67]
	v_mfma_f32_16x16x32_bf16 v[64:67], v[210:213], v[242:245], v[64:67]
	s_setprio 0
	s_barrier
	s_mov_b32 m0, s48
	s_add_u32 s2, s2, 0x40080
	s_addc_u32 s3, s3, 0
	ds_read_b128 v[214:217], v178 offset:49152
	ds_read_b128 v[218:221], v178 offset:50176
	ds_read_b128 v[222:225], v178 offset:51200
	ds_read_b128 v[226:229], v178 offset:52224
	ds_read_b128 v[230:233], v178 offset:53248
	ds_read_b128 v[234:237], v178 offset:54272
	ds_read_b128 v[238:241], v178 offset:55296
	ds_read_b128 v[242:245], v178 offset:56320
	s_add_u32 s98, s2, 0xfffc0000
	s_addc_u32 s99, s3, -1
	global_load_lds_dwordx4 v132, s[98:99]
	s_mov_b32 m0, s49
	s_nop 0
	global_load_lds_dwordx4 v128, s[98:99]
	s_mov_b32 m0, s52
	s_nop 0
	global_load_lds_dwordx4 v132, s[2:3]
	s_mov_b32 m0, s53
	s_nop 0
	global_load_lds_dwordx4 v128, s[2:3]
	s_mov_b32 m0, s50
	s_nop 0
	s_add_u32 s100, s4, 0xfffc0080
	s_addc_u32 s101, s5, -1
	global_load_lds_dwordx4 v134, s[100:101]
	s_mov_b32 m0, s51
	s_nop 0
	global_load_lds_dwordx4 v130, s[100:101]
	s_waitcnt vmcnt(8)
	s_waitcnt lgkmcnt(0)
	s_barrier
	s_setprio 1
	v_mfma_f32_16x16x32_bf16 v[60:63], v[140:143], v[214:217], v[60:63]
	v_mfma_f32_16x16x32_bf16 v[60:63], v[162:165], v[218:221], v[60:63]
	v_mfma_f32_16x16x32_bf16 v[56:59], v[166:169], v[214:217], v[56:59]
	v_mfma_f32_16x16x32_bf16 v[56:59], v[170:173], v[218:221], v[56:59]
	v_mfma_f32_16x16x32_bf16 v[44:47], v[140:143], v[222:225], v[44:47]
	v_mfma_f32_16x16x32_bf16 v[44:47], v[162:165], v[226:229], v[44:47]
	v_mfma_f32_16x16x32_bf16 v[40:43], v[166:169], v[222:225], v[40:43]
	v_mfma_f32_16x16x32_bf16 v[40:43], v[170:173], v[226:229], v[40:43]
	v_mfma_f32_16x16x32_bf16 v[28:31], v[140:143], v[230:233], v[28:31]
	v_mfma_f32_16x16x32_bf16 v[28:31], v[162:165], v[234:237], v[28:31]
	v_mfma_f32_16x16x32_bf16 v[24:27], v[166:169], v[230:233], v[24:27]
	v_mfma_f32_16x16x32_bf16 v[24:27], v[170:173], v[234:237], v[24:27]
	v_mfma_f32_16x16x32_bf16 v[12:15], v[140:143], v[238:241], v[12:15]
	v_mfma_f32_16x16x32_bf16 v[12:15], v[162:165], v[242:245], v[12:15]
	v_mfma_f32_16x16x32_bf16 v[8:11], v[166:169], v[238:241], v[8:11]
	v_mfma_f32_16x16x32_bf16 v[8:11], v[170:173], v[242:245], v[8:11]
	v_mfma_f32_16x16x32_bf16 v[52:55], v[180:183], v[214:217], v[52:55]
	v_mfma_f32_16x16x32_bf16 v[52:55], v[184:187], v[218:221], v[52:55]
	v_mfma_f32_16x16x32_bf16 v[48:51], v[188:191], v[214:217], v[48:51]
	v_mfma_f32_16x16x32_bf16 v[48:51], v[210:213], v[218:221], v[48:51]
	v_mfma_f32_16x16x32_bf16 v[36:39], v[180:183], v[222:225], v[36:39]
	v_mfma_f32_16x16x32_bf16 v[36:39], v[184:187], v[226:229], v[36:39]
	v_mfma_f32_16x16x32_bf16 v[32:35], v[188:191], v[222:225], v[32:35]
	v_mfma_f32_16x16x32_bf16 v[32:35], v[210:213], v[226:229], v[32:35]
	v_mfma_f32_16x16x32_bf16 v[20:23], v[180:183], v[230:233], v[20:23]
	v_mfma_f32_16x16x32_bf16 v[20:23], v[184:187], v[234:237], v[20:23]
	v_mfma_f32_16x16x32_bf16 v[16:19], v[188:191], v[230:233], v[16:19]
	v_mfma_f32_16x16x32_bf16 v[16:19], v[210:213], v[234:237], v[16:19]
	v_mfma_f32_16x16x32_bf16 v[4:7], v[180:183], v[238:241], v[4:7]
	v_mfma_f32_16x16x32_bf16 v[4:7], v[184:187], v[242:245], v[4:7]
	v_mfma_f32_16x16x32_bf16 v[0:3], v[188:191], v[238:241], v[0:3]
	v_mfma_f32_16x16x32_bf16 v[0:3], v[210:213], v[242:245], v[0:3]
	s_setprio 0
	s_barrier
	s_add_i32 s55, s55, 2
	s_add_u32 s0, s0, 0x100
	s_addc_u32 s1, s1, 0
	s_add_u32 s38, s38, 0x100
	s_addc_u32 s39, s39, 0
	s_cmp_gt_u32 s55, 13
	s_cbranch_scc0 .LBB0_749
	s_and_b64 vcc, exec, s[18:19]
	s_cbranch_vccz .LBB0_752
	s_barrier

; #define PG8_STAGE(bufoff, gbase, voff) do { _Pragma("unroll") for (int _i = 0; _i < 2; ++_i) \
;         __builtin_amdgcn_global_load_lds((const unsigned*)((const char*)(gbase) + (voff)[_i]), (PG8_LAS unsigned*)(lds + (bufoff) + ldsw + _i * 8192), 16, 0, 0); } while (0)
; #define PG8_LDA(dst, b, h) do { _Pragma("unroll") for (int m = 0; m < 4; ++m) _Pragma("unroll") for (int k = 0; k < 2; ++k) dst[m][k] = *(const PG8_LAS bf16x8*)(lds + PG8_SA(b, h) + aoff + m * 2048 + k * 1024); } while (0)
; #define PG8_LDB(dst, b, h) do { _Pragma("unroll") for (int n = 0; n < 2; ++n) _Pragma("unroll") for (int k = 0; k < 2; ++k) dst[n][k] = *(const PG8_LAS bf16x8*)(lds + PG8_SB(b, h) + boff + n * 2048 + k * 1024); } while (0)
; #define PG8_MMA(ai, bj, At, Bt) do { __builtin_amdgcn_s_setprio(1); _Pragma("unroll") for (int m = 0; m < 4; ++m) _Pragma("unroll") for (int n = 0; n < 2; ++n) _Pragma("unroll") for (int k = 0; k < 2; ++k) \
;         acc[ai][bj][m][n] = __builtin_amdgcn_mfma_f32_16x16x32_bf16(Bt[n][k], At[m][k], acc[ai][bj][m][n], 0, 0, 0); __builtin_amdgcn_s_setprio(0); } while (0)
; #define PG8_WAIT_V(n) asm volatile("s_waitcnt vmcnt(" #n ")" ::: "memory")
; #define PG8_WAIT_L(n) asm volatile("s_waitcnt lgkmcnt(" #n ")" ::: "memory")
; #define PG8_BAR __builtin_amdgcn_s_barrier()
; template <class Epi, class Sched, bool ALIGN_EPI = false, bool SP2 = false>
; __device__ __forceinline__ void gemm_phase(PG8_LAS unsigned char* lds, const Gemm g, const Sched& S, const Epi& E) {
;     ...
;             const char* a1 = cA + (size_t)(t + 1) * kstep;
;             const char* a2 = last ? nA : cA + (size_t)(t + 2) * kstep; const char* b2 = last ? nB : cB + (size_t)(t + 2) * kstep;
;             const char* a3 = a2 + kstep; const char* b3 = b2 + kstep;
;             if (last && has_next) S.a_ready(nxt);
;             if constexpr (SP2) {
;             PG8_LDB(B0, 0, 0); PG8_LDB(B1, 0, 1); PG8_SCHED; PG8_LDA(At, 0, 0); PG8_STAGE(PG8_SA(1, 1), a1 + hstep, voffA);
;             PG8_WAIT_V(8); PG8_WAIT_L(0); PG8_BAR; PG8_MMA(0, 0, At, B0); PG8_MMA(0, 1, At, B1); PG8_BAR; PG8_SCHED;
;             PG8_LDA(At, 0, 1); PG8_STAGE(PG8_SB(0, 0), b2, voffB); PG8_STAGE(PG8_SB(0, 1), b2 + hstep, voffB); PG8_STAGE(PG8_SA(0, 0), a2, voffA);
;             PG8_WAIT_V(8); PG8_WAIT_L(0); PG8_BAR; PG8_MMA(1, 0, At, B0); PG8_MMA(1, 1, At, B1); PG8_BAR; PG8_SCHED;
.Labi_peel:
	s_waitcnt lgkmcnt(0)
	ds_read_b128 v[140:143], v254
	ds_read_b128 v[162:165], v254 offset:1024
	ds_read_b128 v[166:169], v254 offset:2048
	ds_read_b128 v[176:179], v254 offset:3072
	ds_read_b128 v[180:183], v254 offset:16384
	ds_read_b128 v[184:187], v254 offset:17408
	ds_read_b128 v[188:191], v254 offset:18432
	ds_read_b128 v[210:213], v254 offset:19456
	s_add_u32 s2, s0, 0xfffc0080
	s_addc_u32 s3, s1, -1
	s_cmp_eq_u32 s52, 12
	s_cselect_b32 s5, s17, s3
	s_cselect_b32 s4, s48, s2
	s_cselect_b32 s3, s15, s51
	s_cselect_b32 s2, s49, s50
	s_add_i32 m0, s6, 0xc000
	ds_read_b128 v[214:217], v173
	ds_read_b128 v[218:221], v173 offset:1024
	ds_read_b128 v[222:225], v173 offset:2048
	ds_read_b128 v[226:229], v173 offset:3072
	ds_read_b128 v[230:233], v173 offset:4096
	ds_read_b128 v[234:237], v173 offset:5120
	ds_read_b128 v[238:241], v173 offset:6144
	ds_read_b128 v[242:245], v173 offset:7168
	global_load_lds_dwordx4 v136, s[0:1]
	s_add_i32 m0, s6, 0xe000
	s_nop 0
	global_load_lds_dwordx4 v138, s[0:1]
	s_waitcnt vmcnt(8)
	s_waitcnt lgkmcnt(0)
	s_barrier
	s_setprio 1
	v_mfma_f32_16x16x32_bf16 v[124:127], v[140:143], v[214:217], 0
	v_mfma_f32_16x16x32_bf16 v[124:127], v[162:165], v[218:221], v[124:127]
	v_mfma_f32_16x16x32_bf16 v[120:123], v[166:169], v[214:217], 0
	v_mfma_f32_16x16x32_bf16 v[120:123], v[176:179], v[218:221], v[120:123]
	v_mfma_f32_16x16x32_bf16 v[112:115], v[140:143], v[222:225], 0
	v_mfma_f32_16x16x32_bf16 v[112:115], v[162:165], v[226:229], v[112:115]
	v_mfma_f32_16x16x32_bf16 v[104:107], v[166:169], v[222:225], 0
	v_mfma_f32_16x16x32_bf16 v[104:107], v[176:179], v[226:229], v[104:107]
	v_mfma_f32_16x16x32_bf16 v[96:99], v[140:143], v[230:233], 0
	v_mfma_f32_16x16x32_bf16 v[96:99], v[162:165], v[234:237], v[96:99]
	v_mfma_f32_16x16x32_bf16 v[88:91], v[166:169], v[230:233], 0
	v_mfma_f32_16x16x32_bf16 v[88:91], v[176:179], v[234:237], v[88:91]
	v_mfma_f32_16x16x32_bf16 v[80:83], v[140:143], v[238:241], 0
	v_mfma_f32_16x16x32_bf16 v[80:83], v[162:165], v[242:245], v[80:83]
	v_mfma_f32_16x16x32_bf16 v[72:75], v[166:169], v[238:241], 0
	v_mfma_f32_16x16x32_bf16 v[72:75], v[176:179], v[242:245], v[72:75]
	v_mfma_f32_16x16x32_bf16 v[116:119], v[180:183], v[214:217], 0
	v_mfma_f32_16x16x32_bf16 v[116:119], v[184:187], v[218:221], v[116:119]
	v_mfma_f32_16x16x32_bf16 v[108:111], v[188:191], v[214:217], 0
	v_mfma_f32_16x16x32_bf16 v[108:111], v[210:213], v[218:221], v[108:111]
	v_mfma_f32_16x16x32_bf16 v[100:103], v[180:183], v[222:225], 0
	v_mfma_f32_16x16x32_bf16 v[100:103], v[184:187], v[226:229], v[100:103]
	v_mfma_f32_16x16x32_bf16 v[92:95], v[188:191], v[222:225], 0
	v_mfma_f32_16x16x32_bf16 v[92:95], v[210:213], v[226:229], v[92:95]
	v_mfma_f32_16x16x32_bf16 v[84:87], v[180:183], v[230:233], 0
	v_mfma_f32_16x16x32_bf16 v[84:87], v[184:187], v[234:237], v[84:87]
	v_mfma_f32_16x16x32_bf16 v[76:79], v[188:191], v[230:233], 0
	v_mfma_f32_16x16x32_bf16 v[76:79], v[210:213], v[234:237], v[76:79]
	v_mfma_f32_16x16x32_bf16 v[68:71], v[180:183], v[238:241], 0
	v_mfma_f32_16x16x32_bf16 v[68:71], v[184:187], v[242:245], v[68:71]
	v_mfma_f32_16x16x32_bf16 v[64:67], v[188:191], v[238:241], 0
	v_mfma_f32_16x16x32_bf16 v[64:67], v[210:213], v[242:245], v[64:67]
	s_setprio 0
	s_barrier
	s_mov_b32 m0, s27
	s_add_u32 s54, s2, 0x40000
	s_addc_u32 s55, s3, 0
	ds_read_b128 v[214:217], v173 offset:16384
	ds_read_b128 v[218:221], v173 offset:17408
	ds_read_b128 v[222:225], v173 offset:18432
	ds_read_b128 v[226:229], v173 offset:19456
	ds_read_b128 v[230:233], v173 offset:20480
	ds_read_b128 v[234:237], v173 offset:21504
	ds_read_b128 v[238:241], v173 offset:22528
	ds_read_b128 v[242:245], v173 offset:23552
	global_load_lds_dwordx4 v132, s[2:3]
	s_mov_b32 m0, s28
	s_nop 0
	global_load_lds_dwordx4 v128, s[2:3]
	s_mov_b32 m0, s29
	s_nop 0
	global_load_lds_dwordx4 v132, s[54:55]
	s_mov_b32 m0, s30
	s_nop 0
	global_load_lds_dwordx4 v128, s[54:55]
	s_mov_b32 m0, s6
	s_nop 0
	global_load_lds_dwordx4 v134, s[4:5]
	s_mov_b32 m0, s31
	s_nop 0
	global_load_lds_dwordx4 v130, s[4:5]
	s_waitcnt vmcnt(8)
	s_waitcnt lgkmcnt(0)
	s_barrier
	s_setprio 1
	v_mfma_f32_16x16x32_bf16 v[60:63], v[140:143], v[214:217], 0
	v_mfma_f32_16x16x32_bf16 v[60:63], v[162:165], v[218:221], v[60:63]
	v_mfma_f32_16x16x32_bf16 v[56:59], v[166:169], v[214:217], 0
	v_mfma_f32_16x16x32_bf16 v[56:59], v[176:179], v[218:221], v[56:59]
	v_mfma_f32_16x16x32_bf16 v[48:51], v[140:143], v[222:225], 0
	v_mfma_f32_16x16x32_bf16 v[48:51], v[162:165], v[226:229], v[48:51]
	v_mfma_f32_16x16x32_bf16 v[40:43], v[166:169], v[222:225], 0
	v_mfma_f32_16x16x32_bf16 v[40:43], v[176:179], v[226:229], v[40:43]
	v_mfma_f32_16x16x32_bf16 v[32:35], v[140:143], v[230:233], 0
	v_mfma_f32_16x16x32_bf16 v[32:35], v[162:165], v[234:237], v[32:35]
	v_mfma_f32_16x16x32_bf16 v[24:27], v[166:169], v[230:233], 0
	v_mfma_f32_16x16x32_bf16 v[24:27], v[176:179], v[234:237], v[24:27]
	v_mfma_f32_16x16x32_bf16 v[16:19], v[140:143], v[238:241], 0
	v_mfma_f32_16x16x32_bf16 v[16:19], v[162:165], v[242:245], v[16:19]
	v_mfma_f32_16x16x32_bf16 v[8:11], v[166:169], v[238:241], 0
	v_mfma_f32_16x16x32_bf16 v[8:11], v[176:179], v[242:245], v[8:11]
	v_mfma_f32_16x16x32_bf16 v[52:55], v[180:183], v[214:217], 0
	v_mfma_f32_16x16x32_bf16 v[52:55], v[184:187], v[218:221], v[52:55]
	v_mfma_f32_16x16x32_bf16 v[44:47], v[188:191], v[214:217], 0
	v_mfma_f32_16x16x32_bf16 v[44:47], v[210:213], v[218:221], v[44:47]
	v_mfma_f32_16x16x32_bf16 v[36:39], v[180:183], v[222:225], 0
	v_mfma_f32_16x16x32_bf16 v[36:39], v[184:187], v[226:229], v[36:39]
	v_mfma_f32_16x16x32_bf16 v[28:31], v[188:191], v[222:225], 0
	v_mfma_f32_16x16x32_bf16 v[28:31], v[210:213], v[226:229], v[28:31]
	v_mfma_f32_16x16x32_bf16 v[20:23], v[180:183], v[230:233], 0
	v_mfma_f32_16x16x32_bf16 v[20:23], v[184:187], v[234:237], v[20:23]
	v_mfma_f32_16x16x32_bf16 v[12:15], v[188:191], v[230:233], 0
	v_mfma_f32_16x16x32_bf16 v[12:15], v[210:213], v[234:237], v[12:15]
	v_mfma_f32_16x16x32_bf16 v[4:7], v[180:183], v[238:241], 0
	v_mfma_f32_16x16x32_bf16 v[4:7], v[184:187], v[242:245], v[4:7]
	v_mfma_f32_16x16x32_bf16 v[0:3], v[188:191], v[238:241], 0
	v_mfma_f32_16x16x32_bf16 v[0:3], v[210:213], v[242:245], v[0:3]
	s_setprio 0
	s_barrier
; #define PG8_STAGE(bufoff, gbase, voff) do { _Pragma("unroll") for (int _i = 0; _i < 2; ++_i) \
;         __builtin_amdgcn_global_load_lds((const unsigned*)((const char*)(gbase) + (voff)[_i]), (PG8_LAS unsigned*)(lds + (bufoff) + ldsw + _i * 8192), 16, 0, 0); } while (0)
; #define PG8_LDA(dst, b, h) do { _Pragma("unroll") for (int m = 0; m < 4; ++m) _Pragma("unroll") for (int k = 0; k < 2; ++k) dst[m][k] = *(const PG8_LAS bf16x8*)(lds + PG8_SA(b, h) + aoff + m * 2048 + k * 1024); } while (0)
; #define PG8_LDB(dst, b, h) do { _Pragma("unroll") for (int n = 0; n < 2; ++n) _Pragma("unroll") for (int k = 0; k < 2; ++k) dst[n][k] = *(const PG8_LAS bf16x8*)(lds + PG8_SB(b, h) + boff + n * 2048 + k * 1024); } while (0)
; #define PG8_MMA(ai, bj, At, Bt) do { __builtin_amdgcn_s_setprio(1); _Pragma("unroll") for (int m = 0; m < 4; ++m) _Pragma("unroll") for (int n = 0; n < 2; ++n) _Pragma("unroll") for (int k = 0; k < 2; ++k) \
;         acc[ai][bj][m][n] = __builtin_amdgcn_mfma_f32_16x16x32_bf16(Bt[n][k], At[m][k], acc[ai][bj][m][n], 0, 0, 0); __builtin_amdgcn_s_setprio(0); } while (0)
; #define PG8_WAIT_V(n) asm volatile("s_waitcnt vmcnt(" #n ")" ::: "memory")
; #define PG8_WAIT_L(n) asm volatile("s_waitcnt lgkmcnt(" #n ")" ::: "memory")
; #define PG8_BAR __builtin_amdgcn_s_barrier()
; #define PG8_SCHED __builtin_amdgcn_sched_barrier(0)
; template <class Epi, class Sched, bool ALIGN_EPI = false, bool SP2 = false>
; __device__ __forceinline__ void gemm_phase(PG8_LAS unsigned char* lds, const Gemm g, const Sched& S, const Epi& E) {
;     ...
;             PG8_LDB(B0, 1, 0); PG8_LDB(B1, 1, 1); PG8_SCHED; PG8_LDA(At, 1, 0); PG8_STAGE(PG8_SA(0, 1), a2 + hstep, voffA);
;             PG8_WAIT_V(8); PG8_WAIT_L(0); PG8_BAR; PG8_MMA(0, 0, At, B0); PG8_MMA(0, 1, At, B1); PG8_BAR; PG8_SCHED;
;             PG8_LDA(At, 1, 1); PG8_STAGE(PG8_SB(1, 0), b3, voffB); PG8_STAGE(PG8_SB(1, 1), b3 + hstep, voffB); PG8_STAGE(PG8_SA(1, 0), a3, voffA);
;             PG8_WAIT_V(8); PG8_WAIT_L(0); PG8_BAR; PG8_MMA(1, 0, At, B0); PG8_MMA(1, 1, At, B1); PG8_BAR; PG8_SCHED;
	ds_read_b128 v[140:143], v254 offset:32768
	ds_read_b128 v[162:165], v254 offset:33792
	ds_read_b128 v[166:169], v254 offset:34816
	ds_read_b128 v[176:179], v254 offset:35840
	ds_read_b128 v[180:183], v254 offset:49152
	ds_read_b128 v[184:187], v254 offset:50176
	ds_read_b128 v[188:191], v254 offset:51200
	ds_read_b128 v[210:213], v254 offset:52224
	s_add_u32 s4, s4, 0x40000
	s_addc_u32 s5, s5, 0
	s_mov_b32 m0, s33
	ds_read_b128 v[214:217], v173 offset:32768
	ds_read_b128 v[218:221], v173 offset:33792
	ds_read_b128 v[222:225], v173 offset:34816
	ds_read_b128 v[226:229], v173 offset:35840
	ds_read_b128 v[230:233], v173 offset:36864
	ds_read_b128 v[234:237], v173 offset:37888
	ds_read_b128 v[238:241], v173 offset:38912
	ds_read_b128 v[242:245], v173 offset:39936
	global_load_lds_dwordx4 v134, s[4:5]
	s_mov_b32 m0, s34
	s_nop 0
	global_load_lds_dwordx4 v130, s[4:5]
	s_waitcnt vmcnt(8)
	s_waitcnt lgkmcnt(0)
	s_barrier
	s_setprio 1
	v_mfma_f32_16x16x32_bf16 v[124:127], v[140:143], v[214:217], v[124:127]
	v_mfma_f32_16x16x32_bf16 v[124:127], v[162:165], v[218:221], v[124:127]
	v_mfma_f32_16x16x32_bf16 v[120:123], v[166:169], v[214:217], v[120:123]
	v_mfma_f32_16x16x32_bf16 v[120:123], v[176:179], v[218:221], v[120:123]
	v_mfma_f32_16x16x32_bf16 v[112:115], v[140:143], v[222:225], v[112:115]
	v_mfma_f32_16x16x32_bf16 v[112:115], v[162:165], v[226:229], v[112:115]
	v_mfma_f32_16x16x32_bf16 v[104:107], v[166:169], v[222:225], v[104:107]
	v_mfma_f32_16x16x32_bf16 v[104:107], v[176:179], v[226:229], v[104:107]
	v_mfma_f32_16x16x32_bf16 v[96:99], v[140:143], v[230:233], v[96:99]
	v_mfma_f32_16x16x32_bf16 v[96:99], v[162:165], v[234:237], v[96:99]
	v_mfma_f32_16x16x32_bf16 v[88:91], v[166:169], v[230:233], v[88:91]
	v_mfma_f32_16x16x32_bf16 v[88:91], v[176:179], v[234:237], v[88:91]
	v_mfma_f32_16x16x32_bf16 v[80:83], v[140:143], v[238:241], v[80:83]
	v_mfma_f32_16x16x32_bf16 v[80:83], v[162:165], v[242:245], v[80:83]
	v_mfma_f32_16x16x32_bf16 v[72:75], v[166:169], v[238:241], v[72:75]
	v_mfma_f32_16x16x32_bf16 v[72:75], v[176:179], v[242:245], v[72:75]
	v_mfma_f32_16x16x32_bf16 v[116:119], v[180:183], v[214:217], v[116:119]
	v_mfma_f32_16x16x32_bf16 v[116:119], v[184:187], v[218:221], v[116:119]
	v_mfma_f32_16x16x32_bf16 v[108:111], v[188:191], v[214:217], v[108:111]
	v_mfma_f32_16x16x32_bf16 v[108:111], v[210:213], v[218:221], v[108:111]
	v_mfma_f32_16x16x32_bf16 v[100:103], v[180:183], v[222:225], v[100:103]
	v_mfma_f32_16x16x32_bf16 v[100:103], v[184:187], v[226:229], v[100:103]
	v_mfma_f32_16x16x32_bf16 v[92:95], v[188:191], v[222:225], v[92:95]
	v_mfma_f32_16x16x32_bf16 v[92:95], v[210:213], v[226:229], v[92:95]
	v_mfma_f32_16x16x32_bf16 v[84:87], v[180:183], v[230:233], v[84:87]
	v_mfma_f32_16x16x32_bf16 v[84:87], v[184:187], v[234:237], v[84:87]
	v_mfma_f32_16x16x32_bf16 v[76:79], v[188:191], v[230:233], v[76:79]
	v_mfma_f32_16x16x32_bf16 v[76:79], v[210:213], v[234:237], v[76:79]
	v_mfma_f32_16x16x32_bf16 v[68:71], v[180:183], v[238:241], v[68:71]
	v_mfma_f32_16x16x32_bf16 v[68:71], v[184:187], v[242:245], v[68:71]
	v_mfma_f32_16x16x32_bf16 v[64:67], v[188:191], v[238:241], v[64:67]
	v_mfma_f32_16x16x32_bf16 v[64:67], v[210:213], v[242:245], v[64:67]
	s_setprio 0
	s_barrier
	s_mov_b32 m0, s37
	s_add_u32 s2, s2, 0x40080
	s_addc_u32 s3, s3, 0
	ds_read_b128 v[214:217], v173 offset:49152
	ds_read_b128 v[218:221], v173 offset:50176
	ds_read_b128 v[222:225], v173 offset:51200
	ds_read_b128 v[226:229], v173 offset:52224
	ds_read_b128 v[230:233], v173 offset:53248
	ds_read_b128 v[234:237], v173 offset:54272
	ds_read_b128 v[238:241], v173 offset:55296
	ds_read_b128 v[242:245], v173 offset:56320
	s_add_u32 s98, s2, 0xfffc0000
	s_addc_u32 s99, s3, -1
	global_load_lds_dwordx4 v132, s[98:99]
	s_mov_b32 m0, s38
	s_nop 0
	global_load_lds_dwordx4 v128, s[98:99]
	s_mov_b32 m0, s41
	s_nop 0
	global_load_lds_dwordx4 v132, s[2:3]
	s_mov_b32 m0, s42
	s_nop 0
	global_load_lds_dwordx4 v128, s[2:3]
	s_mov_b32 m0, s39
	s_nop 0
	s_add_u32 s100, s4, 0xfffc0080
	s_addc_u32 s101, s5, -1
	global_load_lds_dwordx4 v134, s[100:101]
	s_mov_b32 m0, s40
	s_nop 0
	global_load_lds_dwordx4 v130, s[100:101]
	s_waitcnt vmcnt(8)
	s_waitcnt lgkmcnt(0)
	s_barrier
	s_setprio 1
	v_mfma_f32_16x16x32_bf16 v[60:63], v[140:143], v[214:217], v[60:63]
	v_mfma_f32_16x16x32_bf16 v[60:63], v[162:165], v[218:221], v[60:63]
	v_mfma_f32_16x16x32_bf16 v[56:59], v[166:169], v[214:217], v[56:59]
	v_mfma_f32_16x16x32_bf16 v[56:59], v[176:179], v[218:221], v[56:59]
	v_mfma_f32_16x16x32_bf16 v[48:51], v[140:143], v[222:225], v[48:51]
	v_mfma_f32_16x16x32_bf16 v[48:51], v[162:165], v[226:229], v[48:51]
	v_mfma_f32_16x16x32_bf16 v[40:43], v[166:169], v[222:225], v[40:43]
	v_mfma_f32_16x16x32_bf16 v[40:43], v[176:179], v[226:229], v[40:43]
	v_mfma_f32_16x16x32_bf16 v[32:35], v[140:143], v[230:233], v[32:35]
	v_mfma_f32_16x16x32_bf16 v[32:35], v[162:165], v[234:237], v[32:35]
	v_mfma_f32_16x16x32_bf16 v[24:27], v[166:169], v[230:233], v[24:27]
	v_mfma_f32_16x16x32_bf16 v[24:27], v[176:179], v[234:237], v[24:27]
	v_mfma_f32_16x16x32_bf16 v[16:19], v[140:143], v[238:241], v[16:19]
	v_mfma_f32_16x16x32_bf16 v[16:19], v[162:165], v[242:245], v[16:19]
	v_mfma_f32_16x16x32_bf16 v[8:11], v[166:169], v[238:241], v[8:11]
	v_mfma_f32_16x16x32_bf16 v[8:11], v[176:179], v[242:245], v[8:11]
	v_mfma_f32_16x16x32_bf16 v[52:55], v[180:183], v[214:217], v[52:55]
	v_mfma_f32_16x16x32_bf16 v[52:55], v[184:187], v[218:221], v[52:55]
	v_mfma_f32_16x16x32_bf16 v[44:47], v[188:191], v[214:217], v[44:47]
	v_mfma_f32_16x16x32_bf16 v[44:47], v[210:213], v[218:221], v[44:47]
	v_mfma_f32_16x16x32_bf16 v[36:39], v[180:183], v[222:225], v[36:39]
	v_mfma_f32_16x16x32_bf16 v[36:39], v[184:187], v[226:229], v[36:39]
	v_mfma_f32_16x16x32_bf16 v[28:31], v[188:191], v[222:225], v[28:31]
	v_mfma_f32_16x16x32_bf16 v[28:31], v[210:213], v[226:229], v[28:31]
	v_mfma_f32_16x16x32_bf16 v[20:23], v[180:183], v[230:233], v[20:23]
	v_mfma_f32_16x16x32_bf16 v[20:23], v[184:187], v[234:237], v[20:23]
	v_mfma_f32_16x16x32_bf16 v[12:15], v[188:191], v[230:233], v[12:15]
	v_mfma_f32_16x16x32_bf16 v[12:15], v[210:213], v[234:237], v[12:15]
	v_mfma_f32_16x16x32_bf16 v[4:7], v[180:183], v[238:241], v[4:7]
	v_mfma_f32_16x16x32_bf16 v[4:7], v[184:187], v[242:245], v[4:7]
	v_mfma_f32_16x16x32_bf16 v[0:3], v[188:191], v[238:241], v[0:3]
	v_mfma_f32_16x16x32_bf16 v[0:3], v[210:213], v[242:245], v[0:3]
	s_setprio 0
	s_barrier
	s_add_i32 s52, s52, 2
	s_add_u32 s0, s0, 0x100
	s_addc_u32 s1, s1, 0
	s_add_u32 s50, s50, 0x100
	s_addc_u32 s51, s51, 0
	s_cmp_gt_u32 s52, 13
; #define PG8_STAGE(bufoff, gbase, voff) do { _Pragma("unroll") for (int _i = 0; _i < 2; ++_i) \
;         __builtin_amdgcn_global_load_lds((const unsigned*)((const char*)(gbase) + (voff)[_i]), (PG8_LAS unsigned*)(lds + (bufoff) + ldsw + _i * 8192), 16, 0, 0); } while (0)
; #define PG8_LDA(dst, b, h) do { _Pragma("unroll") for (int m = 0; m < 4; ++m) _Pragma("unroll") for (int k = 0; k < 2; ++k) dst[m][k] = *(const PG8_LAS bf16x8*)(lds + PG8_SA(b, h) + aoff + m * 2048 + k * 1024); } while (0)
; #define PG8_LDB(dst, b, h) do { _Pragma("unroll") for (int n = 0; n < 2; ++n) _Pragma("unroll") for (int k = 0; k < 2; ++k) dst[n][k] = *(const PG8_LAS bf16x8*)(lds + PG8_SB(b, h) + boff + n * 2048 + k * 1024); } while (0)
; #define PG8_MMA(ai, bj, At, Bt) do { __builtin_amdgcn_s_setprio(1); _Pragma("unroll") for (int m = 0; m < 4; ++m) _Pragma("unroll") for (int n = 0; n < 2; ++n) _Pragma("unroll") for (int k = 0; k < 2; ++k) \
;         acc[ai][bj][m][n] = __builtin_amdgcn_mfma_f32_16x16x32_bf16(Bt[n][k], At[m][k], acc[ai][bj][m][n], 0, 0, 0); __builtin_amdgcn_s_setprio(0); } while (0)
; #define PG8_WAIT_V(n) asm volatile("s_waitcnt vmcnt(" #n ")" ::: "memory")
; #define PG8_WAIT_L(n) asm volatile("s_waitcnt lgkmcnt(" #n ")" ::: "memory")
; #define PG8_BAR __builtin_amdgcn_s_barrier()
; template <class Epi, class Sched, bool ALIGN_EPI = false, bool SP2 = false>
; __device__ __forceinline__ void gemm_phase(PG8_LAS unsigned char* lds, const Gemm g, const Sched& S, const Epi& E) {
;     ...
;             const char* a1 = cA + (size_t)(t + 1) * kstep;
;             const char* a2 = last ? nA : cA + (size_t)(t + 2) * kstep; const char* b2 = last ? nB : cB + (size_t)(t + 2) * kstep;
;             const char* a3 = a2 + kstep; const char* b3 = b2 + kstep;
;             if (last && has_next) S.a_ready(nxt);
;             if constexpr (SP2) {
;             PG8_LDB(B0, 0, 0); PG8_LDB(B1, 0, 1); PG8_SCHED; PG8_LDA(At, 0, 0); PG8_STAGE(PG8_SA(1, 1), a1 + hstep, voffA);
;             PG8_WAIT_V(8); PG8_WAIT_L(0); PG8_BAR; PG8_MMA(0, 0, At, B0); PG8_MMA(0, 1, At, B1); PG8_BAR; PG8_SCHED;
;             PG8_LDA(At, 0, 1); PG8_STAGE(PG8_SB(0, 0), b2, voffB); PG8_STAGE(PG8_SB(0, 1), b2 + hstep, voffB); PG8_STAGE(PG8_SA(0, 0), a2, voffA);
;             PG8_WAIT_V(8); PG8_WAIT_L(0); PG8_BAR; PG8_MMA(1, 0, At, B0); PG8_MMA(1, 1, At, B1); PG8_BAR; PG8_SCHED;
.LBB0_792:
	s_waitcnt lgkmcnt(0)
	ds_read_b128 v[140:143], v254
	ds_read_b128 v[162:165], v254 offset:1024
	ds_read_b128 v[166:169], v254 offset:2048
	ds_read_b128 v[176:179], v254 offset:3072
	ds_read_b128 v[180:183], v254 offset:16384
	ds_read_b128 v[184:187], v254 offset:17408
	ds_read_b128 v[188:191], v254 offset:18432
	ds_read_b128 v[210:213], v254 offset:19456
	s_add_u32 s2, s0, 0xfffc0080
	s_addc_u32 s3, s1, -1
	s_cmp_eq_u32 s52, 12
	s_cselect_b32 s5, s17, s3
	s_cselect_b32 s4, s48, s2
	s_cselect_b32 s3, s15, s51
	s_cselect_b32 s2, s49, s50
	s_add_i32 m0, s6, 0xc000
	ds_read_b128 v[214:217], v173
	ds_read_b128 v[218:221], v173 offset:1024
	ds_read_b128 v[222:225], v173 offset:2048
	ds_read_b128 v[226:229], v173 offset:3072
	ds_read_b128 v[230:233], v173 offset:4096
	ds_read_b128 v[234:237], v173 offset:5120
	ds_read_b128 v[238:241], v173 offset:6144
	ds_read_b128 v[242:245], v173 offset:7168
	global_load_lds_dwordx4 v136, s[0:1]
	s_add_i32 m0, s6, 0xe000
	s_nop 0
	global_load_lds_dwordx4 v138, s[0:1]
	s_waitcnt vmcnt(8)
	s_waitcnt lgkmcnt(0)
	s_barrier
	s_setprio 1
	v_mfma_f32_16x16x32_bf16 v[124:127], v[140:143], v[214:217], v[124:127]
	v_mfma_f32_16x16x32_bf16 v[124:127], v[162:165], v[218:221], v[124:127]
	v_mfma_f32_16x16x32_bf16 v[120:123], v[166:169], v[214:217], v[120:123]
	v_mfma_f32_16x16x32_bf16 v[120:123], v[176:179], v[218:221], v[120:123]
	v_mfma_f32_16x16x32_bf16 v[112:115], v[140:143], v[222:225], v[112:115]
	v_mfma_f32_16x16x32_bf16 v[112:115], v[162:165], v[226:229], v[112:115]
	v_mfma_f32_16x16x32_bf16 v[104:107], v[166:169], v[222:225], v[104:107]
	v_mfma_f32_16x16x32_bf16 v[104:107], v[176:179], v[226:229], v[104:107]
	v_mfma_f32_16x16x32_bf16 v[96:99], v[140:143], v[230:233], v[96:99]
	v_mfma_f32_16x16x32_bf16 v[96:99], v[162:165], v[234:237], v[96:99]
	v_mfma_f32_16x16x32_bf16 v[88:91], v[166:169], v[230:233], v[88:91]
	v_mfma_f32_16x16x32_bf16 v[88:91], v[176:179], v[234:237], v[88:91]
	v_mfma_f32_16x16x32_bf16 v[80:83], v[140:143], v[238:241], v[80:83]
	v_mfma_f32_16x16x32_bf16 v[80:83], v[162:165], v[242:245], v[80:83]
	v_mfma_f32_16x16x32_bf16 v[72:75], v[166:169], v[238:241], v[72:75]
	v_mfma_f32_16x16x32_bf16 v[72:75], v[176:179], v[242:245], v[72:75]
	v_mfma_f32_16x16x32_bf16 v[116:119], v[180:183], v[214:217], v[116:119]
	v_mfma_f32_16x16x32_bf16 v[116:119], v[184:187], v[218:221], v[116:119]
	v_mfma_f32_16x16x32_bf16 v[108:111], v[188:191], v[214:217], v[108:111]
	v_mfma_f32_16x16x32_bf16 v[108:111], v[210:213], v[218:221], v[108:111]
	v_mfma_f32_16x16x32_bf16 v[100:103], v[180:183], v[222:225], v[100:103]
	v_mfma_f32_16x16x32_bf16 v[100:103], v[184:187], v[226:229], v[100:103]
	v_mfma_f32_16x16x32_bf16 v[92:95], v[188:191], v[222:225], v[92:95]
	v_mfma_f32_16x16x32_bf16 v[92:95], v[210:213], v[226:229], v[92:95]
	v_mfma_f32_16x16x32_bf16 v[84:87], v[180:183], v[230:233], v[84:87]
	v_mfma_f32_16x16x32_bf16 v[84:87], v[184:187], v[234:237], v[84:87]
	v_mfma_f32_16x16x32_bf16 v[76:79], v[188:191], v[230:233], v[76:79]
	v_mfma_f32_16x16x32_bf16 v[76:79], v[210:213], v[234:237], v[76:79]
	v_mfma_f32_16x16x32_bf16 v[68:71], v[180:183], v[238:241], v[68:71]
	v_mfma_f32_16x16x32_bf16 v[68:71], v[184:187], v[242:245], v[68:71]
	v_mfma_f32_16x16x32_bf16 v[64:67], v[188:191], v[238:241], v[64:67]
	v_mfma_f32_16x16x32_bf16 v[64:67], v[210:213], v[242:245], v[64:67]
	s_setprio 0
	s_barrier
	s_mov_b32 m0, s27
	s_add_u32 s54, s2, 0x40000
	s_addc_u32 s55, s3, 0
	ds_read_b128 v[214:217], v173 offset:16384
	ds_read_b128 v[218:221], v173 offset:17408
	ds_read_b128 v[222:225], v173 offset:18432
	ds_read_b128 v[226:229], v173 offset:19456
	ds_read_b128 v[230:233], v173 offset:20480
	ds_read_b128 v[234:237], v173 offset:21504
	ds_read_b128 v[238:241], v173 offset:22528
	ds_read_b128 v[242:245], v173 offset:23552
	global_load_lds_dwordx4 v132, s[2:3]
	s_mov_b32 m0, s28
	s_nop 0
	global_load_lds_dwordx4 v128, s[2:3]
	s_mov_b32 m0, s29
	s_nop 0
	global_load_lds_dwordx4 v132, s[54:55]
	s_mov_b32 m0, s30
	s_nop 0
	global_load_lds_dwordx4 v128, s[54:55]
	s_mov_b32 m0, s6
	s_nop 0
	global_load_lds_dwordx4 v134, s[4:5]
	s_mov_b32 m0, s31
	s_nop 0
	global_load_lds_dwordx4 v130, s[4:5]
	s_waitcnt vmcnt(8)
	s_waitcnt lgkmcnt(0)
	s_barrier
	s_setprio 1
	v_mfma_f32_16x16x32_bf16 v[60:63], v[140:143], v[214:217], v[60:63]
	v_mfma_f32_16x16x32_bf16 v[60:63], v[162:165], v[218:221], v[60:63]
	v_mfma_f32_16x16x32_bf16 v[56:59], v[166:169], v[214:217], v[56:59]
	v_mfma_f32_16x16x32_bf16 v[56:59], v[176:179], v[218:221], v[56:59]
	v_mfma_f32_16x16x32_bf16 v[48:51], v[140:143], v[222:225], v[48:51]
	v_mfma_f32_16x16x32_bf16 v[48:51], v[162:165], v[226:229], v[48:51]
	v_mfma_f32_16x16x32_bf16 v[40:43], v[166:169], v[222:225], v[40:43]
	v_mfma_f32_16x16x32_bf16 v[40:43], v[176:179], v[226:229], v[40:43]
	v_mfma_f32_16x16x32_bf16 v[32:35], v[140:143], v[230:233], v[32:35]
	v_mfma_f32_16x16x32_bf16 v[32:35], v[162:165], v[234:237], v[32:35]
	v_mfma_f32_16x16x32_bf16 v[24:27], v[166:169], v[230:233], v[24:27]
	v_mfma_f32_16x16x32_bf16 v[24:27], v[176:179], v[234:237], v[24:27]
	v_mfma_f32_16x16x32_bf16 v[16:19], v[140:143], v[238:241], v[16:19]
	v_mfma_f32_16x16x32_bf16 v[16:19], v[162:165], v[242:245], v[16:19]
	v_mfma_f32_16x16x32_bf16 v[8:11], v[166:169], v[238:241], v[8:11]
	v_mfma_f32_16x16x32_bf16 v[8:11], v[176:179], v[242:245], v[8:11]
	v_mfma_f32_16x16x32_bf16 v[52:55], v[180:183], v[214:217], v[52:55]
	v_mfma_f32_16x16x32_bf16 v[52:55], v[184:187], v[218:221], v[52:55]
	v_mfma_f32_16x16x32_bf16 v[44:47], v[188:191], v[214:217], v[44:47]
	v_mfma_f32_16x16x32_bf16 v[44:47], v[210:213], v[218:221], v[44:47]
	v_mfma_f32_16x16x32_bf16 v[36:39], v[180:183], v[222:225], v[36:39]
	v_mfma_f32_16x16x32_bf16 v[36:39], v[184:187], v[226:229], v[36:39]
	v_mfma_f32_16x16x32_bf16 v[28:31], v[188:191], v[222:225], v[28:31]
	v_mfma_f32_16x16x32_bf16 v[28:31], v[210:213], v[226:229], v[28:31]
	v_mfma_f32_16x16x32_bf16 v[20:23], v[180:183], v[230:233], v[20:23]
	v_mfma_f32_16x16x32_bf16 v[20:23], v[184:187], v[234:237], v[20:23]
	v_mfma_f32_16x16x32_bf16 v[12:15], v[188:191], v[230:233], v[12:15]
	v_mfma_f32_16x16x32_bf16 v[12:15], v[210:213], v[234:237], v[12:15]
	v_mfma_f32_16x16x32_bf16 v[4:7], v[180:183], v[238:241], v[4:7]
	v_mfma_f32_16x16x32_bf16 v[4:7], v[184:187], v[242:245], v[4:7]
	v_mfma_f32_16x16x32_bf16 v[0:3], v[188:191], v[238:241], v[0:3]
	v_mfma_f32_16x16x32_bf16 v[0:3], v[210:213], v[242:245], v[0:3]
	s_setprio 0
	s_barrier
; #define PG8_STAGE(bufoff, gbase, voff) do { _Pragma("unroll") for (int _i = 0; _i < 2; ++_i) \
;         __builtin_amdgcn_global_load_lds((const unsigned*)((const char*)(gbase) + (voff)[_i]), (PG8_LAS unsigned*)(lds + (bufoff) + ldsw + _i * 8192), 16, 0, 0); } while (0)
; #define PG8_LDA(dst, b, h) do { _Pragma("unroll") for (int m = 0; m < 4; ++m) _Pragma("unroll") for (int k = 0; k < 2; ++k) dst[m][k] = *(const PG8_LAS bf16x8*)(lds + PG8_SA(b, h) + aoff + m * 2048 + k * 1024); } while (0)
; #define PG8_LDB(dst, b, h) do { _Pragma("unroll") for (int n = 0; n < 2; ++n) _Pragma("unroll") for (int k = 0; k < 2; ++k) dst[n][k] = *(const PG8_LAS bf16x8*)(lds + PG8_SB(b, h) + boff + n * 2048 + k * 1024); } while (0)
; #define PG8_MMA(ai, bj, At, Bt) do { __builtin_amdgcn_s_setprio(1); _Pragma("unroll") for (int m = 0; m < 4; ++m) _Pragma("unroll") for (int n = 0; n < 2; ++n) _Pragma("unroll") for (int k = 0; k < 2; ++k) \
;         acc[ai][bj][m][n] = __builtin_amdgcn_mfma_f32_16x16x32_bf16(Bt[n][k], At[m][k], acc[ai][bj][m][n], 0, 0, 0); __builtin_amdgcn_s_setprio(0); } while (0)
; #define PG8_WAIT_V(n) asm volatile("s_waitcnt vmcnt(" #n ")" ::: "memory")
; #define PG8_WAIT_L(n) asm volatile("s_waitcnt lgkmcnt(" #n ")" ::: "memory")
; #define PG8_BAR __builtin_amdgcn_s_barrier()
; #define PG8_SCHED __builtin_amdgcn_sched_barrier(0)
; template <class Epi, class Sched, bool ALIGN_EPI = false, bool SP2 = false>
; __device__ __forceinline__ void gemm_phase(PG8_LAS unsigned char* lds, const Gemm g, const Sched& S, const Epi& E) {
;     ...
;             PG8_LDB(B0, 1, 0); PG8_LDB(B1, 1, 1); PG8_SCHED; PG8_LDA(At, 1, 0); PG8_STAGE(PG8_SA(0, 1), a2 + hstep, voffA);
;             PG8_WAIT_V(8); PG8_WAIT_L(0); PG8_BAR; PG8_MMA(0, 0, At, B0); PG8_MMA(0, 1, At, B1); PG8_BAR; PG8_SCHED;
;             PG8_LDA(At, 1, 1); PG8_STAGE(PG8_SB(1, 0), b3, voffB); PG8_STAGE(PG8_SB(1, 1), b3 + hstep, voffB); PG8_STAGE(PG8_SA(1, 0), a3, voffA);
;             PG8_WAIT_V(8); PG8_WAIT_L(0); PG8_BAR; PG8_MMA(1, 0, At, B0); PG8_MMA(1, 1, At, B1); PG8_BAR; PG8_SCHED;
	ds_read_b128 v[140:143], v254 offset:32768
	ds_read_b128 v[162:165], v254 offset:33792
	ds_read_b128 v[166:169], v254 offset:34816
	ds_read_b128 v[176:179], v254 offset:35840
	ds_read_b128 v[180:183], v254 offset:49152
	ds_read_b128 v[184:187], v254 offset:50176
	ds_read_b128 v[188:191], v254 offset:51200
	ds_read_b128 v[210:213], v254 offset:52224
	s_add_u32 s4, s4, 0x40000
	s_addc_u32 s5, s5, 0
	s_mov_b32 m0, s33
	ds_read_b128 v[214:217], v173 offset:32768
	ds_read_b128 v[218:221], v173 offset:33792
	ds_read_b128 v[222:225], v173 offset:34816
	ds_read_b128 v[226:229], v173 offset:35840
	ds_read_b128 v[230:233], v173 offset:36864
	ds_read_b128 v[234:237], v173 offset:37888
	ds_read_b128 v[238:241], v173 offset:38912
	ds_read_b128 v[242:245], v173 offset:39936
	global_load_lds_dwordx4 v134, s[4:5]
	s_mov_b32 m0, s34
	s_nop 0
	global_load_lds_dwordx4 v130, s[4:5]
	s_waitcnt vmcnt(8)
	s_waitcnt lgkmcnt(0)
	s_barrier
	s_setprio 1
	v_mfma_f32_16x16x32_bf16 v[124:127], v[140:143], v[214:217], v[124:127]
	v_mfma_f32_16x16x32_bf16 v[124:127], v[162:165], v[218:221], v[124:127]
	v_mfma_f32_16x16x32_bf16 v[120:123], v[166:169], v[214:217], v[120:123]
	v_mfma_f32_16x16x32_bf16 v[120:123], v[176:179], v[218:221], v[120:123]
	v_mfma_f32_16x16x32_bf16 v[112:115], v[140:143], v[222:225], v[112:115]
	v_mfma_f32_16x16x32_bf16 v[112:115], v[162:165], v[226:229], v[112:115]
	v_mfma_f32_16x16x32_bf16 v[104:107], v[166:169], v[222:225], v[104:107]
	v_mfma_f32_16x16x32_bf16 v[104:107], v[176:179], v[226:229], v[104:107]
	v_mfma_f32_16x16x32_bf16 v[96:99], v[140:143], v[230:233], v[96:99]
	v_mfma_f32_16x16x32_bf16 v[96:99], v[162:165], v[234:237], v[96:99]
	v_mfma_f32_16x16x32_bf16 v[88:91], v[166:169], v[230:233], v[88:91]
	v_mfma_f32_16x16x32_bf16 v[88:91], v[176:179], v[234:237], v[88:91]
	v_mfma_f32_16x16x32_bf16 v[80:83], v[140:143], v[238:241], v[80:83]
	v_mfma_f32_16x16x32_bf16 v[80:83], v[162:165], v[242:245], v[80:83]
	v_mfma_f32_16x16x32_bf16 v[72:75], v[166:169], v[238:241], v[72:75]
	v_mfma_f32_16x16x32_bf16 v[72:75], v[176:179], v[242:245], v[72:75]
	v_mfma_f32_16x16x32_bf16 v[116:119], v[180:183], v[214:217], v[116:119]
	v_mfma_f32_16x16x32_bf16 v[116:119], v[184:187], v[218:221], v[116:119]
	v_mfma_f32_16x16x32_bf16 v[108:111], v[188:191], v[214:217], v[108:111]
	v_mfma_f32_16x16x32_bf16 v[108:111], v[210:213], v[218:221], v[108:111]
	v_mfma_f32_16x16x32_bf16 v[100:103], v[180:183], v[222:225], v[100:103]
	v_mfma_f32_16x16x32_bf16 v[100:103], v[184:187], v[226:229], v[100:103]
	v_mfma_f32_16x16x32_bf16 v[92:95], v[188:191], v[222:225], v[92:95]
	v_mfma_f32_16x16x32_bf16 v[92:95], v[210:213], v[226:229], v[92:95]
	v_mfma_f32_16x16x32_bf16 v[84:87], v[180:183], v[230:233], v[84:87]
	v_mfma_f32_16x16x32_bf16 v[84:87], v[184:187], v[234:237], v[84:87]
	v_mfma_f32_16x16x32_bf16 v[76:79], v[188:191], v[230:233], v[76:79]
	v_mfma_f32_16x16x32_bf16 v[76:79], v[210:213], v[234:237], v[76:79]
	v_mfma_f32_16x16x32_bf16 v[68:71], v[180:183], v[238:241], v[68:71]
	v_mfma_f32_16x16x32_bf16 v[68:71], v[184:187], v[242:245], v[68:71]
	v_mfma_f32_16x16x32_bf16 v[64:67], v[188:191], v[238:241], v[64:67]
	v_mfma_f32_16x16x32_bf16 v[64:67], v[210:213], v[242:245], v[64:67]
	s_setprio 0
	s_barrier
	s_mov_b32 m0, s37
	s_add_u32 s2, s2, 0x40080
	s_addc_u32 s3, s3, 0
	ds_read_b128 v[214:217], v173 offset:49152
	ds_read_b128 v[218:221], v173 offset:50176
	ds_read_b128 v[222:225], v173 offset:51200
	ds_read_b128 v[226:229], v173 offset:52224
	ds_read_b128 v[230:233], v173 offset:53248
	ds_read_b128 v[234:237], v173 offset:54272
	ds_read_b128 v[238:241], v173 offset:55296
	ds_read_b128 v[242:245], v173 offset:56320
	s_add_u32 s98, s2, 0xfffc0000
	s_addc_u32 s99, s3, -1
	global_load_lds_dwordx4 v132, s[98:99]
	s_mov_b32 m0, s38
	s_nop 0
	global_load_lds_dwordx4 v128, s[98:99]
	s_mov_b32 m0, s41
	s_nop 0
	global_load_lds_dwordx4 v132, s[2:3]
	s_mov_b32 m0, s42
	s_nop 0
	global_load_lds_dwordx4 v128, s[2:3]
	s_mov_b32 m0, s39
	s_nop 0
	s_add_u32 s100, s4, 0xfffc0080
	s_addc_u32 s101, s5, -1
	global_load_lds_dwordx4 v134, s[100:101]
	s_mov_b32 m0, s40
	s_nop 0
	global_load_lds_dwordx4 v130, s[100:101]
	s_waitcnt vmcnt(8)
	s_waitcnt lgkmcnt(0)
	s_barrier
	s_setprio 1
	v_mfma_f32_16x16x32_bf16 v[60:63], v[140:143], v[214:217], v[60:63]
	v_mfma_f32_16x16x32_bf16 v[60:63], v[162:165], v[218:221], v[60:63]
	v_mfma_f32_16x16x32_bf16 v[56:59], v[166:169], v[214:217], v[56:59]
	v_mfma_f32_16x16x32_bf16 v[56:59], v[176:179], v[218:221], v[56:59]
	v_mfma_f32_16x16x32_bf16 v[48:51], v[140:143], v[222:225], v[48:51]
	v_mfma_f32_16x16x32_bf16 v[48:51], v[162:165], v[226:229], v[48:51]
	v_mfma_f32_16x16x32_bf16 v[40:43], v[166:169], v[222:225], v[40:43]
	v_mfma_f32_16x16x32_bf16 v[40:43], v[176:179], v[226:229], v[40:43]
	v_mfma_f32_16x16x32_bf16 v[32:35], v[140:143], v[230:233], v[32:35]
	v_mfma_f32_16x16x32_bf16 v[32:35], v[162:165], v[234:237], v[32:35]
	v_mfma_f32_16x16x32_bf16 v[24:27], v[166:169], v[230:233], v[24:27]
	v_mfma_f32_16x16x32_bf16 v[24:27], v[176:179], v[234:237], v[24:27]
	v_mfma_f32_16x16x32_bf16 v[16:19], v[140:143], v[238:241], v[16:19]
	v_mfma_f32_16x16x32_bf16 v[16:19], v[162:165], v[242:245], v[16:19]
	v_mfma_f32_16x16x32_bf16 v[8:11], v[166:169], v[238:241], v[8:11]
	v_mfma_f32_16x16x32_bf16 v[8:11], v[176:179], v[242:245], v[8:11]
	v_mfma_f32_16x16x32_bf16 v[52:55], v[180:183], v[214:217], v[52:55]
	v_mfma_f32_16x16x32_bf16 v[52:55], v[184:187], v[218:221], v[52:55]
	v_mfma_f32_16x16x32_bf16 v[44:47], v[188:191], v[214:217], v[44:47]
	v_mfma_f32_16x16x32_bf16 v[44:47], v[210:213], v[218:221], v[44:47]
	v_mfma_f32_16x16x32_bf16 v[36:39], v[180:183], v[222:225], v[36:39]
	v_mfma_f32_16x16x32_bf16 v[36:39], v[184:187], v[226:229], v[36:39]
	v_mfma_f32_16x16x32_bf16 v[28:31], v[188:191], v[222:225], v[28:31]
	v_mfma_f32_16x16x32_bf16 v[28:31], v[210:213], v[226:229], v[28:31]
	v_mfma_f32_16x16x32_bf16 v[20:23], v[180:183], v[230:233], v[20:23]
	v_mfma_f32_16x16x32_bf16 v[20:23], v[184:187], v[234:237], v[20:23]
	v_mfma_f32_16x16x32_bf16 v[12:15], v[188:191], v[230:233], v[12:15]
	v_mfma_f32_16x16x32_bf16 v[12:15], v[210:213], v[234:237], v[12:15]
	v_mfma_f32_16x16x32_bf16 v[4:7], v[180:183], v[238:241], v[4:7]
	v_mfma_f32_16x16x32_bf16 v[4:7], v[184:187], v[242:245], v[4:7]
	v_mfma_f32_16x16x32_bf16 v[0:3], v[188:191], v[238:241], v[0:3]
	v_mfma_f32_16x16x32_bf16 v[0:3], v[210:213], v[242:245], v[0:3]
	s_setprio 0
	s_barrier
	s_add_i32 s52, s52, 2
	s_add_u32 s0, s0, 0x100
	s_addc_u32 s1, s1, 0
	s_add_u32 s50, s50, 0x100
	s_addc_u32 s51, s51, 0
	s_cmp_gt_u32 s52, 13
	s_cbranch_scc0 .LBB0_792
	s_and_b64 vcc, exec, s[12:13]
	s_cbranch_vccz .LBB0_795
	s_barrier

; #define PG8_STAGE(bufoff, gbase, voff) do { _Pragma("unroll") for (int _i = 0; _i < 2; ++_i) \
;         __builtin_amdgcn_global_load_lds((const unsigned*)((const char*)(gbase) + (voff)[_i]), (PG8_LAS unsigned*)(lds + (bufoff) + ldsw + _i * 8192), 16, 0, 0); } while (0)
; #define PG8_LDA(dst, b, h) do { _Pragma("unroll") for (int m = 0; m < 4; ++m) _Pragma("unroll") for (int k = 0; k < 2; ++k) dst[m][k] = *(const PG8_LAS bf16x8*)(lds + PG8_SA(b, h) + aoff + m * 2048 + k * 1024); } while (0)
; #define PG8_LDB(dst, b, h) do { _Pragma("unroll") for (int n = 0; n < 2; ++n) _Pragma("unroll") for (int k = 0; k < 2; ++k) dst[n][k] = *(const PG8_LAS bf16x8*)(lds + PG8_SB(b, h) + boff + n * 2048 + k * 1024); } while (0)
; #define PG8_MMA(ai, bj, At, Bt) do { __builtin_amdgcn_s_setprio(1); _Pragma("unroll") for (int m = 0; m < 4; ++m) _Pragma("unroll") for (int n = 0; n < 2; ++n) _Pragma("unroll") for (int k = 0; k < 2; ++k) \
;         acc[ai][bj][m][n] = __builtin_amdgcn_mfma_f32_16x16x32_bf16(Bt[n][k], At[m][k], acc[ai][bj][m][n], 0, 0, 0); __builtin_amdgcn_s_setprio(0); } while (0)
; #define PG8_WAIT_V(n) asm volatile("s_waitcnt vmcnt(" #n ")" ::: "memory")
; #define PG8_WAIT_L(n) asm volatile("s_waitcnt lgkmcnt(" #n ")" ::: "memory")
; #define PG8_BAR __builtin_amdgcn_s_barrier()
; template <class Epi, class Sched, bool ALIGN_EPI = false, bool SP2 = false>
; __device__ __forceinline__ void gemm_phase(PG8_LAS unsigned char* lds, const Gemm g, const Sched& S, const Epi& E) {
;     ...
;             const char* a1 = cA + (size_t)(t + 1) * kstep;
;             const char* a2 = last ? nA : cA + (size_t)(t + 2) * kstep; const char* b2 = last ? nB : cB + (size_t)(t + 2) * kstep;
;             const char* a3 = a2 + kstep; const char* b3 = b2 + kstep;
;             if (last && has_next) S.a_ready(nxt);
;             if constexpr (SP2) {
;             PG8_LDB(B0, 0, 0); PG8_LDB(B1, 0, 1); PG8_SCHED; PG8_LDA(At, 0, 0); PG8_STAGE(PG8_SA(1, 1), a1 + hstep, voffA);
;             PG8_WAIT_V(8); PG8_WAIT_L(0); PG8_BAR; PG8_MMA(0, 0, At, B0); PG8_MMA(0, 1, At, B1); PG8_BAR; PG8_SCHED;
;             PG8_LDA(At, 0, 1); PG8_STAGE(PG8_SB(0, 0), b2, voffB); PG8_STAGE(PG8_SB(0, 1), b2 + hstep, voffB); PG8_STAGE(PG8_SA(0, 0), a2, voffA);
;             PG8_WAIT_V(8); PG8_WAIT_L(0); PG8_BAR; PG8_MMA(1, 0, At, B0); PG8_MMA(1, 1, At, B1); PG8_BAR; PG8_SCHED;
.Lsgo_peel:
	ds_read_b128 v[140:143], v254
	ds_read_b128 v[166:169], v254 offset:1024
	ds_read_b128 v[170:173], v254 offset:2048
	ds_read_b128 v[174:177], v254 offset:3072
	ds_read_b128 v[178:181], v254 offset:16384
	ds_read_b128 v[182:185], v254 offset:17408
	ds_read_b128 v[186:189], v254 offset:18432
	ds_read_b128 v[210:213], v254 offset:19456
	s_add_u32 s2, s0, 0xfffc0080
	s_addc_u32 s3, s1, -1
	s_cmp_eq_u32 s55, 12
	s_cselect_b32 s5, s23, s3
	s_cselect_b32 s4, s51, s2
	s_cselect_b32 s3, s21, s54
	s_cselect_b32 s2, s52, s53
	s_add_i32 m0, s31, 0xc000
	ds_read_b128 v[214:217], v163
	ds_read_b128 v[218:221], v163 offset:1024
	ds_read_b128 v[222:225], v163 offset:2048
	ds_read_b128 v[226:229], v163 offset:3072
	ds_read_b128 v[230:233], v163 offset:4096
	ds_read_b128 v[234:237], v163 offset:5120
	ds_read_b128 v[238:241], v163 offset:6144
	ds_read_b128 v[242:245], v163 offset:7168
	global_load_lds_dwordx4 v136, s[0:1]
	s_add_i32 m0, s31, 0xe000
	s_nop 0
	global_load_lds_dwordx4 v138, s[0:1]
	s_waitcnt vmcnt(8)
	s_waitcnt lgkmcnt(0)
	s_barrier
	s_setprio 1
	v_mfma_f32_16x16x32_bf16 v[124:127], v[140:143], v[214:217], 0
	v_mfma_f32_16x16x32_bf16 v[124:127], v[166:169], v[218:221], v[124:127]
	v_mfma_f32_16x16x32_bf16 v[120:123], v[170:173], v[214:217], 0
	v_mfma_f32_16x16x32_bf16 v[120:123], v[174:177], v[218:221], v[120:123]
	v_mfma_f32_16x16x32_bf16 v[108:111], v[140:143], v[222:225], 0
	v_mfma_f32_16x16x32_bf16 v[108:111], v[166:169], v[226:229], v[108:111]
	v_mfma_f32_16x16x32_bf16 v[104:107], v[170:173], v[222:225], 0
	v_mfma_f32_16x16x32_bf16 v[104:107], v[174:177], v[226:229], v[104:107]
	v_mfma_f32_16x16x32_bf16 v[92:95], v[140:143], v[230:233], 0
	v_mfma_f32_16x16x32_bf16 v[92:95], v[166:169], v[234:237], v[92:95]
	v_mfma_f32_16x16x32_bf16 v[88:91], v[170:173], v[230:233], 0
	v_mfma_f32_16x16x32_bf16 v[88:91], v[174:177], v[234:237], v[88:91]
	v_mfma_f32_16x16x32_bf16 v[76:79], v[140:143], v[238:241], 0
	v_mfma_f32_16x16x32_bf16 v[76:79], v[166:169], v[242:245], v[76:79]
	v_mfma_f32_16x16x32_bf16 v[72:75], v[170:173], v[238:241], 0
	v_mfma_f32_16x16x32_bf16 v[72:75], v[174:177], v[242:245], v[72:75]
	v_mfma_f32_16x16x32_bf16 v[116:119], v[178:181], v[214:217], 0
	v_mfma_f32_16x16x32_bf16 v[116:119], v[182:185], v[218:221], v[116:119]
	v_mfma_f32_16x16x32_bf16 v[112:115], v[186:189], v[214:217], 0
	v_mfma_f32_16x16x32_bf16 v[112:115], v[210:213], v[218:221], v[112:115]
	v_mfma_f32_16x16x32_bf16 v[100:103], v[178:181], v[222:225], 0
	v_mfma_f32_16x16x32_bf16 v[100:103], v[182:185], v[226:229], v[100:103]
	v_mfma_f32_16x16x32_bf16 v[96:99], v[186:189], v[222:225], 0
	v_mfma_f32_16x16x32_bf16 v[96:99], v[210:213], v[226:229], v[96:99]
	v_mfma_f32_16x16x32_bf16 v[84:87], v[178:181], v[230:233], 0
	v_mfma_f32_16x16x32_bf16 v[84:87], v[182:185], v[234:237], v[84:87]
	v_mfma_f32_16x16x32_bf16 v[80:83], v[186:189], v[230:233], 0
	v_mfma_f32_16x16x32_bf16 v[80:83], v[210:213], v[234:237], v[80:83]
	v_mfma_f32_16x16x32_bf16 v[68:71], v[178:181], v[238:241], 0
	v_mfma_f32_16x16x32_bf16 v[68:71], v[182:185], v[242:245], v[68:71]
	v_mfma_f32_16x16x32_bf16 v[64:67], v[186:189], v[238:241], 0
	v_mfma_f32_16x16x32_bf16 v[64:67], v[210:213], v[242:245], v[64:67]
	s_setprio 0
	s_barrier
	s_mov_b32 m0, s33
	s_add_u32 s56, s2, 0x40000
	s_addc_u32 s57, s3, 0
	ds_read_b128 v[214:217], v163 offset:16384
	ds_read_b128 v[218:221], v163 offset:17408
	ds_read_b128 v[222:225], v163 offset:18432
	ds_read_b128 v[226:229], v163 offset:19456
	ds_read_b128 v[230:233], v163 offset:20480
	ds_read_b128 v[234:237], v163 offset:21504
	ds_read_b128 v[238:241], v163 offset:22528
	ds_read_b128 v[242:245], v163 offset:23552
	global_load_lds_dwordx4 v132, s[2:3]
	s_mov_b32 m0, s34
	s_nop 0
	global_load_lds_dwordx4 v128, s[2:3]
	s_mov_b32 m0, s35
	s_nop 0
	global_load_lds_dwordx4 v132, s[56:57]
	s_mov_b32 m0, s36
	s_nop 0
	global_load_lds_dwordx4 v128, s[56:57]
	s_mov_b32 m0, s31
	s_nop 0
	global_load_lds_dwordx4 v134, s[4:5]
	s_mov_b32 m0, s37
	s_nop 0
	global_load_lds_dwordx4 v130, s[4:5]
	s_waitcnt vmcnt(8)
	s_waitcnt lgkmcnt(0)
	s_barrier
	s_setprio 1
	v_mfma_f32_16x16x32_bf16 v[60:63], v[140:143], v[214:217], 0
	v_mfma_f32_16x16x32_bf16 v[60:63], v[166:169], v[218:221], v[60:63]
	v_mfma_f32_16x16x32_bf16 v[56:59], v[170:173], v[214:217], 0
	v_mfma_f32_16x16x32_bf16 v[56:59], v[174:177], v[218:221], v[56:59]
	v_mfma_f32_16x16x32_bf16 v[44:47], v[140:143], v[222:225], 0
	v_mfma_f32_16x16x32_bf16 v[44:47], v[166:169], v[226:229], v[44:47]
	v_mfma_f32_16x16x32_bf16 v[40:43], v[170:173], v[222:225], 0
	v_mfma_f32_16x16x32_bf16 v[40:43], v[174:177], v[226:229], v[40:43]
	v_mfma_f32_16x16x32_bf16 v[28:31], v[140:143], v[230:233], 0
	v_mfma_f32_16x16x32_bf16 v[28:31], v[166:169], v[234:237], v[28:31]
	v_mfma_f32_16x16x32_bf16 v[24:27], v[170:173], v[230:233], 0
	v_mfma_f32_16x16x32_bf16 v[24:27], v[174:177], v[234:237], v[24:27]
	v_mfma_f32_16x16x32_bf16 v[12:15], v[140:143], v[238:241], 0
	v_mfma_f32_16x16x32_bf16 v[12:15], v[166:169], v[242:245], v[12:15]
	v_mfma_f32_16x16x32_bf16 v[8:11], v[170:173], v[238:241], 0
	v_mfma_f32_16x16x32_bf16 v[8:11], v[174:177], v[242:245], v[8:11]
	v_mfma_f32_16x16x32_bf16 v[52:55], v[178:181], v[214:217], 0
	v_mfma_f32_16x16x32_bf16 v[52:55], v[182:185], v[218:221], v[52:55]
	v_mfma_f32_16x16x32_bf16 v[48:51], v[186:189], v[214:217], 0
	v_mfma_f32_16x16x32_bf16 v[48:51], v[210:213], v[218:221], v[48:51]
	v_mfma_f32_16x16x32_bf16 v[36:39], v[178:181], v[222:225], 0
	v_mfma_f32_16x16x32_bf16 v[36:39], v[182:185], v[226:229], v[36:39]
	v_mfma_f32_16x16x32_bf16 v[32:35], v[186:189], v[222:225], 0
	v_mfma_f32_16x16x32_bf16 v[32:35], v[210:213], v[226:229], v[32:35]
	v_mfma_f32_16x16x32_bf16 v[20:23], v[178:181], v[230:233], 0
	v_mfma_f32_16x16x32_bf16 v[20:23], v[182:185], v[234:237], v[20:23]
	v_mfma_f32_16x16x32_bf16 v[16:19], v[186:189], v[230:233], 0
	v_mfma_f32_16x16x32_bf16 v[16:19], v[210:213], v[234:237], v[16:19]
	v_mfma_f32_16x16x32_bf16 v[4:7], v[178:181], v[238:241], 0
	v_mfma_f32_16x16x32_bf16 v[4:7], v[182:185], v[242:245], v[4:7]
	v_mfma_f32_16x16x32_bf16 v[0:3], v[186:189], v[238:241], 0
	v_mfma_f32_16x16x32_bf16 v[0:3], v[210:213], v[242:245], v[0:3]
	s_setprio 0
	s_barrier
; #define PG8_STAGE(bufoff, gbase, voff) do { _Pragma("unroll") for (int _i = 0; _i < 2; ++_i) \
;         __builtin_amdgcn_global_load_lds((const unsigned*)((const char*)(gbase) + (voff)[_i]), (PG8_LAS unsigned*)(lds + (bufoff) + ldsw + _i * 8192), 16, 0, 0); } while (0)
; #define PG8_LDA(dst, b, h) do { _Pragma("unroll") for (int m = 0; m < 4; ++m) _Pragma("unroll") for (int k = 0; k < 2; ++k) dst[m][k] = *(const PG8_LAS bf16x8*)(lds + PG8_SA(b, h) + aoff + m * 2048 + k * 1024); } while (0)
; #define PG8_LDB(dst, b, h) do { _Pragma("unroll") for (int n = 0; n < 2; ++n) _Pragma("unroll") for (int k = 0; k < 2; ++k) dst[n][k] = *(const PG8_LAS bf16x8*)(lds + PG8_SB(b, h) + boff + n * 2048 + k * 1024); } while (0)
; #define PG8_MMA(ai, bj, At, Bt) do { __builtin_amdgcn_s_setprio(1); _Pragma("unroll") for (int m = 0; m < 4; ++m) _Pragma("unroll") for (int n = 0; n < 2; ++n) _Pragma("unroll") for (int k = 0; k < 2; ++k) \
;         acc[ai][bj][m][n] = __builtin_amdgcn_mfma_f32_16x16x32_bf16(Bt[n][k], At[m][k], acc[ai][bj][m][n], 0, 0, 0); __builtin_amdgcn_s_setprio(0); } while (0)
; #define PG8_WAIT_V(n) asm volatile("s_waitcnt vmcnt(" #n ")" ::: "memory")
; #define PG8_WAIT_L(n) asm volatile("s_waitcnt lgkmcnt(" #n ")" ::: "memory")
; #define PG8_BAR __builtin_amdgcn_s_barrier()
; #define PG8_SCHED __builtin_amdgcn_sched_barrier(0)
; template <class Epi, class Sched, bool ALIGN_EPI = false, bool SP2 = false>
; __device__ __forceinline__ void gemm_phase(PG8_LAS unsigned char* lds, const Gemm g, const Sched& S, const Epi& E) {
;     ...
;             PG8_LDB(B0, 1, 0); PG8_LDB(B1, 1, 1); PG8_SCHED; PG8_LDA(At, 1, 0); PG8_STAGE(PG8_SA(0, 1), a2 + hstep, voffA);
;             PG8_WAIT_V(8); PG8_WAIT_L(0); PG8_BAR; PG8_MMA(0, 0, At, B0); PG8_MMA(0, 1, At, B1); PG8_BAR; PG8_SCHED;
;             PG8_LDA(At, 1, 1); PG8_STAGE(PG8_SB(1, 0), b3, voffB); PG8_STAGE(PG8_SB(1, 1), b3 + hstep, voffB); PG8_STAGE(PG8_SA(1, 0), a3, voffA);
;             PG8_WAIT_V(8); PG8_WAIT_L(0); PG8_BAR; PG8_MMA(1, 0, At, B0); PG8_MMA(1, 1, At, B1); PG8_BAR; PG8_SCHED;
	ds_read_b128 v[140:143], v254 offset:32768
	ds_read_b128 v[166:169], v254 offset:33792
	ds_read_b128 v[170:173], v254 offset:34816
	ds_read_b128 v[174:177], v254 offset:35840
	ds_read_b128 v[178:181], v254 offset:49152
	ds_read_b128 v[182:185], v254 offset:50176
	ds_read_b128 v[186:189], v254 offset:51200
	ds_read_b128 v[210:213], v254 offset:52224
	s_add_u32 s4, s4, 0x40000
	s_addc_u32 s5, s5, 0
	s_mov_b32 m0, s38
	ds_read_b128 v[214:217], v163 offset:32768
	ds_read_b128 v[218:221], v163 offset:33792
	ds_read_b128 v[222:225], v163 offset:34816
	ds_read_b128 v[226:229], v163 offset:35840
	ds_read_b128 v[230:233], v163 offset:36864
	ds_read_b128 v[234:237], v163 offset:37888
	ds_read_b128 v[238:241], v163 offset:38912
	ds_read_b128 v[242:245], v163 offset:39936
	global_load_lds_dwordx4 v134, s[4:5]
	s_mov_b32 m0, s39
	s_nop 0
	global_load_lds_dwordx4 v130, s[4:5]
	s_waitcnt vmcnt(8)
	s_waitcnt lgkmcnt(0)
	s_barrier
	s_setprio 1
	v_mfma_f32_16x16x32_bf16 v[124:127], v[140:143], v[214:217], v[124:127]
	v_mfma_f32_16x16x32_bf16 v[124:127], v[166:169], v[218:221], v[124:127]
	v_mfma_f32_16x16x32_bf16 v[120:123], v[170:173], v[214:217], v[120:123]
	v_mfma_f32_16x16x32_bf16 v[120:123], v[174:177], v[218:221], v[120:123]
	v_mfma_f32_16x16x32_bf16 v[108:111], v[140:143], v[222:225], v[108:111]
	v_mfma_f32_16x16x32_bf16 v[108:111], v[166:169], v[226:229], v[108:111]
	v_mfma_f32_16x16x32_bf16 v[104:107], v[170:173], v[222:225], v[104:107]
	v_mfma_f32_16x16x32_bf16 v[104:107], v[174:177], v[226:229], v[104:107]
	v_mfma_f32_16x16x32_bf16 v[92:95], v[140:143], v[230:233], v[92:95]
	v_mfma_f32_16x16x32_bf16 v[92:95], v[166:169], v[234:237], v[92:95]
	v_mfma_f32_16x16x32_bf16 v[88:91], v[170:173], v[230:233], v[88:91]
	v_mfma_f32_16x16x32_bf16 v[88:91], v[174:177], v[234:237], v[88:91]
	v_mfma_f32_16x16x32_bf16 v[76:79], v[140:143], v[238:241], v[76:79]
	v_mfma_f32_16x16x32_bf16 v[76:79], v[166:169], v[242:245], v[76:79]
	v_mfma_f32_16x16x32_bf16 v[72:75], v[170:173], v[238:241], v[72:75]
	v_mfma_f32_16x16x32_bf16 v[72:75], v[174:177], v[242:245], v[72:75]
	v_mfma_f32_16x16x32_bf16 v[116:119], v[178:181], v[214:217], v[116:119]
	v_mfma_f32_16x16x32_bf16 v[116:119], v[182:185], v[218:221], v[116:119]
	v_mfma_f32_16x16x32_bf16 v[112:115], v[186:189], v[214:217], v[112:115]
	v_mfma_f32_16x16x32_bf16 v[112:115], v[210:213], v[218:221], v[112:115]
	v_mfma_f32_16x16x32_bf16 v[100:103], v[178:181], v[222:225], v[100:103]
	v_mfma_f32_16x16x32_bf16 v[100:103], v[182:185], v[226:229], v[100:103]
	v_mfma_f32_16x16x32_bf16 v[96:99], v[186:189], v[222:225], v[96:99]
	v_mfma_f32_16x16x32_bf16 v[96:99], v[210:213], v[226:229], v[96:99]
	v_mfma_f32_16x16x32_bf16 v[84:87], v[178:181], v[230:233], v[84:87]
	v_mfma_f32_16x16x32_bf16 v[84:87], v[182:185], v[234:237], v[84:87]
	v_mfma_f32_16x16x32_bf16 v[80:83], v[186:189], v[230:233], v[80:83]
	v_mfma_f32_16x16x32_bf16 v[80:83], v[210:213], v[234:237], v[80:83]
	v_mfma_f32_16x16x32_bf16 v[68:71], v[178:181], v[238:241], v[68:71]
	v_mfma_f32_16x16x32_bf16 v[68:71], v[182:185], v[242:245], v[68:71]
	v_mfma_f32_16x16x32_bf16 v[64:67], v[186:189], v[238:241], v[64:67]
	v_mfma_f32_16x16x32_bf16 v[64:67], v[210:213], v[242:245], v[64:67]
	s_setprio 0
	s_barrier
	s_mov_b32 m0, s43
	s_add_u32 s2, s2, 0x40080
	s_addc_u32 s3, s3, 0
	ds_read_b128 v[214:217], v163 offset:49152
	ds_read_b128 v[218:221], v163 offset:50176
	ds_read_b128 v[222:225], v163 offset:51200
	ds_read_b128 v[226:229], v163 offset:52224
	ds_read_b128 v[230:233], v163 offset:53248
	ds_read_b128 v[234:237], v163 offset:54272
	ds_read_b128 v[238:241], v163 offset:55296
	ds_read_b128 v[242:245], v163 offset:56320
	s_add_u32 s98, s2, 0xfffc0000
	s_addc_u32 s99, s3, -1
	global_load_lds_dwordx4 v132, s[98:99]
	s_mov_b32 m0, s44
	s_nop 0
	global_load_lds_dwordx4 v128, s[98:99]
	s_mov_b32 m0, s48
	s_nop 0
	global_load_lds_dwordx4 v132, s[2:3]
	s_mov_b32 m0, s49
	s_nop 0
	global_load_lds_dwordx4 v128, s[2:3]
	s_mov_b32 m0, s45
	s_nop 0
	s_add_u32 s100, s4, 0xfffc0080
	s_addc_u32 s101, s5, -1
	global_load_lds_dwordx4 v134, s[100:101]
	s_mov_b32 m0, s47
	s_nop 0
	global_load_lds_dwordx4 v130, s[100:101]
	s_waitcnt vmcnt(8)
	s_waitcnt lgkmcnt(0)
	s_barrier
	s_setprio 1
	v_mfma_f32_16x16x32_bf16 v[60:63], v[140:143], v[214:217], v[60:63]
	v_mfma_f32_16x16x32_bf16 v[60:63], v[166:169], v[218:221], v[60:63]
	v_mfma_f32_16x16x32_bf16 v[56:59], v[170:173], v[214:217], v[56:59]
	v_mfma_f32_16x16x32_bf16 v[56:59], v[174:177], v[218:221], v[56:59]
	v_mfma_f32_16x16x32_bf16 v[44:47], v[140:143], v[222:225], v[44:47]
	v_mfma_f32_16x16x32_bf16 v[44:47], v[166:169], v[226:229], v[44:47]
	v_mfma_f32_16x16x32_bf16 v[40:43], v[170:173], v[222:225], v[40:43]
	v_mfma_f32_16x16x32_bf16 v[40:43], v[174:177], v[226:229], v[40:43]
	v_mfma_f32_16x16x32_bf16 v[28:31], v[140:143], v[230:233], v[28:31]
	v_mfma_f32_16x16x32_bf16 v[28:31], v[166:169], v[234:237], v[28:31]
	v_mfma_f32_16x16x32_bf16 v[24:27], v[170:173], v[230:233], v[24:27]
	v_mfma_f32_16x16x32_bf16 v[24:27], v[174:177], v[234:237], v[24:27]
	v_mfma_f32_16x16x32_bf16 v[12:15], v[140:143], v[238:241], v[12:15]
	v_mfma_f32_16x16x32_bf16 v[12:15], v[166:169], v[242:245], v[12:15]
	v_mfma_f32_16x16x32_bf16 v[8:11], v[170:173], v[238:241], v[8:11]
	v_mfma_f32_16x16x32_bf16 v[8:11], v[174:177], v[242:245], v[8:11]
	v_mfma_f32_16x16x32_bf16 v[52:55], v[178:181], v[214:217], v[52:55]
	v_mfma_f32_16x16x32_bf16 v[52:55], v[182:185], v[218:221], v[52:55]
	v_mfma_f32_16x16x32_bf16 v[48:51], v[186:189], v[214:217], v[48:51]
	v_mfma_f32_16x16x32_bf16 v[48:51], v[210:213], v[218:221], v[48:51]
	v_mfma_f32_16x16x32_bf16 v[36:39], v[178:181], v[222:225], v[36:39]
	v_mfma_f32_16x16x32_bf16 v[36:39], v[182:185], v[226:229], v[36:39]
	v_mfma_f32_16x16x32_bf16 v[32:35], v[186:189], v[222:225], v[32:35]
	v_mfma_f32_16x16x32_bf16 v[32:35], v[210:213], v[226:229], v[32:35]
	v_mfma_f32_16x16x32_bf16 v[20:23], v[178:181], v[230:233], v[20:23]
	v_mfma_f32_16x16x32_bf16 v[20:23], v[182:185], v[234:237], v[20:23]
	v_mfma_f32_16x16x32_bf16 v[16:19], v[186:189], v[230:233], v[16:19]
	v_mfma_f32_16x16x32_bf16 v[16:19], v[210:213], v[234:237], v[16:19]
	v_mfma_f32_16x16x32_bf16 v[4:7], v[178:181], v[238:241], v[4:7]
	v_mfma_f32_16x16x32_bf16 v[4:7], v[182:185], v[242:245], v[4:7]
	v_mfma_f32_16x16x32_bf16 v[0:3], v[186:189], v[238:241], v[0:3]
	v_mfma_f32_16x16x32_bf16 v[0:3], v[210:213], v[242:245], v[0:3]
	s_setprio 0
	s_barrier
	s_add_i32 s55, s55, 2
	s_add_u32 s0, s0, 0x100
	s_addc_u32 s1, s1, 0
	s_add_u32 s53, s53, 0x100
	s_addc_u32 s54, s54, 0
	s_cmp_gt_u32 s55, 13
; #define PG8_STAGE(bufoff, gbase, voff) do { _Pragma("unroll") for (int _i = 0; _i < 2; ++_i) \
;         __builtin_amdgcn_global_load_lds((const unsigned*)((const char*)(gbase) + (voff)[_i]), (PG8_LAS unsigned*)(lds + (bufoff) + ldsw + _i * 8192), 16, 0, 0); } while (0)
; #define PG8_LDA(dst, b, h) do { _Pragma("unroll") for (int m = 0; m < 4; ++m) _Pragma("unroll") for (int k = 0; k < 2; ++k) dst[m][k] = *(const PG8_LAS bf16x8*)(lds + PG8_SA(b, h) + aoff + m * 2048 + k * 1024); } while (0)
; #define PG8_LDB(dst, b, h) do { _Pragma("unroll") for (int n = 0; n < 2; ++n) _Pragma("unroll") for (int k = 0; k < 2; ++k) dst[n][k] = *(const PG8_LAS bf16x8*)(lds + PG8_SB(b, h) + boff + n * 2048 + k * 1024); } while (0)
; #define PG8_MMA(ai, bj, At, Bt) do { __builtin_amdgcn_s_setprio(1); _Pragma("unroll") for (int m = 0; m < 4; ++m) _Pragma("unroll") for (int n = 0; n < 2; ++n) _Pragma("unroll") for (int k = 0; k < 2; ++k) \
;         acc[ai][bj][m][n] = __builtin_amdgcn_mfma_f32_16x16x32_bf16(Bt[n][k], At[m][k], acc[ai][bj][m][n], 0, 0, 0); __builtin_amdgcn_s_setprio(0); } while (0)
; #define PG8_WAIT_V(n) asm volatile("s_waitcnt vmcnt(" #n ")" ::: "memory")
; #define PG8_WAIT_L(n) asm volatile("s_waitcnt lgkmcnt(" #n ")" ::: "memory")
; #define PG8_BAR __builtin_amdgcn_s_barrier()
; template <class Epi, class Sched, bool ALIGN_EPI = false, bool SP2 = false>
; __device__ __forceinline__ void gemm_phase(PG8_LAS unsigned char* lds, const Gemm g, const Sched& S, const Epi& E) {
;     ...
;             const char* a1 = cA + (size_t)(t + 1) * kstep;
;             const char* a2 = last ? nA : cA + (size_t)(t + 2) * kstep; const char* b2 = last ? nB : cB + (size_t)(t + 2) * kstep;
;             const char* a3 = a2 + kstep; const char* b3 = b2 + kstep;
;             if (last && has_next) S.a_ready(nxt);
;             if constexpr (SP2) {
;             PG8_LDB(B0, 0, 0); PG8_LDB(B1, 0, 1); PG8_SCHED; PG8_LDA(At, 0, 0); PG8_STAGE(PG8_SA(1, 1), a1 + hstep, voffA);
;             PG8_WAIT_V(8); PG8_WAIT_L(0); PG8_BAR; PG8_MMA(0, 0, At, B0); PG8_MMA(0, 1, At, B1); PG8_BAR; PG8_SCHED;
;             PG8_LDA(At, 0, 1); PG8_STAGE(PG8_SB(0, 0), b2, voffB); PG8_STAGE(PG8_SB(0, 1), b2 + hstep, voffB); PG8_STAGE(PG8_SA(0, 0), a2, voffA);
;             PG8_WAIT_V(8); PG8_WAIT_L(0); PG8_BAR; PG8_MMA(1, 0, At, B0); PG8_MMA(1, 1, At, B1); PG8_BAR; PG8_SCHED;
.LBB0_1042:
	ds_read_b128 v[140:143], v254
	ds_read_b128 v[166:169], v254 offset:1024
	ds_read_b128 v[170:173], v254 offset:2048
	ds_read_b128 v[174:177], v254 offset:3072
	ds_read_b128 v[178:181], v254 offset:16384
	ds_read_b128 v[182:185], v254 offset:17408
	ds_read_b128 v[186:189], v254 offset:18432
	ds_read_b128 v[210:213], v254 offset:19456
	s_add_u32 s2, s0, 0xfffc0080
	s_addc_u32 s3, s1, -1
	s_cmp_eq_u32 s55, 12
	s_cselect_b32 s5, s23, s3
	s_cselect_b32 s4, s51, s2
	s_cselect_b32 s3, s21, s54
	s_cselect_b32 s2, s52, s53
	s_add_i32 m0, s31, 0xc000
	ds_read_b128 v[214:217], v163
	ds_read_b128 v[218:221], v163 offset:1024
	ds_read_b128 v[222:225], v163 offset:2048
	ds_read_b128 v[226:229], v163 offset:3072
	ds_read_b128 v[230:233], v163 offset:4096
	ds_read_b128 v[234:237], v163 offset:5120
	ds_read_b128 v[238:241], v163 offset:6144
	ds_read_b128 v[242:245], v163 offset:7168
	global_load_lds_dwordx4 v136, s[0:1]
	s_add_i32 m0, s31, 0xe000
	s_nop 0
	global_load_lds_dwordx4 v138, s[0:1]
	s_waitcnt vmcnt(8)
	s_waitcnt lgkmcnt(0)
	s_barrier
	s_setprio 1
	v_mfma_f32_16x16x32_bf16 v[124:127], v[140:143], v[214:217], v[124:127]
	v_mfma_f32_16x16x32_bf16 v[124:127], v[166:169], v[218:221], v[124:127]
	v_mfma_f32_16x16x32_bf16 v[120:123], v[170:173], v[214:217], v[120:123]
	v_mfma_f32_16x16x32_bf16 v[120:123], v[174:177], v[218:221], v[120:123]
	v_mfma_f32_16x16x32_bf16 v[108:111], v[140:143], v[222:225], v[108:111]
	v_mfma_f32_16x16x32_bf16 v[108:111], v[166:169], v[226:229], v[108:111]
	v_mfma_f32_16x16x32_bf16 v[104:107], v[170:173], v[222:225], v[104:107]
	v_mfma_f32_16x16x32_bf16 v[104:107], v[174:177], v[226:229], v[104:107]
	v_mfma_f32_16x16x32_bf16 v[92:95], v[140:143], v[230:233], v[92:95]
	v_mfma_f32_16x16x32_bf16 v[92:95], v[166:169], v[234:237], v[92:95]
	v_mfma_f32_16x16x32_bf16 v[88:91], v[170:173], v[230:233], v[88:91]
	v_mfma_f32_16x16x32_bf16 v[88:91], v[174:177], v[234:237], v[88:91]
	v_mfma_f32_16x16x32_bf16 v[76:79], v[140:143], v[238:241], v[76:79]
	v_mfma_f32_16x16x32_bf16 v[76:79], v[166:169], v[242:245], v[76:79]
	v_mfma_f32_16x16x32_bf16 v[72:75], v[170:173], v[238:241], v[72:75]
	v_mfma_f32_16x16x32_bf16 v[72:75], v[174:177], v[242:245], v[72:75]
	v_mfma_f32_16x16x32_bf16 v[116:119], v[178:181], v[214:217], v[116:119]
	v_mfma_f32_16x16x32_bf16 v[116:119], v[182:185], v[218:221], v[116:119]
	v_mfma_f32_16x16x32_bf16 v[112:115], v[186:189], v[214:217], v[112:115]
	v_mfma_f32_16x16x32_bf16 v[112:115], v[210:213], v[218:221], v[112:115]
	v_mfma_f32_16x16x32_bf16 v[100:103], v[178:181], v[222:225], v[100:103]
	v_mfma_f32_16x16x32_bf16 v[100:103], v[182:185], v[226:229], v[100:103]
	v_mfma_f32_16x16x32_bf16 v[96:99], v[186:189], v[222:225], v[96:99]
	v_mfma_f32_16x16x32_bf16 v[96:99], v[210:213], v[226:229], v[96:99]
	v_mfma_f32_16x16x32_bf16 v[84:87], v[178:181], v[230:233], v[84:87]
	v_mfma_f32_16x16x32_bf16 v[84:87], v[182:185], v[234:237], v[84:87]
	v_mfma_f32_16x16x32_bf16 v[80:83], v[186:189], v[230:233], v[80:83]
	v_mfma_f32_16x16x32_bf16 v[80:83], v[210:213], v[234:237], v[80:83]
	v_mfma_f32_16x16x32_bf16 v[68:71], v[178:181], v[238:241], v[68:71]
	v_mfma_f32_16x16x32_bf16 v[68:71], v[182:185], v[242:245], v[68:71]
	v_mfma_f32_16x16x32_bf16 v[64:67], v[186:189], v[238:241], v[64:67]
	v_mfma_f32_16x16x32_bf16 v[64:67], v[210:213], v[242:245], v[64:67]
	s_setprio 0
	s_barrier
	s_mov_b32 m0, s33
	s_add_u32 s56, s2, 0x40000
	s_addc_u32 s57, s3, 0
	ds_read_b128 v[214:217], v163 offset:16384
	ds_read_b128 v[218:221], v163 offset:17408
	ds_read_b128 v[222:225], v163 offset:18432
	ds_read_b128 v[226:229], v163 offset:19456
	ds_read_b128 v[230:233], v163 offset:20480
	ds_read_b128 v[234:237], v163 offset:21504
	ds_read_b128 v[238:241], v163 offset:22528
	ds_read_b128 v[242:245], v163 offset:23552
	global_load_lds_dwordx4 v132, s[2:3]
	s_mov_b32 m0, s34
	s_nop 0
	global_load_lds_dwordx4 v128, s[2:3]
	s_mov_b32 m0, s35
	s_nop 0
	global_load_lds_dwordx4 v132, s[56:57]
	s_mov_b32 m0, s36
	s_nop 0
	global_load_lds_dwordx4 v128, s[56:57]
	s_mov_b32 m0, s31
	s_nop 0
	global_load_lds_dwordx4 v134, s[4:5]
	s_mov_b32 m0, s37
	s_nop 0
	global_load_lds_dwordx4 v130, s[4:5]
	s_waitcnt vmcnt(8)
	s_waitcnt lgkmcnt(0)
	s_barrier
	s_setprio 1
	v_mfma_f32_16x16x32_bf16 v[60:63], v[140:143], v[214:217], v[60:63]
	v_mfma_f32_16x16x32_bf16 v[60:63], v[166:169], v[218:221], v[60:63]
	v_mfma_f32_16x16x32_bf16 v[56:59], v[170:173], v[214:217], v[56:59]
	v_mfma_f32_16x16x32_bf16 v[56:59], v[174:177], v[218:221], v[56:59]
	v_mfma_f32_16x16x32_bf16 v[44:47], v[140:143], v[222:225], v[44:47]
	v_mfma_f32_16x16x32_bf16 v[44:47], v[166:169], v[226:229], v[44:47]
	v_mfma_f32_16x16x32_bf16 v[40:43], v[170:173], v[222:225], v[40:43]
	v_mfma_f32_16x16x32_bf16 v[40:43], v[174:177], v[226:229], v[40:43]
	v_mfma_f32_16x16x32_bf16 v[28:31], v[140:143], v[230:233], v[28:31]
	v_mfma_f32_16x16x32_bf16 v[28:31], v[166:169], v[234:237], v[28:31]
	v_mfma_f32_16x16x32_bf16 v[24:27], v[170:173], v[230:233], v[24:27]
	v_mfma_f32_16x16x32_bf16 v[24:27], v[174:177], v[234:237], v[24:27]
	v_mfma_f32_16x16x32_bf16 v[12:15], v[140:143], v[238:241], v[12:15]
	v_mfma_f32_16x16x32_bf16 v[12:15], v[166:169], v[242:245], v[12:15]
	v_mfma_f32_16x16x32_bf16 v[8:11], v[170:173], v[238:241], v[8:11]
	v_mfma_f32_16x16x32_bf16 v[8:11], v[174:177], v[242:245], v[8:11]
	v_mfma_f32_16x16x32_bf16 v[52:55], v[178:181], v[214:217], v[52:55]
	v_mfma_f32_16x16x32_bf16 v[52:55], v[182:185], v[218:221], v[52:55]
	v_mfma_f32_16x16x32_bf16 v[48:51], v[186:189], v[214:217], v[48:51]
	v_mfma_f32_16x16x32_bf16 v[48:51], v[210:213], v[218:221], v[48:51]
	v_mfma_f32_16x16x32_bf16 v[36:39], v[178:181], v[222:225], v[36:39]
	v_mfma_f32_16x16x32_bf16 v[36:39], v[182:185], v[226:229], v[36:39]
	v_mfma_f32_16x16x32_bf16 v[32:35], v[186:189], v[222:225], v[32:35]
	v_mfma_f32_16x16x32_bf16 v[32:35], v[210:213], v[226:229], v[32:35]
	v_mfma_f32_16x16x32_bf16 v[20:23], v[178:181], v[230:233], v[20:23]
	v_mfma_f32_16x16x32_bf16 v[20:23], v[182:185], v[234:237], v[20:23]
	v_mfma_f32_16x16x32_bf16 v[16:19], v[186:189], v[230:233], v[16:19]
	v_mfma_f32_16x16x32_bf16 v[16:19], v[210:213], v[234:237], v[16:19]
	v_mfma_f32_16x16x32_bf16 v[4:7], v[178:181], v[238:241], v[4:7]
	v_mfma_f32_16x16x32_bf16 v[4:7], v[182:185], v[242:245], v[4:7]
	v_mfma_f32_16x16x32_bf16 v[0:3], v[186:189], v[238:241], v[0:3]
	v_mfma_f32_16x16x32_bf16 v[0:3], v[210:213], v[242:245], v[0:3]
	s_setprio 0
	s_barrier
; #define PG8_STAGE(bufoff, gbase, voff) do { _Pragma("unroll") for (int _i = 0; _i < 2; ++_i) \
;         __builtin_amdgcn_global_load_lds((const unsigned*)((const char*)(gbase) + (voff)[_i]), (PG8_LAS unsigned*)(lds + (bufoff) + ldsw + _i * 8192), 16, 0, 0); } while (0)
; #define PG8_LDA(dst, b, h) do { _Pragma("unroll") for (int m = 0; m < 4; ++m) _Pragma("unroll") for (int k = 0; k < 2; ++k) dst[m][k] = *(const PG8_LAS bf16x8*)(lds + PG8_SA(b, h) + aoff + m * 2048 + k * 1024); } while (0)
; #define PG8_LDB(dst, b, h) do { _Pragma("unroll") for (int n = 0; n < 2; ++n) _Pragma("unroll") for (int k = 0; k < 2; ++k) dst[n][k] = *(const PG8_LAS bf16x8*)(lds + PG8_SB(b, h) + boff + n * 2048 + k * 1024); } while (0)
; #define PG8_MMA(ai, bj, At, Bt) do { __builtin_amdgcn_s_setprio(1); _Pragma("unroll") for (int m = 0; m < 4; ++m) _Pragma("unroll") for (int n = 0; n < 2; ++n) _Pragma("unroll") for (int k = 0; k < 2; ++k) \
;         acc[ai][bj][m][n] = __builtin_amdgcn_mfma_f32_16x16x32_bf16(Bt[n][k], At[m][k], acc[ai][bj][m][n], 0, 0, 0); __builtin_amdgcn_s_setprio(0); } while (0)
; #define PG8_WAIT_V(n) asm volatile("s_waitcnt vmcnt(" #n ")" ::: "memory")
; #define PG8_WAIT_L(n) asm volatile("s_waitcnt lgkmcnt(" #n ")" ::: "memory")
; #define PG8_BAR __builtin_amdgcn_s_barrier()
; #define PG8_SCHED __builtin_amdgcn_sched_barrier(0)
; template <class Epi, class Sched, bool ALIGN_EPI = false, bool SP2 = false>
; __device__ __forceinline__ void gemm_phase(PG8_LAS unsigned char* lds, const Gemm g, const Sched& S, const Epi& E) {
;     ...
;             PG8_LDB(B0, 1, 0); PG8_LDB(B1, 1, 1); PG8_SCHED; PG8_LDA(At, 1, 0); PG8_STAGE(PG8_SA(0, 1), a2 + hstep, voffA);
;             PG8_WAIT_V(8); PG8_WAIT_L(0); PG8_BAR; PG8_MMA(0, 0, At, B0); PG8_MMA(0, 1, At, B1); PG8_BAR; PG8_SCHED;
;             PG8_LDA(At, 1, 1); PG8_STAGE(PG8_SB(1, 0), b3, voffB); PG8_STAGE(PG8_SB(1, 1), b3 + hstep, voffB); PG8_STAGE(PG8_SA(1, 0), a3, voffA);
;             PG8_WAIT_V(8); PG8_WAIT_L(0); PG8_BAR; PG8_MMA(1, 0, At, B0); PG8_MMA(1, 1, At, B1); PG8_BAR; PG8_SCHED;
	ds_read_b128 v[140:143], v254 offset:32768
	ds_read_b128 v[166:169], v254 offset:33792
	ds_read_b128 v[170:173], v254 offset:34816
	ds_read_b128 v[174:177], v254 offset:35840
	ds_read_b128 v[178:181], v254 offset:49152
	ds_read_b128 v[182:185], v254 offset:50176
	ds_read_b128 v[186:189], v254 offset:51200
	ds_read_b128 v[210:213], v254 offset:52224
	s_add_u32 s4, s4, 0x40000
	s_addc_u32 s5, s5, 0
	s_mov_b32 m0, s38
	ds_read_b128 v[214:217], v163 offset:32768
	ds_read_b128 v[218:221], v163 offset:33792
	ds_read_b128 v[222:225], v163 offset:34816
	ds_read_b128 v[226:229], v163 offset:35840
	ds_read_b128 v[230:233], v163 offset:36864
	ds_read_b128 v[234:237], v163 offset:37888
	ds_read_b128 v[238:241], v163 offset:38912
	ds_read_b128 v[242:245], v163 offset:39936
	global_load_lds_dwordx4 v134, s[4:5]
	s_mov_b32 m0, s39
	s_nop 0
	global_load_lds_dwordx4 v130, s[4:5]
	s_waitcnt vmcnt(8)
	s_waitcnt lgkmcnt(0)
	s_barrier
	s_setprio 1
	v_mfma_f32_16x16x32_bf16 v[124:127], v[140:143], v[214:217], v[124:127]
	v_mfma_f32_16x16x32_bf16 v[124:127], v[166:169], v[218:221], v[124:127]
	v_mfma_f32_16x16x32_bf16 v[120:123], v[170:173], v[214:217], v[120:123]
	v_mfma_f32_16x16x32_bf16 v[120:123], v[174:177], v[218:221], v[120:123]
	v_mfma_f32_16x16x32_bf16 v[108:111], v[140:143], v[222:225], v[108:111]
	v_mfma_f32_16x16x32_bf16 v[108:111], v[166:169], v[226:229], v[108:111]
	v_mfma_f32_16x16x32_bf16 v[104:107], v[170:173], v[222:225], v[104:107]
	v_mfma_f32_16x16x32_bf16 v[104:107], v[174:177], v[226:229], v[104:107]
	v_mfma_f32_16x16x32_bf16 v[92:95], v[140:143], v[230:233], v[92:95]
	v_mfma_f32_16x16x32_bf16 v[92:95], v[166:169], v[234:237], v[92:95]
	v_mfma_f32_16x16x32_bf16 v[88:91], v[170:173], v[230:233], v[88:91]
	v_mfma_f32_16x16x32_bf16 v[88:91], v[174:177], v[234:237], v[88:91]
	v_mfma_f32_16x16x32_bf16 v[76:79], v[140:143], v[238:241], v[76:79]
	v_mfma_f32_16x16x32_bf16 v[76:79], v[166:169], v[242:245], v[76:79]
	v_mfma_f32_16x16x32_bf16 v[72:75], v[170:173], v[238:241], v[72:75]
	v_mfma_f32_16x16x32_bf16 v[72:75], v[174:177], v[242:245], v[72:75]
	v_mfma_f32_16x16x32_bf16 v[116:119], v[178:181], v[214:217], v[116:119]
	v_mfma_f32_16x16x32_bf16 v[116:119], v[182:185], v[218:221], v[116:119]
	v_mfma_f32_16x16x32_bf16 v[112:115], v[186:189], v[214:217], v[112:115]
	v_mfma_f32_16x16x32_bf16 v[112:115], v[210:213], v[218:221], v[112:115]
	v_mfma_f32_16x16x32_bf16 v[100:103], v[178:181], v[222:225], v[100:103]
	v_mfma_f32_16x16x32_bf16 v[100:103], v[182:185], v[226:229], v[100:103]
	v_mfma_f32_16x16x32_bf16 v[96:99], v[186:189], v[222:225], v[96:99]
	v_mfma_f32_16x16x32_bf16 v[96:99], v[210:213], v[226:229], v[96:99]
	v_mfma_f32_16x16x32_bf16 v[84:87], v[178:181], v[230:233], v[84:87]
	v_mfma_f32_16x16x32_bf16 v[84:87], v[182:185], v[234:237], v[84:87]
	v_mfma_f32_16x16x32_bf16 v[80:83], v[186:189], v[230:233], v[80:83]
	v_mfma_f32_16x16x32_bf16 v[80:83], v[210:213], v[234:237], v[80:83]
	v_mfma_f32_16x16x32_bf16 v[68:71], v[178:181], v[238:241], v[68:71]
	v_mfma_f32_16x16x32_bf16 v[68:71], v[182:185], v[242:245], v[68:71]
	v_mfma_f32_16x16x32_bf16 v[64:67], v[186:189], v[238:241], v[64:67]
	v_mfma_f32_16x16x32_bf16 v[64:67], v[210:213], v[242:245], v[64:67]
	s_setprio 0
	s_barrier
	s_mov_b32 m0, s43
	s_add_u32 s2, s2, 0x40080
	s_addc_u32 s3, s3, 0
	ds_read_b128 v[214:217], v163 offset:49152
	ds_read_b128 v[218:221], v163 offset:50176
	ds_read_b128 v[222:225], v163 offset:51200
	ds_read_b128 v[226:229], v163 offset:52224
	ds_read_b128 v[230:233], v163 offset:53248
	ds_read_b128 v[234:237], v163 offset:54272
	ds_read_b128 v[238:241], v163 offset:55296
	ds_read_b128 v[242:245], v163 offset:56320
	s_add_u32 s98, s2, 0xfffc0000
	s_addc_u32 s99, s3, -1
	global_load_lds_dwordx4 v132, s[98:99]
	s_mov_b32 m0, s44
	s_nop 0
	global_load_lds_dwordx4 v128, s[98:99]
	s_mov_b32 m0, s48
	s_nop 0
	global_load_lds_dwordx4 v132, s[2:3]
	s_mov_b32 m0, s49
	s_nop 0
	global_load_lds_dwordx4 v128, s[2:3]
	s_mov_b32 m0, s45
	s_nop 0
	s_add_u32 s100, s4, 0xfffc0080
	s_addc_u32 s101, s5, -1
	global_load_lds_dwordx4 v134, s[100:101]
	s_mov_b32 m0, s47
	s_nop 0
	global_load_lds_dwordx4 v130, s[100:101]
	s_waitcnt vmcnt(8)
	s_waitcnt lgkmcnt(0)
	s_barrier
	s_setprio 1
	v_mfma_f32_16x16x32_bf16 v[60:63], v[140:143], v[214:217], v[60:63]
	v_mfma_f32_16x16x32_bf16 v[60:63], v[166:169], v[218:221], v[60:63]
	v_mfma_f32_16x16x32_bf16 v[56:59], v[170:173], v[214:217], v[56:59]
	v_mfma_f32_16x16x32_bf16 v[56:59], v[174:177], v[218:221], v[56:59]
	v_mfma_f32_16x16x32_bf16 v[44:47], v[140:143], v[222:225], v[44:47]
	v_mfma_f32_16x16x32_bf16 v[44:47], v[166:169], v[226:229], v[44:47]
	v_mfma_f32_16x16x32_bf16 v[40:43], v[170:173], v[222:225], v[40:43]
	v_mfma_f32_16x16x32_bf16 v[40:43], v[174:177], v[226:229], v[40:43]
	v_mfma_f32_16x16x32_bf16 v[28:31], v[140:143], v[230:233], v[28:31]
	v_mfma_f32_16x16x32_bf16 v[28:31], v[166:169], v[234:237], v[28:31]
	v_mfma_f32_16x16x32_bf16 v[24:27], v[170:173], v[230:233], v[24:27]
	v_mfma_f32_16x16x32_bf16 v[24:27], v[174:177], v[234:237], v[24:27]
	v_mfma_f32_16x16x32_bf16 v[12:15], v[140:143], v[238:241], v[12:15]
	v_mfma_f32_16x16x32_bf16 v[12:15], v[166:169], v[242:245], v[12:15]
	v_mfma_f32_16x16x32_bf16 v[8:11], v[170:173], v[238:241], v[8:11]
	v_mfma_f32_16x16x32_bf16 v[8:11], v[174:177], v[242:245], v[8:11]
	v_mfma_f32_16x16x32_bf16 v[52:55], v[178:181], v[214:217], v[52:55]
	v_mfma_f32_16x16x32_bf16 v[52:55], v[182:185], v[218:221], v[52:55]
	v_mfma_f32_16x16x32_bf16 v[48:51], v[186:189], v[214:217], v[48:51]
	v_mfma_f32_16x16x32_bf16 v[48:51], v[210:213], v[218:221], v[48:51]
	v_mfma_f32_16x16x32_bf16 v[36:39], v[178:181], v[222:225], v[36:39]
	v_mfma_f32_16x16x32_bf16 v[36:39], v[182:185], v[226:229], v[36:39]
	v_mfma_f32_16x16x32_bf16 v[32:35], v[186:189], v[222:225], v[32:35]
	v_mfma_f32_16x16x32_bf16 v[32:35], v[210:213], v[226:229], v[32:35]
	v_mfma_f32_16x16x32_bf16 v[20:23], v[178:181], v[230:233], v[20:23]
	v_mfma_f32_16x16x32_bf16 v[20:23], v[182:185], v[234:237], v[20:23]
	v_mfma_f32_16x16x32_bf16 v[16:19], v[186:189], v[230:233], v[16:19]
	v_mfma_f32_16x16x32_bf16 v[16:19], v[210:213], v[234:237], v[16:19]
	v_mfma_f32_16x16x32_bf16 v[4:7], v[178:181], v[238:241], v[4:7]
	v_mfma_f32_16x16x32_bf16 v[4:7], v[182:185], v[242:245], v[4:7]
	v_mfma_f32_16x16x32_bf16 v[0:3], v[186:189], v[238:241], v[0:3]
	v_mfma_f32_16x16x32_bf16 v[0:3], v[210:213], v[242:245], v[0:3]
	s_setprio 0
	s_barrier
	s_add_i32 s55, s55, 2
	s_add_u32 s0, s0, 0x100
	s_addc_u32 s1, s1, 0
	s_add_u32 s53, s53, 0x100
	s_addc_u32 s54, s54, 0
	s_cmp_gt_u32 s55, 13
	s_cbranch_scc0 .LBB0_1042
	s_and_b64 vcc, exec, s[18:19]
	s_cbranch_vccz .LBB0_1045
	s_barrier
